# hand-written final phase (all loads of a row in flight, next row prefetched) and prologue x/p bf16 conversion loops with batched loads
# speedup vs baseline: 1.0282x; 1.0282x over previous
; __device__ __forceinline__ unsigned cvt_pk_bf16(float lo, float hi) { unsigned r; asm volatile("v_cvt_pk_bf16_f32 %0, %1, %2" : "=v"(r) : "v"(lo), "v"(hi)); return r; }
; #define GAS __attribute__((address_space(1)))
; __device__ __forceinline__ float wave_sum(float v) {
; #pragma unroll
;     for (int o = 1; o < 64; o <<= 1) v += __shfl_xor(v, o);
;     return v;
; }
; __device__ __forceinline__ void p0_prologue(const In& in, float* out, unsigned char* ws, LAS unsigned char* lds, int tid, int lane, int wave) {
;     ...
;     { bf16* XB = (bf16*)(ws + WS_XB); float* ss1 = (float*)(ws + WS_STAT) + ST_SS1 * MROWS;
;       for (int mm = gw; mm < MROWS * P0_REP; mm += NGW) { const int m = mm % MROWS; const GAS f32x4* xr = (const GAS f32x4*)(in.x + (size_t)m * DM) + lane; GAS v2u* o = (GAS v2u*)(XB + (size_t)m * DM) + lane; float s = 0.f;
; #pragma unroll
;           for (int j = 0; j < 8; ++j) { const f32x4 v = xr[64 * j]; s += (v.x * v.x + v.y * v.y) + (v.z * v.z + v.w * v.w); v2u w; w.x = cvt_pk_bf16(v.x, v.y); w.y = cvt_pk_bf16(v.z, v.w); o[64 * j] = w; }
;           s = wave_sum(s); if (lane == 0) ss1[m] = s; } }
.Lxb_entry:
	s_mov_b64 s[0:1], exec
	v_lshlrev_b32_e32 v2, 4, v74
	v_lshlrev_b32_e32 v3, 3, v74
	v_mov_b32_e32 v4, 0
	v_mbcnt_hi_u32_b32 v5, -1, v254
	v_xor_b32_e32 v68, 1, v5
	v_xor_b32_e32 v69, 2, v5
	v_xor_b32_e32 v70, 4, v5
	v_xor_b32_e32 v71, 8, v5
	v_xor_b32_e32 v72, 16, v5
	v_xor_b32_e32 v73, 32, v5
	v_lshlrev_b32_e32 v68, 2, v68
	v_lshlrev_b32_e32 v69, 2, v69
	v_lshlrev_b32_e32 v70, 2, v70
	v_lshlrev_b32_e32 v71, 2, v71
	v_lshlrev_b32_e32 v72, 2, v72
	v_lshlrev_b32_e32 v73, 2, v73
	s_mov_b32 s6, s24
	s_waitcnt lgkmcnt(0)
	s_lshl_b32 s3, s6, 13
	s_add_u32 s4, s52, s3
	s_addc_u32 s5, s53, 0
	s_add_u32 s4, s4, 0x1000
	s_addc_u32 s5, s5, 0
	global_load_dwordx4 v[16:19], v2, s[4:5] offset:-4096
	global_load_dwordx4 v[20:23], v2, s[4:5] offset:-3072
	global_load_dwordx4 v[24:27], v2, s[4:5] offset:-2048
	global_load_dwordx4 v[28:31], v2, s[4:5] offset:-1024
	global_load_dwordx4 v[32:35], v2, s[4:5] offset:0
	global_load_dwordx4 v[36:39], v2, s[4:5] offset:1024
	global_load_dwordx4 v[40:43], v2, s[4:5] offset:2048
	global_load_dwordx4 v[44:47], v2, s[4:5] offset:3072
	s_lshl_b32 s3, s6, 12
	s_add_u32 s8, s28, s3
	s_addc_u32 s9, s29, 0
	s_lshl_b32 s3, s6, 2
	s_add_u32 s12, s68, s3
	s_addc_u32 s13, s69, 0
	s_add_i32 s6, s6, s26
	s_cmpk_gt_i32 s6, 0x7fff
	s_cbranch_scc1 .Lxb_last_f
	s_lshl_b32 s3, s6, 13
	s_add_u32 s4, s52, s3
	s_addc_u32 s5, s53, 0
	s_add_u32 s4, s4, 0x1000
	s_addc_u32 s5, s5, 0
	global_load_dwordx4 v[80:83], v2, s[4:5] offset:-4096
	global_load_dwordx4 v[84:87], v2, s[4:5] offset:-3072
	global_load_dwordx4 v[88:91], v2, s[4:5] offset:-2048
	global_load_dwordx4 v[92:95], v2, s[4:5] offset:-1024
	global_load_dwordx4 v[96:99], v2, s[4:5] offset:0
	global_load_dwordx4 v[100:103], v2, s[4:5] offset:1024
	global_load_dwordx4 v[104:107], v2, s[4:5] offset:2048
	global_load_dwordx4 v[108:111], v2, s[4:5] offset:3072
	s_waitcnt vmcnt(8)
	v_cvt_pk_bf16_f32 v48, v16, v17
	v_cvt_pk_bf16_f32 v49, v18, v19
	v_mul_f32_e32 v65, v17, v17
	v_mul_f32_e32 v66, v19, v19
	global_store_dwordx2 v3, v[48:49], s[8:9]
	v_fmac_f32_e32 v65, v16, v16
	v_fmac_f32_e32 v66, v18, v18
	v_add_f32_e32 v64, v65, v66
	v_cvt_pk_bf16_f32 v50, v20, v21
	v_cvt_pk_bf16_f32 v51, v22, v23
	v_mul_f32_e32 v65, v21, v21
	v_mul_f32_e32 v66, v23, v23
	global_store_dwordx2 v3, v[50:51], s[8:9] offset:512
	v_fmac_f32_e32 v65, v20, v20
	v_fmac_f32_e32 v66, v22, v22
	v_add_f32_e32 v65, v65, v66
	v_add_f32_e32 v64, v64, v65
	v_cvt_pk_bf16_f32 v52, v24, v25
	v_cvt_pk_bf16_f32 v53, v26, v27
	v_mul_f32_e32 v65, v25, v25
	v_mul_f32_e32 v66, v27, v27
	global_store_dwordx2 v3, v[52:53], s[8:9] offset:1024
	v_fmac_f32_e32 v65, v24, v24
	v_fmac_f32_e32 v66, v26, v26
	v_add_f32_e32 v65, v65, v66
	v_add_f32_e32 v64, v64, v65
	v_cvt_pk_bf16_f32 v54, v28, v29
	v_cvt_pk_bf16_f32 v55, v30, v31
	v_mul_f32_e32 v65, v29, v29
	v_mul_f32_e32 v66, v31, v31
	global_store_dwordx2 v3, v[54:55], s[8:9] offset:1536
	v_fmac_f32_e32 v65, v28, v28
	v_fmac_f32_e32 v66, v30, v30
	v_add_f32_e32 v65, v65, v66
	v_add_f32_e32 v64, v64, v65
	v_cvt_pk_bf16_f32 v56, v32, v33
	v_cvt_pk_bf16_f32 v57, v34, v35
	v_mul_f32_e32 v65, v33, v33
	v_mul_f32_e32 v66, v35, v35
	global_store_dwordx2 v3, v[56:57], s[8:9] offset:2048
	v_fmac_f32_e32 v65, v32, v32
	v_fmac_f32_e32 v66, v34, v34
	v_add_f32_e32 v65, v65, v66
	v_add_f32_e32 v64, v64, v65
	v_cvt_pk_bf16_f32 v58, v36, v37
	v_cvt_pk_bf16_f32 v59, v38, v39
	v_mul_f32_e32 v65, v37, v37
	v_mul_f32_e32 v66, v39, v39
	global_store_dwordx2 v3, v[58:59], s[8:9] offset:2560
	v_fmac_f32_e32 v65, v36, v36
	v_fmac_f32_e32 v66, v38, v38
	v_add_f32_e32 v65, v65, v66
	v_add_f32_e32 v64, v64, v65
	v_cvt_pk_bf16_f32 v60, v40, v41
	v_cvt_pk_bf16_f32 v61, v42, v43
	v_mul_f32_e32 v65, v41, v41
	v_mul_f32_e32 v66, v43, v43
	global_store_dwordx2 v3, v[60:61], s[8:9] offset:3072
	v_fmac_f32_e32 v65, v40, v40
	v_fmac_f32_e32 v66, v42, v42
	v_add_f32_e32 v65, v65, v66
	v_add_f32_e32 v64, v64, v65
	v_cvt_pk_bf16_f32 v62, v44, v45
	v_cvt_pk_bf16_f32 v63, v46, v47
	v_mul_f32_e32 v65, v45, v45
	v_mul_f32_e32 v66, v47, v47
	global_store_dwordx2 v3, v[62:63], s[8:9] offset:3584
	v_fmac_f32_e32 v65, v44, v44
	v_fmac_f32_e32 v66, v46, v46
	v_add_f32_e32 v65, v65, v66
	v_add_f32_e32 v64, v64, v65
	ds_bpermute_b32 v67, v68, v64
	s_waitcnt lgkmcnt(0)
	v_add_f32_e32 v64, v64, v67
	ds_bpermute_b32 v67, v69, v64
	s_waitcnt lgkmcnt(0)
	v_add_f32_e32 v64, v64, v67
	ds_bpermute_b32 v67, v70, v64
	s_waitcnt lgkmcnt(0)
	v_add_f32_e32 v64, v64, v67
	ds_bpermute_b32 v67, v71, v64
	s_waitcnt lgkmcnt(0)
	v_add_f32_e32 v64, v64, v67
	ds_bpermute_b32 v67, v72, v64
	s_waitcnt lgkmcnt(0)
	v_add_f32_e32 v64, v64, v67
	ds_bpermute_b32 v67, v73, v64
	s_waitcnt lgkmcnt(0)
	v_add_f32_e32 v64, v64, v67
	s_mov_b64 exec, 1
	global_store_dword v4, v64, s[12:13]
	s_mov_b64 exec, s[0:1]
	s_branch .Lxb_next_f
; __device__ __forceinline__ unsigned cvt_pk_bf16(float lo, float hi) { unsigned r; asm volatile("v_cvt_pk_bf16_f32 %0, %1, %2" : "=v"(r) : "v"(lo), "v"(hi)); return r; }
; #define GAS __attribute__((address_space(1)))
; __device__ __forceinline__ void p0_prologue(const In& in, float* out, unsigned char* ws, LAS unsigned char* lds, int tid, int lane, int wave) {
;     ...
;     { bf16* XB = (bf16*)(ws + WS_XB); float* ss1 = (float*)(ws + WS_STAT) + ST_SS1 * MROWS;
;       for (int mm = gw; mm < MROWS * P0_REP; mm += NGW) { const int m = mm % MROWS; const GAS f32x4* xr = (const GAS f32x4*)(in.x + (size_t)m * DM) + lane; GAS v2u* o = (GAS v2u*)(XB + (size_t)m * DM) + lane; float s = 0.f;
; #pragma unroll
;           for (int j = 0; j < 8; ++j) { const f32x4 v = xr[64 * j]; s += (v.x * v.x + v.y * v.y) + (v.z * v.z + v.w * v.w); v2u w; w.x = cvt_pk_bf16(v.x, v.y); w.y = cvt_pk_bf16(v.z, v.w); o[64 * j] = w; }
;           s = wave_sum(s); if (lane == 0) ss1[m] = s; } }
.Lxb_last_f:
	s_waitcnt vmcnt(0)
	v_cvt_pk_bf16_f32 v48, v16, v17
	v_cvt_pk_bf16_f32 v49, v18, v19
	v_mul_f32_e32 v65, v17, v17
	v_mul_f32_e32 v66, v19, v19
	global_store_dwordx2 v3, v[48:49], s[8:9]
	v_fmac_f32_e32 v65, v16, v16
	v_fmac_f32_e32 v66, v18, v18
	v_add_f32_e32 v64, v65, v66
	v_cvt_pk_bf16_f32 v50, v20, v21
	v_cvt_pk_bf16_f32 v51, v22, v23
	v_mul_f32_e32 v65, v21, v21
	v_mul_f32_e32 v66, v23, v23
	global_store_dwordx2 v3, v[50:51], s[8:9] offset:512
	v_fmac_f32_e32 v65, v20, v20
	v_fmac_f32_e32 v66, v22, v22
	v_add_f32_e32 v65, v65, v66
	v_add_f32_e32 v64, v64, v65
	v_cvt_pk_bf16_f32 v52, v24, v25
	v_cvt_pk_bf16_f32 v53, v26, v27
	v_mul_f32_e32 v65, v25, v25
	v_mul_f32_e32 v66, v27, v27
	global_store_dwordx2 v3, v[52:53], s[8:9] offset:1024
	v_fmac_f32_e32 v65, v24, v24
	v_fmac_f32_e32 v66, v26, v26
	v_add_f32_e32 v65, v65, v66
	v_add_f32_e32 v64, v64, v65
	v_cvt_pk_bf16_f32 v54, v28, v29
	v_cvt_pk_bf16_f32 v55, v30, v31
	v_mul_f32_e32 v65, v29, v29
	v_mul_f32_e32 v66, v31, v31
	global_store_dwordx2 v3, v[54:55], s[8:9] offset:1536
	v_fmac_f32_e32 v65, v28, v28
	v_fmac_f32_e32 v66, v30, v30
	v_add_f32_e32 v65, v65, v66
	v_add_f32_e32 v64, v64, v65
	v_cvt_pk_bf16_f32 v56, v32, v33
	v_cvt_pk_bf16_f32 v57, v34, v35
	v_mul_f32_e32 v65, v33, v33
	v_mul_f32_e32 v66, v35, v35
	global_store_dwordx2 v3, v[56:57], s[8:9] offset:2048
	v_fmac_f32_e32 v65, v32, v32
	v_fmac_f32_e32 v66, v34, v34
	v_add_f32_e32 v65, v65, v66
	v_add_f32_e32 v64, v64, v65
	v_cvt_pk_bf16_f32 v58, v36, v37
	v_cvt_pk_bf16_f32 v59, v38, v39
	v_mul_f32_e32 v65, v37, v37
	v_mul_f32_e32 v66, v39, v39
	global_store_dwordx2 v3, v[58:59], s[8:9] offset:2560
	v_fmac_f32_e32 v65, v36, v36
	v_fmac_f32_e32 v66, v38, v38
	v_add_f32_e32 v65, v65, v66
	v_add_f32_e32 v64, v64, v65
	v_cvt_pk_bf16_f32 v60, v40, v41
	v_cvt_pk_bf16_f32 v61, v42, v43
	v_mul_f32_e32 v65, v41, v41
	v_mul_f32_e32 v66, v43, v43
	global_store_dwordx2 v3, v[60:61], s[8:9] offset:3072
	v_fmac_f32_e32 v65, v40, v40
	v_fmac_f32_e32 v66, v42, v42
	v_add_f32_e32 v65, v65, v66
	v_add_f32_e32 v64, v64, v65
	v_cvt_pk_bf16_f32 v62, v44, v45
	v_cvt_pk_bf16_f32 v63, v46, v47
	v_mul_f32_e32 v65, v45, v45
	v_mul_f32_e32 v66, v47, v47
	global_store_dwordx2 v3, v[62:63], s[8:9] offset:3584
	v_fmac_f32_e32 v65, v44, v44
	v_fmac_f32_e32 v66, v46, v46
	v_add_f32_e32 v65, v65, v66
	v_add_f32_e32 v64, v64, v65
	ds_bpermute_b32 v67, v68, v64
	s_waitcnt lgkmcnt(0)
	v_add_f32_e32 v64, v64, v67
	ds_bpermute_b32 v67, v69, v64
	s_waitcnt lgkmcnt(0)
	v_add_f32_e32 v64, v64, v67
	ds_bpermute_b32 v67, v70, v64
	s_waitcnt lgkmcnt(0)
	v_add_f32_e32 v64, v64, v67
	ds_bpermute_b32 v67, v71, v64
	s_waitcnt lgkmcnt(0)
	v_add_f32_e32 v64, v64, v67
	ds_bpermute_b32 v67, v72, v64
	s_waitcnt lgkmcnt(0)
	v_add_f32_e32 v64, v64, v67
	ds_bpermute_b32 v67, v73, v64
	s_waitcnt lgkmcnt(0)
	v_add_f32_e32 v64, v64, v67
	s_mov_b64 exec, 1
	global_store_dword v4, v64, s[12:13]
	s_mov_b64 exec, s[0:1]
	s_branch .LBB0_196
.Lxb_next_f:
.Lxb_loop:
	s_lshl_b32 s3, s6, 12
	s_add_u32 s8, s28, s3
	s_addc_u32 s9, s29, 0
	s_lshl_b32 s3, s6, 2
	s_add_u32 s12, s68, s3
	s_addc_u32 s13, s69, 0
	s_add_i32 s6, s6, s26
	s_cmpk_gt_i32 s6, 0x7fff
	s_cbranch_scc1 .Lxb_last_b
	s_lshl_b32 s3, s6, 13
	s_add_u32 s4, s52, s3
	s_addc_u32 s5, s53, 0
	s_add_u32 s4, s4, 0x1000
	s_addc_u32 s5, s5, 0
	global_load_dwordx4 v[16:19], v2, s[4:5] offset:-4096
	global_load_dwordx4 v[20:23], v2, s[4:5] offset:-3072
	global_load_dwordx4 v[24:27], v2, s[4:5] offset:-2048
	global_load_dwordx4 v[28:31], v2, s[4:5] offset:-1024
	global_load_dwordx4 v[32:35], v2, s[4:5] offset:0
	global_load_dwordx4 v[36:39], v2, s[4:5] offset:1024
	global_load_dwordx4 v[40:43], v2, s[4:5] offset:2048
	global_load_dwordx4 v[44:47], v2, s[4:5] offset:3072
	s_waitcnt vmcnt(17)
	v_cvt_pk_bf16_f32 v48, v80, v81
	v_cvt_pk_bf16_f32 v49, v82, v83
	v_mul_f32_e32 v65, v81, v81
	v_mul_f32_e32 v66, v83, v83
	global_store_dwordx2 v3, v[48:49], s[8:9]
	v_fmac_f32_e32 v65, v80, v80
	v_fmac_f32_e32 v66, v82, v82
	v_add_f32_e32 v64, v65, v66
	v_cvt_pk_bf16_f32 v50, v84, v85
	v_cvt_pk_bf16_f32 v51, v86, v87
	v_mul_f32_e32 v65, v85, v85
	v_mul_f32_e32 v66, v87, v87
	global_store_dwordx2 v3, v[50:51], s[8:9] offset:512
	v_fmac_f32_e32 v65, v84, v84
	v_fmac_f32_e32 v66, v86, v86
	v_add_f32_e32 v65, v65, v66
	v_add_f32_e32 v64, v64, v65
	v_cvt_pk_bf16_f32 v52, v88, v89
	v_cvt_pk_bf16_f32 v53, v90, v91
	v_mul_f32_e32 v65, v89, v89
	v_mul_f32_e32 v66, v91, v91
	global_store_dwordx2 v3, v[52:53], s[8:9] offset:1024
	v_fmac_f32_e32 v65, v88, v88
	v_fmac_f32_e32 v66, v90, v90
	v_add_f32_e32 v65, v65, v66
	v_add_f32_e32 v64, v64, v65
	v_cvt_pk_bf16_f32 v54, v92, v93
	v_cvt_pk_bf16_f32 v55, v94, v95
	v_mul_f32_e32 v65, v93, v93
	v_mul_f32_e32 v66, v95, v95
	global_store_dwordx2 v3, v[54:55], s[8:9] offset:1536
	v_fmac_f32_e32 v65, v92, v92
	v_fmac_f32_e32 v66, v94, v94
	v_add_f32_e32 v65, v65, v66
	v_add_f32_e32 v64, v64, v65
	v_cvt_pk_bf16_f32 v56, v96, v97
	v_cvt_pk_bf16_f32 v57, v98, v99
	v_mul_f32_e32 v65, v97, v97
	v_mul_f32_e32 v66, v99, v99
	global_store_dwordx2 v3, v[56:57], s[8:9] offset:2048
	v_fmac_f32_e32 v65, v96, v96
	v_fmac_f32_e32 v66, v98, v98
	v_add_f32_e32 v65, v65, v66
	v_add_f32_e32 v64, v64, v65
	v_cvt_pk_bf16_f32 v58, v100, v101
	v_cvt_pk_bf16_f32 v59, v102, v103
	v_mul_f32_e32 v65, v101, v101
	v_mul_f32_e32 v66, v103, v103
	global_store_dwordx2 v3, v[58:59], s[8:9] offset:2560
	v_fmac_f32_e32 v65, v100, v100
	v_fmac_f32_e32 v66, v102, v102
	v_add_f32_e32 v65, v65, v66
	v_add_f32_e32 v64, v64, v65
	v_cvt_pk_bf16_f32 v60, v104, v105
	v_cvt_pk_bf16_f32 v61, v106, v107
	v_mul_f32_e32 v65, v105, v105
	v_mul_f32_e32 v66, v107, v107
	global_store_dwordx2 v3, v[60:61], s[8:9] offset:3072
	v_fmac_f32_e32 v65, v104, v104
	v_fmac_f32_e32 v66, v106, v106
	v_add_f32_e32 v65, v65, v66
	v_add_f32_e32 v64, v64, v65
	v_cvt_pk_bf16_f32 v62, v108, v109
	v_cvt_pk_bf16_f32 v63, v110, v111
	v_mul_f32_e32 v65, v109, v109
	v_mul_f32_e32 v66, v111, v111
	global_store_dwordx2 v3, v[62:63], s[8:9] offset:3584
	v_fmac_f32_e32 v65, v108, v108
	v_fmac_f32_e32 v66, v110, v110
	v_add_f32_e32 v65, v65, v66
	v_add_f32_e32 v64, v64, v65
	ds_bpermute_b32 v67, v68, v64
	s_waitcnt lgkmcnt(0)
	v_add_f32_e32 v64, v64, v67
	ds_bpermute_b32 v67, v69, v64
	s_waitcnt lgkmcnt(0)
	v_add_f32_e32 v64, v64, v67
	ds_bpermute_b32 v67, v70, v64
	s_waitcnt lgkmcnt(0)
	v_add_f32_e32 v64, v64, v67
	ds_bpermute_b32 v67, v71, v64
	s_waitcnt lgkmcnt(0)
	v_add_f32_e32 v64, v64, v67
	ds_bpermute_b32 v67, v72, v64
	s_waitcnt lgkmcnt(0)
	v_add_f32_e32 v64, v64, v67
	ds_bpermute_b32 v67, v73, v64
	s_waitcnt lgkmcnt(0)
	v_add_f32_e32 v64, v64, v67
	s_mov_b64 exec, 1
	global_store_dword v4, v64, s[12:13]
	s_mov_b64 exec, s[0:1]
	s_branch .Lxb_next_b
; __device__ __forceinline__ unsigned cvt_pk_bf16(float lo, float hi) { unsigned r; asm volatile("v_cvt_pk_bf16_f32 %0, %1, %2" : "=v"(r) : "v"(lo), "v"(hi)); return r; }
; #define GAS __attribute__((address_space(1)))
; __device__ __forceinline__ void p0_prologue(const In& in, float* out, unsigned char* ws, LAS unsigned char* lds, int tid, int lane, int wave) {
;     ...
;     { bf16* XB = (bf16*)(ws + WS_XB); float* ss1 = (float*)(ws + WS_STAT) + ST_SS1 * MROWS;
;       for (int mm = gw; mm < MROWS * P0_REP; mm += NGW) { const int m = mm % MROWS; const GAS f32x4* xr = (const GAS f32x4*)(in.x + (size_t)m * DM) + lane; GAS v2u* o = (GAS v2u*)(XB + (size_t)m * DM) + lane; float s = 0.f;
; #pragma unroll
;           for (int j = 0; j < 8; ++j) { const f32x4 v = xr[64 * j]; s += (v.x * v.x + v.y * v.y) + (v.z * v.z + v.w * v.w); v2u w; w.x = cvt_pk_bf16(v.x, v.y); w.y = cvt_pk_bf16(v.z, v.w); o[64 * j] = w; }
;           s = wave_sum(s); if (lane == 0) ss1[m] = s; } }
.Lxb_last_b:
	s_waitcnt vmcnt(9)
	v_cvt_pk_bf16_f32 v48, v80, v81
	v_cvt_pk_bf16_f32 v49, v82, v83
	v_mul_f32_e32 v65, v81, v81
	v_mul_f32_e32 v66, v83, v83
	global_store_dwordx2 v3, v[48:49], s[8:9]
	v_fmac_f32_e32 v65, v80, v80
	v_fmac_f32_e32 v66, v82, v82
	v_add_f32_e32 v64, v65, v66
	v_cvt_pk_bf16_f32 v50, v84, v85
	v_cvt_pk_bf16_f32 v51, v86, v87
	v_mul_f32_e32 v65, v85, v85
	v_mul_f32_e32 v66, v87, v87
	global_store_dwordx2 v3, v[50:51], s[8:9] offset:512
	v_fmac_f32_e32 v65, v84, v84
	v_fmac_f32_e32 v66, v86, v86
	v_add_f32_e32 v65, v65, v66
	v_add_f32_e32 v64, v64, v65
	v_cvt_pk_bf16_f32 v52, v88, v89
	v_cvt_pk_bf16_f32 v53, v90, v91
	v_mul_f32_e32 v65, v89, v89
	v_mul_f32_e32 v66, v91, v91
	global_store_dwordx2 v3, v[52:53], s[8:9] offset:1024
	v_fmac_f32_e32 v65, v88, v88
	v_fmac_f32_e32 v66, v90, v90
	v_add_f32_e32 v65, v65, v66
	v_add_f32_e32 v64, v64, v65
	v_cvt_pk_bf16_f32 v54, v92, v93
	v_cvt_pk_bf16_f32 v55, v94, v95
	v_mul_f32_e32 v65, v93, v93
	v_mul_f32_e32 v66, v95, v95
	global_store_dwordx2 v3, v[54:55], s[8:9] offset:1536
	v_fmac_f32_e32 v65, v92, v92
	v_fmac_f32_e32 v66, v94, v94
	v_add_f32_e32 v65, v65, v66
	v_add_f32_e32 v64, v64, v65
	v_cvt_pk_bf16_f32 v56, v96, v97
	v_cvt_pk_bf16_f32 v57, v98, v99
	v_mul_f32_e32 v65, v97, v97
	v_mul_f32_e32 v66, v99, v99
	global_store_dwordx2 v3, v[56:57], s[8:9] offset:2048
	v_fmac_f32_e32 v65, v96, v96
	v_fmac_f32_e32 v66, v98, v98
	v_add_f32_e32 v65, v65, v66
	v_add_f32_e32 v64, v64, v65
	v_cvt_pk_bf16_f32 v58, v100, v101
	v_cvt_pk_bf16_f32 v59, v102, v103
	v_mul_f32_e32 v65, v101, v101
	v_mul_f32_e32 v66, v103, v103
	global_store_dwordx2 v3, v[58:59], s[8:9] offset:2560
	v_fmac_f32_e32 v65, v100, v100
	v_fmac_f32_e32 v66, v102, v102
	v_add_f32_e32 v65, v65, v66
	v_add_f32_e32 v64, v64, v65
	v_cvt_pk_bf16_f32 v60, v104, v105
	v_cvt_pk_bf16_f32 v61, v106, v107
	v_mul_f32_e32 v65, v105, v105
	v_mul_f32_e32 v66, v107, v107
	global_store_dwordx2 v3, v[60:61], s[8:9] offset:3072
	v_fmac_f32_e32 v65, v104, v104
	v_fmac_f32_e32 v66, v106, v106
	v_add_f32_e32 v65, v65, v66
	v_add_f32_e32 v64, v64, v65
	v_cvt_pk_bf16_f32 v62, v108, v109
	v_cvt_pk_bf16_f32 v63, v110, v111
	v_mul_f32_e32 v65, v109, v109
	v_mul_f32_e32 v66, v111, v111
	global_store_dwordx2 v3, v[62:63], s[8:9] offset:3584
	v_fmac_f32_e32 v65, v108, v108
	v_fmac_f32_e32 v66, v110, v110
	v_add_f32_e32 v65, v65, v66
	v_add_f32_e32 v64, v64, v65
	ds_bpermute_b32 v67, v68, v64
	s_waitcnt lgkmcnt(0)
	v_add_f32_e32 v64, v64, v67
	ds_bpermute_b32 v67, v69, v64
	s_waitcnt lgkmcnt(0)
	v_add_f32_e32 v64, v64, v67
	ds_bpermute_b32 v67, v70, v64
	s_waitcnt lgkmcnt(0)
	v_add_f32_e32 v64, v64, v67
	ds_bpermute_b32 v67, v71, v64
	s_waitcnt lgkmcnt(0)
	v_add_f32_e32 v64, v64, v67
	ds_bpermute_b32 v67, v72, v64
	s_waitcnt lgkmcnt(0)
	v_add_f32_e32 v64, v64, v67
	ds_bpermute_b32 v67, v73, v64
	s_waitcnt lgkmcnt(0)
	v_add_f32_e32 v64, v64, v67
	s_mov_b64 exec, 1
	global_store_dword v4, v64, s[12:13]
	s_mov_b64 exec, s[0:1]
	s_branch .LBB0_196
; __device__ __forceinline__ unsigned cvt_pk_bf16(float lo, float hi) { unsigned r; asm volatile("v_cvt_pk_bf16_f32 %0, %1, %2" : "=v"(r) : "v"(lo), "v"(hi)); return r; }
; #define GAS __attribute__((address_space(1)))
; __device__ __forceinline__ void p0_prologue(const In& in, float* out, unsigned char* ws, LAS unsigned char* lds, int tid, int lane, int wave) {
;     ...
;     { bf16* XB = (bf16*)(ws + WS_XB); float* ss1 = (float*)(ws + WS_STAT) + ST_SS1 * MROWS;
;       for (int mm = gw; mm < MROWS * P0_REP; mm += NGW) { const int m = mm % MROWS; const GAS f32x4* xr = (const GAS f32x4*)(in.x + (size_t)m * DM) + lane; GAS v2u* o = (GAS v2u*)(XB + (size_t)m * DM) + lane; float s = 0.f;
; #pragma unroll
;           for (int j = 0; j < 8; ++j) { const f32x4 v = xr[64 * j]; s += (v.x * v.x + v.y * v.y) + (v.z * v.z + v.w * v.w); v2u w; w.x = cvt_pk_bf16(v.x, v.y); w.y = cvt_pk_bf16(v.z, v.w); o[64 * j] = w; }
;           s = wave_sum(s); if (lane == 0) ss1[m] = s; } }
.Lxb_next_b:
	s_lshl_b32 s3, s6, 12
	s_add_u32 s8, s28, s3
	s_addc_u32 s9, s29, 0
	s_lshl_b32 s3, s6, 2
	s_add_u32 s12, s68, s3
	s_addc_u32 s13, s69, 0
	s_add_i32 s6, s6, s26
	s_cmpk_gt_i32 s6, 0x7fff
	s_cbranch_scc1 .Lxb_last_a
	s_lshl_b32 s3, s6, 13
	s_add_u32 s4, s52, s3
	s_addc_u32 s5, s53, 0
	s_add_u32 s4, s4, 0x1000
	s_addc_u32 s5, s5, 0
	global_load_dwordx4 v[80:83], v2, s[4:5] offset:-4096
	global_load_dwordx4 v[84:87], v2, s[4:5] offset:-3072
	global_load_dwordx4 v[88:91], v2, s[4:5] offset:-2048
	global_load_dwordx4 v[92:95], v2, s[4:5] offset:-1024
	global_load_dwordx4 v[96:99], v2, s[4:5] offset:0
	global_load_dwordx4 v[100:103], v2, s[4:5] offset:1024
	global_load_dwordx4 v[104:107], v2, s[4:5] offset:2048
	global_load_dwordx4 v[108:111], v2, s[4:5] offset:3072
	s_waitcnt vmcnt(17)
	v_cvt_pk_bf16_f32 v48, v16, v17
	v_cvt_pk_bf16_f32 v49, v18, v19
	v_mul_f32_e32 v65, v17, v17
	v_mul_f32_e32 v66, v19, v19
	global_store_dwordx2 v3, v[48:49], s[8:9]
	v_fmac_f32_e32 v65, v16, v16
	v_fmac_f32_e32 v66, v18, v18
	v_add_f32_e32 v64, v65, v66
	v_cvt_pk_bf16_f32 v50, v20, v21
	v_cvt_pk_bf16_f32 v51, v22, v23
	v_mul_f32_e32 v65, v21, v21
	v_mul_f32_e32 v66, v23, v23
	global_store_dwordx2 v3, v[50:51], s[8:9] offset:512
	v_fmac_f32_e32 v65, v20, v20
	v_fmac_f32_e32 v66, v22, v22
	v_add_f32_e32 v65, v65, v66
	v_add_f32_e32 v64, v64, v65
	v_cvt_pk_bf16_f32 v52, v24, v25
	v_cvt_pk_bf16_f32 v53, v26, v27
	v_mul_f32_e32 v65, v25, v25
	v_mul_f32_e32 v66, v27, v27
	global_store_dwordx2 v3, v[52:53], s[8:9] offset:1024
	v_fmac_f32_e32 v65, v24, v24
	v_fmac_f32_e32 v66, v26, v26
	v_add_f32_e32 v65, v65, v66
	v_add_f32_e32 v64, v64, v65
	v_cvt_pk_bf16_f32 v54, v28, v29
	v_cvt_pk_bf16_f32 v55, v30, v31
	v_mul_f32_e32 v65, v29, v29
	v_mul_f32_e32 v66, v31, v31
	global_store_dwordx2 v3, v[54:55], s[8:9] offset:1536
	v_fmac_f32_e32 v65, v28, v28
	v_fmac_f32_e32 v66, v30, v30
	v_add_f32_e32 v65, v65, v66
	v_add_f32_e32 v64, v64, v65
	v_cvt_pk_bf16_f32 v56, v32, v33
	v_cvt_pk_bf16_f32 v57, v34, v35
	v_mul_f32_e32 v65, v33, v33
	v_mul_f32_e32 v66, v35, v35
	global_store_dwordx2 v3, v[56:57], s[8:9] offset:2048
	v_fmac_f32_e32 v65, v32, v32
	v_fmac_f32_e32 v66, v34, v34
	v_add_f32_e32 v65, v65, v66
	v_add_f32_e32 v64, v64, v65
	v_cvt_pk_bf16_f32 v58, v36, v37
	v_cvt_pk_bf16_f32 v59, v38, v39
	v_mul_f32_e32 v65, v37, v37
	v_mul_f32_e32 v66, v39, v39
	global_store_dwordx2 v3, v[58:59], s[8:9] offset:2560
	v_fmac_f32_e32 v65, v36, v36
	v_fmac_f32_e32 v66, v38, v38
	v_add_f32_e32 v65, v65, v66
	v_add_f32_e32 v64, v64, v65
	v_cvt_pk_bf16_f32 v60, v40, v41
	v_cvt_pk_bf16_f32 v61, v42, v43
	v_mul_f32_e32 v65, v41, v41
	v_mul_f32_e32 v66, v43, v43
	global_store_dwordx2 v3, v[60:61], s[8:9] offset:3072
	v_fmac_f32_e32 v65, v40, v40
	v_fmac_f32_e32 v66, v42, v42
	v_add_f32_e32 v65, v65, v66
	v_add_f32_e32 v64, v64, v65
	v_cvt_pk_bf16_f32 v62, v44, v45
	v_cvt_pk_bf16_f32 v63, v46, v47
	v_mul_f32_e32 v65, v45, v45
	v_mul_f32_e32 v66, v47, v47
	global_store_dwordx2 v3, v[62:63], s[8:9] offset:3584
	v_fmac_f32_e32 v65, v44, v44
	v_fmac_f32_e32 v66, v46, v46
	v_add_f32_e32 v65, v65, v66
	v_add_f32_e32 v64, v64, v65
	ds_bpermute_b32 v67, v68, v64
	s_waitcnt lgkmcnt(0)
	v_add_f32_e32 v64, v64, v67
	ds_bpermute_b32 v67, v69, v64
	s_waitcnt lgkmcnt(0)
	v_add_f32_e32 v64, v64, v67
	ds_bpermute_b32 v67, v70, v64
	s_waitcnt lgkmcnt(0)
	v_add_f32_e32 v64, v64, v67
	ds_bpermute_b32 v67, v71, v64
	s_waitcnt lgkmcnt(0)
	v_add_f32_e32 v64, v64, v67
	ds_bpermute_b32 v67, v72, v64
	s_waitcnt lgkmcnt(0)
	v_add_f32_e32 v64, v64, v67
	ds_bpermute_b32 v67, v73, v64
	s_waitcnt lgkmcnt(0)
	v_add_f32_e32 v64, v64, v67
	s_mov_b64 exec, 1
	global_store_dword v4, v64, s[12:13]
	s_mov_b64 exec, s[0:1]
	s_branch .Lxb_next_a
.Lxb_last_a:
	s_waitcnt vmcnt(9)
	v_cvt_pk_bf16_f32 v48, v16, v17
	v_cvt_pk_bf16_f32 v49, v18, v19
	v_mul_f32_e32 v65, v17, v17
	v_mul_f32_e32 v66, v19, v19
	global_store_dwordx2 v3, v[48:49], s[8:9]
	v_fmac_f32_e32 v65, v16, v16
	v_fmac_f32_e32 v66, v18, v18
	v_add_f32_e32 v64, v65, v66
	v_cvt_pk_bf16_f32 v50, v20, v21
	v_cvt_pk_bf16_f32 v51, v22, v23
	v_mul_f32_e32 v65, v21, v21
	v_mul_f32_e32 v66, v23, v23
	global_store_dwordx2 v3, v[50:51], s[8:9] offset:512
	v_fmac_f32_e32 v65, v20, v20
	v_fmac_f32_e32 v66, v22, v22
	v_add_f32_e32 v65, v65, v66
	v_add_f32_e32 v64, v64, v65
	v_cvt_pk_bf16_f32 v52, v24, v25
	v_cvt_pk_bf16_f32 v53, v26, v27
	v_mul_f32_e32 v65, v25, v25
	v_mul_f32_e32 v66, v27, v27
	global_store_dwordx2 v3, v[52:53], s[8:9] offset:1024
	v_fmac_f32_e32 v65, v24, v24
	v_fmac_f32_e32 v66, v26, v26
	v_add_f32_e32 v65, v65, v66
	v_add_f32_e32 v64, v64, v65
	v_cvt_pk_bf16_f32 v54, v28, v29
	v_cvt_pk_bf16_f32 v55, v30, v31
	v_mul_f32_e32 v65, v29, v29
	v_mul_f32_e32 v66, v31, v31
	global_store_dwordx2 v3, v[54:55], s[8:9] offset:1536
	v_fmac_f32_e32 v65, v28, v28
	v_fmac_f32_e32 v66, v30, v30
	v_add_f32_e32 v65, v65, v66
	v_add_f32_e32 v64, v64, v65
	v_cvt_pk_bf16_f32 v56, v32, v33
	v_cvt_pk_bf16_f32 v57, v34, v35
	v_mul_f32_e32 v65, v33, v33
	v_mul_f32_e32 v66, v35, v35
	global_store_dwordx2 v3, v[56:57], s[8:9] offset:2048
	v_fmac_f32_e32 v65, v32, v32
	v_fmac_f32_e32 v66, v34, v34
	v_add_f32_e32 v65, v65, v66
	v_add_f32_e32 v64, v64, v65
	v_cvt_pk_bf16_f32 v58, v36, v37
	v_cvt_pk_bf16_f32 v59, v38, v39
	v_mul_f32_e32 v65, v37, v37
	v_mul_f32_e32 v66, v39, v39
	global_store_dwordx2 v3, v[58:59], s[8:9] offset:2560
	v_fmac_f32_e32 v65, v36, v36
	v_fmac_f32_e32 v66, v38, v38
	v_add_f32_e32 v65, v65, v66
	v_add_f32_e32 v64, v64, v65
	v_cvt_pk_bf16_f32 v60, v40, v41
	v_cvt_pk_bf16_f32 v61, v42, v43
	v_mul_f32_e32 v65, v41, v41
	v_mul_f32_e32 v66, v43, v43
	global_store_dwordx2 v3, v[60:61], s[8:9] offset:3072
	v_fmac_f32_e32 v65, v40, v40
	v_fmac_f32_e32 v66, v42, v42
	v_add_f32_e32 v65, v65, v66
	v_add_f32_e32 v64, v64, v65
	v_cvt_pk_bf16_f32 v62, v44, v45
	v_cvt_pk_bf16_f32 v63, v46, v47
	v_mul_f32_e32 v65, v45, v45
	v_mul_f32_e32 v66, v47, v47
	global_store_dwordx2 v3, v[62:63], s[8:9] offset:3584
	v_fmac_f32_e32 v65, v44, v44
	v_fmac_f32_e32 v66, v46, v46
	v_add_f32_e32 v65, v65, v66
	v_add_f32_e32 v64, v64, v65
	ds_bpermute_b32 v67, v68, v64
	s_waitcnt lgkmcnt(0)
	v_add_f32_e32 v64, v64, v67
	ds_bpermute_b32 v67, v69, v64
	s_waitcnt lgkmcnt(0)
	v_add_f32_e32 v64, v64, v67
	ds_bpermute_b32 v67, v70, v64
	s_waitcnt lgkmcnt(0)
	v_add_f32_e32 v64, v64, v67
	ds_bpermute_b32 v67, v71, v64
	s_waitcnt lgkmcnt(0)
	v_add_f32_e32 v64, v64, v67
	ds_bpermute_b32 v67, v72, v64
	s_waitcnt lgkmcnt(0)
	v_add_f32_e32 v64, v64, v67
	ds_bpermute_b32 v67, v73, v64
	s_waitcnt lgkmcnt(0)
	v_add_f32_e32 v64, v64, v67
	s_mov_b64 exec, 1
	global_store_dword v4, v64, s[12:13]
	s_mov_b64 exec, s[0:1]
	s_branch .LBB0_196
.Lxb_next_a:
	s_branch .Lxb_loop

; __device__ __forceinline__ unsigned cvt_pk_bf16(float lo, float hi) { unsigned r; asm volatile("v_cvt_pk_bf16_f32 %0, %1, %2" : "=v"(r) : "v"(lo), "v"(hi)); return r; }
; #define GAS __attribute__((address_space(1)))
; __device__ __forceinline__ void p0_prologue(const In& in, float* out, unsigned char* ws, LAS unsigned char* lds, int tid, int lane, int wave) {
;     ...
;     { const GAS f32x4* ps = (const GAS f32x4*)in.p; GAS v2u* o = (GAS v2u*)(ws + WS_PB);
;       for (int i = bx * NTHREADS + tid; i < MROWS * PLE / 4; i += G * NTHREADS) { const f32x4 v = ps[i]; v2u w; w.x = cvt_pk_bf16(v.x, v.y); w.y = cvt_pk_bf16(v.z, v.w); o[i] = w; } }
.Lpb_entry:
	s_lshl_b32 s4, s70, 9
	v_ashrrev_i32_e32 v11, 31, v10
	v_mov_b32_e32 v4, s54
	v_mov_b32_e32 v5, s55
	v_lshl_add_u64 v[2:3], v[10:11], 3, s[68:69]
	s_mov_b64 s[6:7], 0xb000000
	s_ashr_i32 s5, s4, 31
	v_lshl_add_u64 v[2:3], v[2:3], 0, s[6:7]
	s_lshl_b64 s[6:7], s[4:5], 3
	v_lshl_add_u64 v[4:5], v[10:11], 4, v[4:5]
	s_lshl_b64 s[8:9], s[4:5], 4
	s_mov_b32 s3, s2
	s_mul_i32 s10, s70, 7
.Lpb_batch:
	s_add_i32 s11, s3, s10
	s_cmpk_ge_i32 s11, 0x1000
	s_cbranch_scc1 .Lpb_tail
	global_load_dwordx4 v[16:19], v[4:5], off
	v_lshl_add_u64 v[4:5], v[4:5], 0, s[8:9]
	global_load_dwordx4 v[20:23], v[4:5], off
	v_lshl_add_u64 v[4:5], v[4:5], 0, s[8:9]
	global_load_dwordx4 v[24:27], v[4:5], off
	v_lshl_add_u64 v[4:5], v[4:5], 0, s[8:9]
	global_load_dwordx4 v[28:31], v[4:5], off
	v_lshl_add_u64 v[4:5], v[4:5], 0, s[8:9]
	global_load_dwordx4 v[32:35], v[4:5], off
	v_lshl_add_u64 v[4:5], v[4:5], 0, s[8:9]
	global_load_dwordx4 v[36:39], v[4:5], off
	v_lshl_add_u64 v[4:5], v[4:5], 0, s[8:9]
	global_load_dwordx4 v[40:43], v[4:5], off
	v_lshl_add_u64 v[4:5], v[4:5], 0, s[8:9]
	global_load_dwordx4 v[44:47], v[4:5], off
	v_lshl_add_u64 v[4:5], v[4:5], 0, s[8:9]
	s_waitcnt vmcnt(7)
	v_cvt_pk_bf16_f32 v48, v16, v17
	v_cvt_pk_bf16_f32 v49, v18, v19
	global_store_dwordx2 v[2:3], v[48:49], off
	v_lshl_add_u64 v[2:3], v[2:3], 0, s[6:7]
	s_waitcnt vmcnt(7)
	v_cvt_pk_bf16_f32 v50, v20, v21
	v_cvt_pk_bf16_f32 v51, v22, v23
	global_store_dwordx2 v[2:3], v[50:51], off
	v_lshl_add_u64 v[2:3], v[2:3], 0, s[6:7]
	s_waitcnt vmcnt(7)
	v_cvt_pk_bf16_f32 v52, v24, v25
	v_cvt_pk_bf16_f32 v53, v26, v27
	global_store_dwordx2 v[2:3], v[52:53], off
	v_lshl_add_u64 v[2:3], v[2:3], 0, s[6:7]
	s_waitcnt vmcnt(7)
	v_cvt_pk_bf16_f32 v54, v28, v29
	v_cvt_pk_bf16_f32 v55, v30, v31
	global_store_dwordx2 v[2:3], v[54:55], off
	v_lshl_add_u64 v[2:3], v[2:3], 0, s[6:7]
	s_waitcnt vmcnt(7)
	v_cvt_pk_bf16_f32 v56, v32, v33
	v_cvt_pk_bf16_f32 v57, v34, v35
	global_store_dwordx2 v[2:3], v[56:57], off
	v_lshl_add_u64 v[2:3], v[2:3], 0, s[6:7]
	s_waitcnt vmcnt(7)
	v_cvt_pk_bf16_f32 v58, v36, v37
	v_cvt_pk_bf16_f32 v59, v38, v39
	global_store_dwordx2 v[2:3], v[58:59], off
	v_lshl_add_u64 v[2:3], v[2:3], 0, s[6:7]
	s_waitcnt vmcnt(7)
	v_cvt_pk_bf16_f32 v60, v40, v41
	v_cvt_pk_bf16_f32 v61, v42, v43
	global_store_dwordx2 v[2:3], v[60:61], off
	v_lshl_add_u64 v[2:3], v[2:3], 0, s[6:7]
	s_waitcnt vmcnt(7)
	v_cvt_pk_bf16_f32 v62, v44, v45
	v_cvt_pk_bf16_f32 v63, v46, v47
	global_store_dwordx2 v[2:3], v[62:63], off
	v_lshl_add_u64 v[2:3], v[2:3], 0, s[6:7]
	s_lshl_b32 s11, s70, 3
	s_add_i32 s3, s3, s11
	s_branch .Lpb_batch
.Lpb_tail:
	s_cmpk_ge_i32 s3, 0x1000
	s_cbranch_scc1 .LBB0_199
	global_load_dwordx4 v[16:19], v[4:5], off
	v_lshl_add_u64 v[4:5], v[4:5], 0, s[8:9]
	s_add_i32 s3, s3, s70
	s_waitcnt vmcnt(0)
	v_cvt_pk_bf16_f32 v48, v16, v17
	v_cvt_pk_bf16_f32 v49, v18, v19
	global_store_dwordx2 v[2:3], v[48:49], off
	v_lshl_add_u64 v[2:3], v[2:3], 0, s[6:7]
	s_branch .Lpb_tail

; #define PG8_STAGE(bufoff, gbase, voff) do { _Pragma("unroll") for (int _i = 0; _i < 2; ++_i) \
;         { unsigned _vo = (voff)[_i]; asm volatile("" : "+v"(_vo));     \
;         __builtin_amdgcn_global_load_lds((const unsigned*)((const char*)(gbase) + _vo), (PG8_LAS unsigned*)(lds + (bufoff) + ldsw + _i * 8192), 16, 0, 0); } } while (0)
; #define PG8_LDA(dst, b, h) do { _Pragma("unroll") for (int m = 0; m < 4; ++m) _Pragma("unroll") for (int k = 0; k < 2; ++k) dst[m][k] = *(const PG8_LAS bf16x8*)(lds + PG8_SA(b, h) + aoff + m * 2048 + k * 1024); } while (0)
; #define PG8_LDB(dst, b, h) do { _Pragma("unroll") for (int n = 0; n < 2; ++n) _Pragma("unroll") for (int k = 0; k < 2; ++k) dst[n][k] = *(const PG8_LAS bf16x8*)(lds + PG8_SB(b, h) + boff + n * 2048 + k * 1024); } while (0)
; #define PG8_WAIT_V(n) asm volatile("s_waitcnt vmcnt(" #n ")" ::: "memory")
; #define PG8_WAIT_L(n) asm volatile("s_waitcnt lgkmcnt(" #n ")" ::: "memory")
; #define PG8_BAR __builtin_amdgcn_s_barrier()
; #define PG8_SCHED __builtin_amdgcn_sched_barrier(0)
; template <class Epi, class Sched, bool ALIGN_EPI = false, bool SP2 = false, bool ABLK = false, bool F8 = false>
; __device__ __forceinline__ void gemm_phase(PG8_LAS unsigned char* lds, const Gemm g, const Sched& S, const Epi& E, const int wave_s) {
;     ...
;             PG8_LDB(B0, 0, 0); PG8_LDB(B1, 0, 1); PG8_SCHED; PG8_LDA(At, 0, 0); PG8_STAGE(PG8_SA(1, 1), a1 + hstepA, voffA);
;             PG8_WAIT_V(8); PG8_WAIT_L(0); PG8_BAR; PG8_MMA(0, 0, At, B0); PG8_MMA(0, 1, At, B1); PG8_BAR; PG8_SCHED;
;             PG8_LDA(At, 0, 1); PG8_STAGE(PG8_SB(0, 0), b2, voffB); PG8_STAGE(PG8_SB(0, 1), b2 + hstep, voffB); PG8_STAGE(PG8_SA(0, 0), a2, voffA);
;             PG8_WAIT_V(8); PG8_WAIT_L(0); PG8_BAR; PG8_MMA(1, 0, At, B0); PG8_MMA(1, 1, At, B1); PG8_BAR; PG8_SCHED;
.LBB0_223:
	v_add_u32_e32 v128, s64, v160
	ds_read_b128 v[166:169], v128
	ds_read_b128 v[170:173], v128 offset:1024
	ds_read_b128 v[174:177], v128 offset:2048
	ds_read_b128 v[178:181], v128 offset:3072
	v_add_u32_e32 v128, s65, v160
	ds_read_b128 v[182:185], v128
	ds_read_b128 v[186:189], v128 offset:1024
	ds_read_b128 v[190:193], v128 offset:2048
	ds_read_b128 v[194:197], v128 offset:3072
	s_add_u32 s62, s58, 0xfff80080
	s_addc_u32 s63, s59, -1
	s_and_b64 s[60:61], s[60:61], exec
	s_cselect_b32 s61, s63, s49
	s_cselect_b32 s60, s62, s77
	s_cselect_b32 s63, s80, s17
	s_cselect_b32 s62, s79, s78
	v_mov_b32_e32 v128, v156
	ds_read_b128 v[198:201], v163
	ds_read_b128 v[202:205], v163 offset:1024
	ds_read_b128 v[206:209], v163 offset:2048
	ds_read_b128 v[210:213], v163 offset:3072
	ds_read_b128 v[214:217], v163 offset:4096
	ds_read_b128 v[218:221], v163 offset:5120
	ds_read_b128 v[222:225], v163 offset:6144
	ds_read_b128 v[230:233], v163 offset:7168
	s_add_i32 m0, s22, 0xc000
	s_nop 0
	global_load_lds_dwordx4 v128, s[58:59]
	v_mov_b32_e32 v128, v158
	s_add_i32 m0, s22, 0xe000
	s_nop 0
	global_load_lds_dwordx4 v128, s[58:59]
	s_waitcnt vmcnt(8)
	s_waitcnt lgkmcnt(0)
	s_barrier
	s_setprio 1
	s_waitcnt lgkmcnt(0)
	v_mfma_f32_16x16x32_bf16 v[124:127], v[166:169], v[198:201], v[124:127]
	v_mfma_f32_16x16x32_bf16 v[116:119], v[174:177], v[198:201], v[116:119]
	v_mfma_f32_16x16x32_bf16 v[108:111], v[166:169], v[206:209], v[108:111]
	v_mfma_f32_16x16x32_bf16 v[100:103], v[174:177], v[206:209], v[100:103]
	v_mfma_f32_16x16x32_bf16 v[92:95], v[166:169], v[214:217], v[92:95]
	v_mfma_f32_16x16x32_bf16 v[84:87], v[174:177], v[214:217], v[84:87]
	v_mfma_f32_16x16x32_bf16 v[76:79], v[166:169], v[222:225], v[76:79]
	v_mfma_f32_16x16x32_bf16 v[68:71], v[174:177], v[222:225], v[68:71]
	v_mfma_f32_16x16x32_bf16 v[124:127], v[170:173], v[202:205], v[124:127]
	v_mfma_f32_16x16x32_bf16 v[116:119], v[178:181], v[202:205], v[116:119]
	v_mfma_f32_16x16x32_bf16 v[108:111], v[170:173], v[210:213], v[108:111]
	v_mfma_f32_16x16x32_bf16 v[100:103], v[178:181], v[210:213], v[100:103]
	v_mfma_f32_16x16x32_bf16 v[92:95], v[170:173], v[218:221], v[92:95]
	v_mfma_f32_16x16x32_bf16 v[84:87], v[178:181], v[218:221], v[84:87]
	v_mfma_f32_16x16x32_bf16 v[76:79], v[170:173], v[230:233], v[76:79]
	v_mfma_f32_16x16x32_bf16 v[68:71], v[178:181], v[230:233], v[68:71]
	s_setprio 0
	s_setprio 1
	v_mfma_f32_16x16x32_bf16 v[120:123], v[182:185], v[198:201], v[120:123]
	v_mfma_f32_16x16x32_bf16 v[112:115], v[190:193], v[198:201], v[112:115]
	v_mfma_f32_16x16x32_bf16 v[104:107], v[182:185], v[206:209], v[104:107]
	v_mfma_f32_16x16x32_bf16 v[96:99], v[190:193], v[206:209], v[96:99]
	v_mfma_f32_16x16x32_bf16 v[88:91], v[182:185], v[214:217], v[88:91]
	v_mfma_f32_16x16x32_bf16 v[80:83], v[190:193], v[214:217], v[80:83]
	v_mfma_f32_16x16x32_bf16 v[72:75], v[182:185], v[222:225], v[72:75]
	v_mfma_f32_16x16x32_bf16 v[64:67], v[190:193], v[222:225], v[64:67]
	v_mfma_f32_16x16x32_bf16 v[120:123], v[186:189], v[202:205], v[120:123]
	v_mfma_f32_16x16x32_bf16 v[112:115], v[194:197], v[202:205], v[112:115]
	v_mfma_f32_16x16x32_bf16 v[104:107], v[186:189], v[210:213], v[104:107]
	v_mfma_f32_16x16x32_bf16 v[96:99], v[194:197], v[210:213], v[96:99]
	v_mfma_f32_16x16x32_bf16 v[88:91], v[186:189], v[218:221], v[88:91]
	v_mfma_f32_16x16x32_bf16 v[80:83], v[194:197], v[218:221], v[80:83]
	v_mfma_f32_16x16x32_bf16 v[72:75], v[186:189], v[230:233], v[72:75]
	v_mfma_f32_16x16x32_bf16 v[64:67], v[194:197], v[230:233], v[64:67]
	s_setprio 0
	s_barrier
	v_mov_b32_e32 v128, v157
	s_add_i32 s72, s64, s3
	ds_read_b128 v[198:201], v163 offset:16384
	ds_read_b128 v[202:205], v163 offset:17408
	ds_read_b128 v[206:209], v163 offset:18432
	ds_read_b128 v[210:213], v163 offset:19456
	ds_read_b128 v[214:217], v163 offset:20480
	ds_read_b128 v[218:221], v163 offset:21504
	ds_read_b128 v[222:225], v163 offset:22528
	ds_read_b128 v[230:233], v163 offset:23552
	s_mov_b32 m0, s72
	s_nop 0
	global_load_lds_dwordx4 v128, s[62:63]
	v_mov_b32_e32 v128, v159
	s_add_i32 m0, s72, 0x2000
	s_add_u32 s72, s62, 0x80000
	global_load_lds_dwordx4 v128, s[62:63]
	s_addc_u32 s73, s63, 0
	v_mov_b32_e32 v128, v157
	s_add_i32 s83, s65, s3
	s_mov_b32 m0, s83
	s_nop 0
	global_load_lds_dwordx4 v128, s[72:73]
	v_mov_b32_e32 v128, v159
	s_add_i32 m0, s83, 0x2000
	s_nop 0
	global_load_lds_dwordx4 v128, s[72:73]
	v_mov_b32_e32 v128, v156
	s_mov_b32 m0, s22
	s_nop 0
	global_load_lds_dwordx4 v128, s[60:61]
	v_mov_b32_e32 v128, v158
	s_mov_b32 m0, s23
	s_nop 0
	global_load_lds_dwordx4 v128, s[60:61]
	s_waitcnt vmcnt(8)
	s_waitcnt lgkmcnt(0)
	s_barrier
; #define PG8_STAGE(bufoff, gbase, voff) do { _Pragma("unroll") for (int _i = 0; _i < 2; ++_i) \
;         { unsigned _vo = (voff)[_i]; asm volatile("" : "+v"(_vo));     \
;         __builtin_amdgcn_global_load_lds((const unsigned*)((const char*)(gbase) + _vo), (PG8_LAS unsigned*)(lds + (bufoff) + ldsw + _i * 8192), 16, 0, 0); } } while (0)
; #define PG8_LDA(dst, b, h) do { _Pragma("unroll") for (int m = 0; m < 4; ++m) _Pragma("unroll") for (int k = 0; k < 2; ++k) dst[m][k] = *(const PG8_LAS bf16x8*)(lds + PG8_SA(b, h) + aoff + m * 2048 + k * 1024); } while (0)
; #define PG8_LDB(dst, b, h) do { _Pragma("unroll") for (int n = 0; n < 2; ++n) _Pragma("unroll") for (int k = 0; k < 2; ++k) dst[n][k] = *(const PG8_LAS bf16x8*)(lds + PG8_SB(b, h) + boff + n * 2048 + k * 1024); } while (0)
; #define PG8_WAIT_V(n) asm volatile("s_waitcnt vmcnt(" #n ")" ::: "memory")
; #define PG8_WAIT_L(n) asm volatile("s_waitcnt lgkmcnt(" #n ")" ::: "memory")
; #define PG8_BAR __builtin_amdgcn_s_barrier()
; #define PG8_SCHED __builtin_amdgcn_sched_barrier(0)
; template <class Epi, class Sched, bool ALIGN_EPI = false, bool SP2 = false, bool ABLK = false, bool F8 = false>
; __device__ __forceinline__ void gemm_phase(PG8_LAS unsigned char* lds, const Gemm g, const Sched& S, const Epi& E, const int wave_s) {
;     ...
;             PG8_WAIT_V(8); PG8_WAIT_L(0); PG8_BAR; PG8_MMA(1, 0, At, B0); PG8_MMA(1, 1, At, B1); PG8_BAR; PG8_SCHED;
;             PG8_LDB(B0, 1, 0); PG8_LDB(B1, 1, 1); PG8_SCHED; PG8_LDA(At, 1, 0); PG8_STAGE(PG8_SA(0, 1), a2 + hstepA, voffA);
;             PG8_WAIT_V(8); PG8_WAIT_L(0); PG8_BAR; PG8_MMA(0, 0, At, B0); PG8_MMA(0, 1, At, B1); PG8_BAR; PG8_SCHED;
	s_setprio 1
	s_waitcnt lgkmcnt(0)
	v_mfma_f32_16x16x32_bf16 v[60:63], v[166:169], v[198:201], v[60:63]
	v_mfma_f32_16x16x32_bf16 v[52:55], v[174:177], v[198:201], v[52:55]
	v_mfma_f32_16x16x32_bf16 v[44:47], v[166:169], v[206:209], v[44:47]
	v_mfma_f32_16x16x32_bf16 v[36:39], v[174:177], v[206:209], v[36:39]
	v_mfma_f32_16x16x32_bf16 v[28:31], v[166:169], v[214:217], v[28:31]
	v_mfma_f32_16x16x32_bf16 v[20:23], v[174:177], v[214:217], v[20:23]
	v_mfma_f32_16x16x32_bf16 v[12:15], v[166:169], v[222:225], v[12:15]
	v_mfma_f32_16x16x32_bf16 v[4:7], v[174:177], v[222:225], v[4:7]
	v_mfma_f32_16x16x32_bf16 v[60:63], v[170:173], v[202:205], v[60:63]
	v_mfma_f32_16x16x32_bf16 v[52:55], v[178:181], v[202:205], v[52:55]
	v_mfma_f32_16x16x32_bf16 v[44:47], v[170:173], v[210:213], v[44:47]
	v_mfma_f32_16x16x32_bf16 v[36:39], v[178:181], v[210:213], v[36:39]
	v_mfma_f32_16x16x32_bf16 v[28:31], v[170:173], v[218:221], v[28:31]
	v_mfma_f32_16x16x32_bf16 v[20:23], v[178:181], v[218:221], v[20:23]
	v_mfma_f32_16x16x32_bf16 v[12:15], v[170:173], v[230:233], v[12:15]
	v_mfma_f32_16x16x32_bf16 v[4:7], v[178:181], v[230:233], v[4:7]
	s_setprio 0
	s_setprio 1
	v_mfma_f32_16x16x32_bf16 v[56:59], v[182:185], v[198:201], v[56:59]
	v_mfma_f32_16x16x32_bf16 v[48:51], v[190:193], v[198:201], v[48:51]
	v_mfma_f32_16x16x32_bf16 v[40:43], v[182:185], v[206:209], v[40:43]
	v_mfma_f32_16x16x32_bf16 v[32:35], v[190:193], v[206:209], v[32:35]
	v_mfma_f32_16x16x32_bf16 v[24:27], v[182:185], v[214:217], v[24:27]
	v_mfma_f32_16x16x32_bf16 v[16:19], v[190:193], v[214:217], v[16:19]
	v_mfma_f32_16x16x32_bf16 v[8:11], v[182:185], v[222:225], v[8:11]
	v_mfma_f32_16x16x32_bf16 v[0:3], v[190:193], v[222:225], v[0:3]
	v_mfma_f32_16x16x32_bf16 v[56:59], v[186:189], v[202:205], v[56:59]
	v_mfma_f32_16x16x32_bf16 v[48:51], v[194:197], v[202:205], v[48:51]
	v_mfma_f32_16x16x32_bf16 v[40:43], v[186:189], v[210:213], v[40:43]
	v_mfma_f32_16x16x32_bf16 v[32:35], v[194:197], v[210:213], v[32:35]
	v_mfma_f32_16x16x32_bf16 v[24:27], v[186:189], v[218:221], v[24:27]
	v_mfma_f32_16x16x32_bf16 v[16:19], v[194:197], v[218:221], v[16:19]
	v_mfma_f32_16x16x32_bf16 v[8:11], v[186:189], v[230:233], v[8:11]
	v_mfma_f32_16x16x32_bf16 v[0:3], v[194:197], v[230:233], v[0:3]
	s_setprio 0
	s_barrier
	s_add_i32 s83, 0, 0x18000
	v_add_u32_e32 v128, s83, v160
	s_add_i32 s84, 0, 0x1c000
	ds_read_b128 v[166:169], v128
	ds_read_b128 v[170:173], v128 offset:1024
	ds_read_b128 v[174:177], v128 offset:2048
	ds_read_b128 v[178:181], v128 offset:3072
	v_add_u32_e32 v128, s84, v160
	ds_read_b128 v[182:185], v128
	ds_read_b128 v[186:189], v128 offset:1024
	ds_read_b128 v[190:193], v128 offset:2048
	ds_read_b128 v[194:197], v128 offset:3072
	s_add_u32 s72, s60, 0x80000
	v_mov_b32_e32 v128, v156
	s_mov_b32 m0, s46
	ds_read_b128 v[198:201], v163 offset:32768
	ds_read_b128 v[202:205], v163 offset:33792
	ds_read_b128 v[206:209], v163 offset:34816
	ds_read_b128 v[210:213], v163 offset:35840
	ds_read_b128 v[214:217], v163 offset:36864
	ds_read_b128 v[218:221], v163 offset:37888
	ds_read_b128 v[222:225], v163 offset:38912
	ds_read_b128 v[230:233], v163 offset:39936
	s_addc_u32 s73, s61, 0
	s_nop 0
	global_load_lds_dwordx4 v128, s[72:73]
	v_mov_b32_e32 v128, v158
	s_mov_b32 m0, s47
	s_nop 0
	global_load_lds_dwordx4 v128, s[72:73]
	s_waitcnt vmcnt(8)
	s_waitcnt lgkmcnt(0)
	s_barrier
	s_setprio 1
	s_waitcnt lgkmcnt(0)
	v_mfma_f32_16x16x32_bf16 v[124:127], v[166:169], v[198:201], v[124:127]
	v_mfma_f32_16x16x32_bf16 v[116:119], v[174:177], v[198:201], v[116:119]
	v_mfma_f32_16x16x32_bf16 v[108:111], v[166:169], v[206:209], v[108:111]
	v_mfma_f32_16x16x32_bf16 v[100:103], v[174:177], v[206:209], v[100:103]
	v_mfma_f32_16x16x32_bf16 v[92:95], v[166:169], v[214:217], v[92:95]
	v_mfma_f32_16x16x32_bf16 v[84:87], v[174:177], v[214:217], v[84:87]
	v_mfma_f32_16x16x32_bf16 v[76:79], v[166:169], v[222:225], v[76:79]
	v_mfma_f32_16x16x32_bf16 v[68:71], v[174:177], v[222:225], v[68:71]
	v_mfma_f32_16x16x32_bf16 v[124:127], v[170:173], v[202:205], v[124:127]
	v_mfma_f32_16x16x32_bf16 v[116:119], v[178:181], v[202:205], v[116:119]
	v_mfma_f32_16x16x32_bf16 v[108:111], v[170:173], v[210:213], v[108:111]
	v_mfma_f32_16x16x32_bf16 v[100:103], v[178:181], v[210:213], v[100:103]
	v_mfma_f32_16x16x32_bf16 v[92:95], v[170:173], v[218:221], v[92:95]
	v_mfma_f32_16x16x32_bf16 v[84:87], v[178:181], v[218:221], v[84:87]
	v_mfma_f32_16x16x32_bf16 v[76:79], v[170:173], v[230:233], v[76:79]
	v_mfma_f32_16x16x32_bf16 v[68:71], v[178:181], v[230:233], v[68:71]
	s_setprio 0
	s_setprio 1
	v_mfma_f32_16x16x32_bf16 v[120:123], v[182:185], v[198:201], v[120:123]
	v_mfma_f32_16x16x32_bf16 v[112:115], v[190:193], v[198:201], v[112:115]
	v_mfma_f32_16x16x32_bf16 v[104:107], v[182:185], v[206:209], v[104:107]
	v_mfma_f32_16x16x32_bf16 v[96:99], v[190:193], v[206:209], v[96:99]
	v_mfma_f32_16x16x32_bf16 v[88:91], v[182:185], v[214:217], v[88:91]
	v_mfma_f32_16x16x32_bf16 v[80:83], v[190:193], v[214:217], v[80:83]
	v_mfma_f32_16x16x32_bf16 v[72:75], v[182:185], v[222:225], v[72:75]
	v_mfma_f32_16x16x32_bf16 v[64:67], v[190:193], v[222:225], v[64:67]
	v_mfma_f32_16x16x32_bf16 v[120:123], v[186:189], v[202:205], v[120:123]
	v_mfma_f32_16x16x32_bf16 v[112:115], v[194:197], v[202:205], v[112:115]
	v_mfma_f32_16x16x32_bf16 v[104:107], v[186:189], v[210:213], v[104:107]
	v_mfma_f32_16x16x32_bf16 v[96:99], v[194:197], v[210:213], v[96:99]
	v_mfma_f32_16x16x32_bf16 v[88:91], v[186:189], v[218:221], v[88:91]
	v_mfma_f32_16x16x32_bf16 v[80:83], v[194:197], v[218:221], v[80:83]
	v_mfma_f32_16x16x32_bf16 v[72:75], v[186:189], v[230:233], v[72:75]
	v_mfma_f32_16x16x32_bf16 v[64:67], v[194:197], v[230:233], v[64:67]
	s_setprio 0
	s_barrier
; #define PG8_STAGE(bufoff, gbase, voff) do { _Pragma("unroll") for (int _i = 0; _i < 2; ++_i) \
;         { unsigned _vo = (voff)[_i]; asm volatile("" : "+v"(_vo));     \
;         __builtin_amdgcn_global_load_lds((const unsigned*)((const char*)(gbase) + _vo), (PG8_LAS unsigned*)(lds + (bufoff) + ldsw + _i * 8192), 16, 0, 0); } } while (0)
; #define PG8_LDA(dst, b, h) do { _Pragma("unroll") for (int m = 0; m < 4; ++m) _Pragma("unroll") for (int k = 0; k < 2; ++k) dst[m][k] = *(const PG8_LAS bf16x8*)(lds + PG8_SA(b, h) + aoff + m * 2048 + k * 1024); } while (0)
; #define PG8_WAIT_V(n) asm volatile("s_waitcnt vmcnt(" #n ")" ::: "memory")
; #define PG8_WAIT_L(n) asm volatile("s_waitcnt lgkmcnt(" #n ")" ::: "memory")
; #define PG8_BAR __builtin_amdgcn_s_barrier()
; #define PG8_SCHED __builtin_amdgcn_sched_barrier(0)
; template <class Epi, class Sched, bool ALIGN_EPI = false, bool SP2 = false, bool ABLK = false, bool F8 = false>
; __device__ __forceinline__ void gemm_phase(PG8_LAS unsigned char* lds, const Gemm g, const Sched& S, const Epi& E, const int wave_s) {
;     ...
;         for (int t = 0; t < nt; t += 2) {
;             const bool last = (t == nt - 2);
;             const char* a1 = cA + (size_t)(t + 1) * kstepA;
;             const char* a2 = last ? nA : cA + (size_t)(t + 2) * kstepA; const char* b2 = last ? nB : cB + (size_t)(t + 2) * kstep;
;             const char* a3 = a2 + kstepA; const char* b3 = b2 + kstep;
;     ...
;             PG8_LDA(At, 1, 1); PG8_STAGE(PG8_SB(1, 0), b3, voffB); PG8_STAGE(PG8_SB(1, 1), b3 + hstep, voffB); PG8_STAGE(PG8_SA(1, 0), a3, voffA);
;             PG8_WAIT_V(8); PG8_WAIT_L(0); PG8_BAR; PG8_MMA(1, 0, At, B0); PG8_MMA(1, 1, At, B1); PG8_BAR; PG8_SCHED;
	v_mov_b32_e32 v128, v157
	ds_read_b128 v[198:201], v163 offset:49152
	ds_read_b128 v[202:205], v163 offset:50176
	ds_read_b128 v[206:209], v163 offset:51200
	ds_read_b128 v[210:213], v163 offset:52224
	ds_read_b128 v[214:217], v163 offset:53248
	ds_read_b128 v[218:221], v163 offset:54272
	ds_read_b128 v[222:225], v163 offset:55296
	ds_read_b128 v[230:233], v163 offset:56320
	s_add_i32 s72, s83, s3
	v_lshl_add_u64 v[226:227], s[62:63], 0, v[128:129]
	v_lshl_add_u64 v[226:227], v[226:227], 0, s[14:15]
	s_mov_b32 m0, s72
	v_mov_b32_e32 v128, v159
	global_load_lds_dwordx4 v[226:227], off
	s_add_i32 m0, s72, 0x2000
	s_nop 0
	v_lshl_add_u64 v[226:227], s[62:63], 0, v[128:129]
	s_add_u32 s62, s62, 0x80080
	v_lshl_add_u64 v[226:227], v[226:227], 0, s[14:15]
	s_addc_u32 s63, s63, 0
	v_mov_b32_e32 v128, v157
	s_add_i32 s72, s84, s3
	global_load_lds_dwordx4 v[226:227], off
	s_mov_b32 m0, s72
	s_nop 0
	global_load_lds_dwordx4 v128, s[62:63]
	v_mov_b32_e32 v128, v159
	s_add_i32 m0, s72, 0x2000
	s_nop 0
	global_load_lds_dwordx4 v128, s[62:63]
	v_mov_b32_e32 v128, v156
	s_mov_b32 m0, s55
	v_lshl_add_u64 v[226:227], s[60:61], 0, v[128:129]
	v_lshl_add_u64 v[226:227], v[226:227], 0, s[14:15]
	v_mov_b32_e32 v128, v158
	global_load_lds_dwordx4 v[226:227], off
	s_mov_b32 m0, s57
	v_lshl_add_u64 v[226:227], s[60:61], 0, v[128:129]
	v_lshl_add_u64 v[226:227], v[226:227], 0, s[14:15]
	global_load_lds_dwordx4 v[226:227], off
	s_waitcnt vmcnt(8)
	s_waitcnt lgkmcnt(0)
	s_barrier
	s_setprio 1
	s_waitcnt lgkmcnt(0)
	v_mfma_f32_16x16x32_bf16 v[60:63], v[166:169], v[198:201], v[60:63]
	v_mfma_f32_16x16x32_bf16 v[52:55], v[174:177], v[198:201], v[52:55]
	v_mfma_f32_16x16x32_bf16 v[44:47], v[166:169], v[206:209], v[44:47]
	v_mfma_f32_16x16x32_bf16 v[36:39], v[174:177], v[206:209], v[36:39]
	v_mfma_f32_16x16x32_bf16 v[28:31], v[166:169], v[214:217], v[28:31]
	v_mfma_f32_16x16x32_bf16 v[20:23], v[174:177], v[214:217], v[20:23]
	v_mfma_f32_16x16x32_bf16 v[12:15], v[166:169], v[222:225], v[12:15]
	v_mfma_f32_16x16x32_bf16 v[4:7], v[174:177], v[222:225], v[4:7]
	v_mfma_f32_16x16x32_bf16 v[60:63], v[170:173], v[202:205], v[60:63]
	v_mfma_f32_16x16x32_bf16 v[52:55], v[178:181], v[202:205], v[52:55]
	v_mfma_f32_16x16x32_bf16 v[44:47], v[170:173], v[210:213], v[44:47]
	v_mfma_f32_16x16x32_bf16 v[36:39], v[178:181], v[210:213], v[36:39]
	v_mfma_f32_16x16x32_bf16 v[28:31], v[170:173], v[218:221], v[28:31]
	v_mfma_f32_16x16x32_bf16 v[20:23], v[178:181], v[218:221], v[20:23]
	v_mfma_f32_16x16x32_bf16 v[12:15], v[170:173], v[230:233], v[12:15]
	v_mfma_f32_16x16x32_bf16 v[4:7], v[178:181], v[230:233], v[4:7]
	s_setprio 0
	s_setprio 1
	v_mfma_f32_16x16x32_bf16 v[56:59], v[182:185], v[198:201], v[56:59]
	v_mfma_f32_16x16x32_bf16 v[48:51], v[190:193], v[198:201], v[48:51]
	v_mfma_f32_16x16x32_bf16 v[40:43], v[182:185], v[206:209], v[40:43]
	v_mfma_f32_16x16x32_bf16 v[32:35], v[190:193], v[206:209], v[32:35]
	v_mfma_f32_16x16x32_bf16 v[24:27], v[182:185], v[214:217], v[24:27]
	v_mfma_f32_16x16x32_bf16 v[16:19], v[190:193], v[214:217], v[16:19]
	v_mfma_f32_16x16x32_bf16 v[8:11], v[182:185], v[222:225], v[8:11]
	v_mfma_f32_16x16x32_bf16 v[0:3], v[190:193], v[222:225], v[0:3]
	v_mfma_f32_16x16x32_bf16 v[56:59], v[186:189], v[202:205], v[56:59]
	v_mfma_f32_16x16x32_bf16 v[48:51], v[194:197], v[202:205], v[48:51]
	v_mfma_f32_16x16x32_bf16 v[40:43], v[186:189], v[210:213], v[40:43]
	v_mfma_f32_16x16x32_bf16 v[32:35], v[194:197], v[210:213], v[32:35]
	v_mfma_f32_16x16x32_bf16 v[24:27], v[186:189], v[218:221], v[24:27]
	v_mfma_f32_16x16x32_bf16 v[16:19], v[194:197], v[218:221], v[16:19]
	v_mfma_f32_16x16x32_bf16 v[8:11], v[186:189], v[230:233], v[8:11]
	v_mfma_f32_16x16x32_bf16 v[0:3], v[194:197], v[230:233], v[0:3]
	s_setprio 0
	s_barrier
	s_add_i32 s81, s81, 2
	s_add_u32 s58, s58, 0x100
	s_addc_u32 s59, s59, 0
	s_add_u32 s79, s79, 0x100
	s_addc_u32 s80, s80, 0
	s_cmp_gt_u32 s81, 29
	s_cbranch_scc1 .LBB0_226

; #define PG8_STAGE(bufoff, gbase, voff) do { _Pragma("unroll") for (int _i = 0; _i < 2; ++_i) \
;         { unsigned _vo = (voff)[_i]; asm volatile("" : "+v"(_vo));     \
;         __builtin_amdgcn_global_load_lds((const unsigned*)((const char*)(gbase) + _vo), (PG8_LAS unsigned*)(lds + (bufoff) + ldsw + _i * 8192), 16, 0, 0); } } while (0)
; #define PG8_LDA(dst, b, h) do { _Pragma("unroll") for (int m = 0; m < 4; ++m) _Pragma("unroll") for (int k = 0; k < 2; ++k) dst[m][k] = *(const PG8_LAS bf16x8*)(lds + PG8_SA(b, h) + aoff + m * 2048 + k * 1024); } while (0)
; #define PG8_LDB(dst, b, h) do { _Pragma("unroll") for (int n = 0; n < 2; ++n) _Pragma("unroll") for (int k = 0; k < 2; ++k) dst[n][k] = *(const PG8_LAS bf16x8*)(lds + PG8_SB(b, h) + boff + n * 2048 + k * 1024); } while (0)
; #define PG8_WAIT_V(n) asm volatile("s_waitcnt vmcnt(" #n ")" ::: "memory")
; #define PG8_WAIT_L(n) asm volatile("s_waitcnt lgkmcnt(" #n ")" ::: "memory")
; #define PG8_BAR __builtin_amdgcn_s_barrier()
; #define PG8_SCHED __builtin_amdgcn_sched_barrier(0)
; template <class Epi, class Sched, bool ALIGN_EPI = false, bool SP2 = false, bool ABLK = false, bool F8 = false>
; __device__ __forceinline__ void gemm_phase(PG8_LAS unsigned char* lds, const Gemm g, const Sched& S, const Epi& E, const int wave_s) {
;     ...
;             PG8_LDB(B0, 0, 0); PG8_LDB(B1, 0, 1); PG8_SCHED; PG8_LDA(At, 0, 0); PG8_STAGE(PG8_SA(1, 1), a1 + hstepA, voffA);
;             PG8_WAIT_V(8); PG8_WAIT_L(0); PG8_BAR; PG8_MMA(0, 0, At, B0); PG8_MMA(0, 1, At, B1); PG8_BAR; PG8_SCHED;
;             PG8_LDA(At, 0, 1); PG8_STAGE(PG8_SB(0, 0), b2, voffB); PG8_STAGE(PG8_SB(0, 1), b2 + hstep, voffB); PG8_STAGE(PG8_SA(0, 0), a2, voffA);
;             PG8_WAIT_V(8); PG8_WAIT_L(0); PG8_BAR; PG8_MMA(1, 0, At, B0); PG8_MMA(1, 1, At, B1); PG8_BAR; PG8_SCHED;
.LBB0_304:
	ds_read_b128 v[104:107], v230
	ds_read_b128 v[116:119], v230 offset:1024
	ds_read_b128 v[128:131], v230 offset:2048
	ds_read_b128 v[140:143], v230 offset:3072
	ds_read_b128 v[144:147], v231
	ds_read_b128 v[148:151], v231 offset:1024
	ds_read_b128 v[152:155], v231 offset:2048
	ds_read_b128 v[156:159], v231 offset:3072
	s_add_u32 s52, s50, 0x4000
	s_addc_u32 s53, s51, 0
	s_cmpk_eq_i32 s77, 0x54
	s_cselect_b32 s56, s12, s52
	s_cselect_b32 s57, s13, s53
	s_cselect_b32 s54, s48, s67
	s_cselect_b32 s55, s49, s76
	s_add_u32 s52, s56, 0x8000
	s_addc_u32 s53, s57, 0
	v_mov_b32_e32 v184, v222
	ds_read_b128 v[160:163], v232
	ds_read_b128 v[164:167], v232 offset:1024
	ds_read_b128 v[168:171], v232 offset:2048
	ds_read_b128 v[172:175], v232 offset:3072
	ds_read_b128 v[176:179], v232 offset:4096
	ds_read_b128 v[180:183], v232 offset:5120
	ds_read_b128 v[190:193], v232 offset:6144
	ds_read_b128 v[194:197], v232 offset:7168
	s_add_i32 m0, s22, 0xc000
	s_nop 0
	global_load_lds_dwordx4 v184, s[50:51]
	v_mov_b32_e32 v184, v224
	s_add_i32 m0, s22, 0xe000
	s_nop 0
	global_load_lds_dwordx4 v184, s[50:51]
	s_waitcnt vmcnt(8)
	s_waitcnt lgkmcnt(0)
	s_barrier
	s_setprio 1
	s_waitcnt lgkmcnt(0)
	v_mfma_f32_16x16x32_bf16 v[136:139], v[104:107], v[160:163], v[136:139]
	v_mfma_f32_16x16x32_bf16 v[132:135], v[128:131], v[160:163], v[132:135]
	v_mfma_f32_16x16x32_bf16 v[112:115], v[104:107], v[168:171], v[112:115]
	v_mfma_f32_16x16x32_bf16 v[108:111], v[128:131], v[168:171], v[108:111]
	v_mfma_f32_16x16x32_bf16 v[92:95], v[104:107], v[176:179], v[92:95]
	v_mfma_f32_16x16x32_bf16 v[88:91], v[128:131], v[176:179], v[88:91]
	v_mfma_f32_16x16x32_bf16 v[76:79], v[104:107], v[190:193], v[76:79]
	v_mfma_f32_16x16x32_bf16 v[72:75], v[128:131], v[190:193], v[72:75]
	v_mfma_f32_16x16x32_bf16 v[136:139], v[116:119], v[164:167], v[136:139]
	v_mfma_f32_16x16x32_bf16 v[132:135], v[140:143], v[164:167], v[132:135]
	v_mfma_f32_16x16x32_bf16 v[112:115], v[116:119], v[172:175], v[112:115]
	v_mfma_f32_16x16x32_bf16 v[108:111], v[140:143], v[172:175], v[108:111]
	v_mfma_f32_16x16x32_bf16 v[92:95], v[116:119], v[180:183], v[92:95]
	v_mfma_f32_16x16x32_bf16 v[88:91], v[140:143], v[180:183], v[88:91]
	v_mfma_f32_16x16x32_bf16 v[76:79], v[116:119], v[194:197], v[76:79]
	v_mfma_f32_16x16x32_bf16 v[72:75], v[140:143], v[194:197], v[72:75]
	s_setprio 0
	s_setprio 1
	v_mfma_f32_16x16x32_bf16 v[124:127], v[144:147], v[160:163], v[124:127]
	v_mfma_f32_16x16x32_bf16 v[120:123], v[152:155], v[160:163], v[120:123]
	v_mfma_f32_16x16x32_bf16 v[100:103], v[144:147], v[168:171], v[100:103]
	v_mfma_f32_16x16x32_bf16 v[96:99], v[152:155], v[168:171], v[96:99]
	v_mfma_f32_16x16x32_bf16 v[84:87], v[144:147], v[176:179], v[84:87]
	v_mfma_f32_16x16x32_bf16 v[80:83], v[152:155], v[176:179], v[80:83]
	v_mfma_f32_16x16x32_bf16 v[68:71], v[144:147], v[190:193], v[68:71]
	v_mfma_f32_16x16x32_bf16 v[64:67], v[152:155], v[190:193], v[64:67]
	v_mfma_f32_16x16x32_bf16 v[124:127], v[148:151], v[164:167], v[124:127]
	v_mfma_f32_16x16x32_bf16 v[120:123], v[156:159], v[164:167], v[120:123]
	v_mfma_f32_16x16x32_bf16 v[100:103], v[148:151], v[172:175], v[100:103]
	v_mfma_f32_16x16x32_bf16 v[96:99], v[156:159], v[172:175], v[96:99]
	v_mfma_f32_16x16x32_bf16 v[84:87], v[148:151], v[180:183], v[84:87]
	v_mfma_f32_16x16x32_bf16 v[80:83], v[156:159], v[180:183], v[80:83]
	v_mfma_f32_16x16x32_bf16 v[68:71], v[148:151], v[194:197], v[68:71]
	v_mfma_f32_16x16x32_bf16 v[64:67], v[156:159], v[194:197], v[64:67]
	s_setprio 0
	s_barrier
	v_mov_b32_e32 v184, v223
	s_add_i32 s72, s61, s3
	ds_read_b128 v[160:163], v232 offset:16384
	ds_read_b128 v[164:167], v232 offset:17408
	ds_read_b128 v[168:171], v232 offset:18432
	ds_read_b128 v[172:175], v232 offset:19456
	ds_read_b128 v[176:179], v232 offset:20480
	ds_read_b128 v[180:183], v232 offset:21504
	ds_read_b128 v[190:193], v232 offset:22528
	ds_read_b128 v[194:197], v232 offset:23552
	s_mov_b32 m0, s72
	s_nop 0
	global_load_lds_dwordx4 v184, s[54:55]
	v_mov_b32_e32 v184, v225
	s_add_i32 m0, s72, 0x2000
	s_add_u32 s72, s54, 0x160000
	global_load_lds_dwordx4 v184, s[54:55]
	s_addc_u32 s73, s55, 0
	v_mov_b32_e32 v184, v223
	s_add_i32 s78, s62, s3
	s_mov_b32 m0, s78
	s_nop 0
	global_load_lds_dwordx4 v184, s[72:73]
	v_mov_b32_e32 v184, v225
	s_add_i32 m0, s78, 0x2000
	s_nop 0
	global_load_lds_dwordx4 v184, s[72:73]
	v_mov_b32_e32 v184, v222
	s_mov_b32 m0, s22
	s_nop 0
	global_load_lds_dwordx4 v184, s[56:57]
	v_mov_b32_e32 v184, v224
	s_mov_b32 m0, s23
	s_nop 0
	global_load_lds_dwordx4 v184, s[56:57]
	s_waitcnt vmcnt(8)
	s_waitcnt lgkmcnt(0)
	s_barrier
; #define PG8_STAGE(bufoff, gbase, voff) do { _Pragma("unroll") for (int _i = 0; _i < 2; ++_i) \
;         { unsigned _vo = (voff)[_i]; asm volatile("" : "+v"(_vo));     \
;         __builtin_amdgcn_global_load_lds((const unsigned*)((const char*)(gbase) + _vo), (PG8_LAS unsigned*)(lds + (bufoff) + ldsw + _i * 8192), 16, 0, 0); } } while (0)
; #define PG8_LDA(dst, b, h) do { _Pragma("unroll") for (int m = 0; m < 4; ++m) _Pragma("unroll") for (int k = 0; k < 2; ++k) dst[m][k] = *(const PG8_LAS bf16x8*)(lds + PG8_SA(b, h) + aoff + m * 2048 + k * 1024); } while (0)
; #define PG8_LDB(dst, b, h) do { _Pragma("unroll") for (int n = 0; n < 2; ++n) _Pragma("unroll") for (int k = 0; k < 2; ++k) dst[n][k] = *(const PG8_LAS bf16x8*)(lds + PG8_SB(b, h) + boff + n * 2048 + k * 1024); } while (0)
; #define PG8_WAIT_V(n) asm volatile("s_waitcnt vmcnt(" #n ")" ::: "memory")
; #define PG8_WAIT_L(n) asm volatile("s_waitcnt lgkmcnt(" #n ")" ::: "memory")
; #define PG8_BAR __builtin_amdgcn_s_barrier()
; #define PG8_SCHED __builtin_amdgcn_sched_barrier(0)
; template <class Epi, class Sched, bool ALIGN_EPI = false, bool SP2 = false, bool ABLK = false, bool F8 = false>
; __device__ __forceinline__ void gemm_phase(PG8_LAS unsigned char* lds, const Gemm g, const Sched& S, const Epi& E, const int wave_s) {
;     ...
;             PG8_WAIT_V(8); PG8_WAIT_L(0); PG8_BAR; PG8_MMA(1, 0, At, B0); PG8_MMA(1, 1, At, B1); PG8_BAR; PG8_SCHED;
;             PG8_LDB(B0, 1, 0); PG8_LDB(B1, 1, 1); PG8_SCHED; PG8_LDA(At, 1, 0); PG8_STAGE(PG8_SA(0, 1), a2 + hstepA, voffA);
;             PG8_WAIT_V(8); PG8_WAIT_L(0); PG8_BAR; PG8_MMA(0, 0, At, B0); PG8_MMA(0, 1, At, B1); PG8_BAR; PG8_SCHED;
	s_setprio 1
	s_waitcnt lgkmcnt(0)
	v_mfma_f32_16x16x32_bf16 v[60:63], v[104:107], v[160:163], v[60:63]
	v_mfma_f32_16x16x32_bf16 v[56:59], v[128:131], v[160:163], v[56:59]
	v_mfma_f32_16x16x32_bf16 v[44:47], v[104:107], v[168:171], v[44:47]
	v_mfma_f32_16x16x32_bf16 v[40:43], v[128:131], v[168:171], v[40:43]
	v_mfma_f32_16x16x32_bf16 v[28:31], v[104:107], v[176:179], v[28:31]
	v_mfma_f32_16x16x32_bf16 v[24:27], v[128:131], v[176:179], v[24:27]
	v_mfma_f32_16x16x32_bf16 v[12:15], v[104:107], v[190:193], v[12:15]
	v_mfma_f32_16x16x32_bf16 v[8:11], v[128:131], v[190:193], v[8:11]
	v_mfma_f32_16x16x32_bf16 v[60:63], v[116:119], v[164:167], v[60:63]
	v_mfma_f32_16x16x32_bf16 v[56:59], v[140:143], v[164:167], v[56:59]
	v_mfma_f32_16x16x32_bf16 v[44:47], v[116:119], v[172:175], v[44:47]
	v_mfma_f32_16x16x32_bf16 v[40:43], v[140:143], v[172:175], v[40:43]
	v_mfma_f32_16x16x32_bf16 v[28:31], v[116:119], v[180:183], v[28:31]
	v_mfma_f32_16x16x32_bf16 v[24:27], v[140:143], v[180:183], v[24:27]
	v_mfma_f32_16x16x32_bf16 v[12:15], v[116:119], v[194:197], v[12:15]
	v_mfma_f32_16x16x32_bf16 v[8:11], v[140:143], v[194:197], v[8:11]
	s_setprio 0
	s_setprio 1
	v_mfma_f32_16x16x32_bf16 v[52:55], v[144:147], v[160:163], v[52:55]
	v_mfma_f32_16x16x32_bf16 v[48:51], v[152:155], v[160:163], v[48:51]
	v_mfma_f32_16x16x32_bf16 v[36:39], v[144:147], v[168:171], v[36:39]
	v_mfma_f32_16x16x32_bf16 v[32:35], v[152:155], v[168:171], v[32:35]
	v_mfma_f32_16x16x32_bf16 v[20:23], v[144:147], v[176:179], v[20:23]
	v_mfma_f32_16x16x32_bf16 v[16:19], v[152:155], v[176:179], v[16:19]
	v_mfma_f32_16x16x32_bf16 v[4:7], v[144:147], v[190:193], v[4:7]
	v_mfma_f32_16x16x32_bf16 v[0:3], v[152:155], v[190:193], v[0:3]
	v_mfma_f32_16x16x32_bf16 v[52:55], v[148:151], v[164:167], v[52:55]
	v_mfma_f32_16x16x32_bf16 v[48:51], v[156:159], v[164:167], v[48:51]
	v_mfma_f32_16x16x32_bf16 v[36:39], v[148:151], v[172:175], v[36:39]
	v_mfma_f32_16x16x32_bf16 v[32:35], v[156:159], v[172:175], v[32:35]
	v_mfma_f32_16x16x32_bf16 v[20:23], v[148:151], v[180:183], v[20:23]
	v_mfma_f32_16x16x32_bf16 v[16:19], v[156:159], v[180:183], v[16:19]
	v_mfma_f32_16x16x32_bf16 v[4:7], v[148:151], v[194:197], v[4:7]
	v_mfma_f32_16x16x32_bf16 v[0:3], v[156:159], v[194:197], v[0:3]
	s_setprio 0
	s_barrier
	s_add_i32 s72, 0, 0x18000
	s_add_i32 s73, 0, 0x1c000
	v_add_u32_e32 v140, s72, v227
	v_add_u32_e32 v156, s73, v227
	ds_read_b128 v[104:107], v140
	ds_read_b128 v[116:119], v140 offset:1024
	ds_read_b128 v[128:131], v140 offset:2048
	ds_read_b128 v[140:143], v140 offset:3072
	ds_read_b128 v[144:147], v156
	ds_read_b128 v[148:151], v156 offset:1024
	ds_read_b128 v[152:155], v156 offset:2048
	ds_read_b128 v[156:159], v156 offset:3072
	s_add_u32 s56, s56, 0x4000
	v_mov_b32_e32 v184, v222
	s_mov_b32 m0, s46
	ds_read_b128 v[160:163], v232 offset:32768
	ds_read_b128 v[164:167], v232 offset:33792
	ds_read_b128 v[168:171], v232 offset:34816
	ds_read_b128 v[172:175], v232 offset:35840
	ds_read_b128 v[176:179], v232 offset:36864
	ds_read_b128 v[180:183], v232 offset:37888
	ds_read_b128 v[190:193], v232 offset:38912
	ds_read_b128 v[194:197], v232 offset:39936
	s_addc_u32 s57, s57, 0
	s_nop 0
	global_load_lds_dwordx4 v184, s[56:57]
	v_mov_b32_e32 v184, v224
	s_mov_b32 m0, s47
	s_nop 0
	global_load_lds_dwordx4 v184, s[56:57]
	s_waitcnt vmcnt(8)
	s_waitcnt lgkmcnt(0)
	s_barrier
	s_setprio 1
	s_waitcnt lgkmcnt(0)
	v_mfma_f32_16x16x32_bf16 v[136:139], v[104:107], v[160:163], v[136:139]
	v_mfma_f32_16x16x32_bf16 v[132:135], v[128:131], v[160:163], v[132:135]
	v_mfma_f32_16x16x32_bf16 v[112:115], v[104:107], v[168:171], v[112:115]
	v_mfma_f32_16x16x32_bf16 v[108:111], v[128:131], v[168:171], v[108:111]
	v_mfma_f32_16x16x32_bf16 v[92:95], v[104:107], v[176:179], v[92:95]
	v_mfma_f32_16x16x32_bf16 v[88:91], v[128:131], v[176:179], v[88:91]
	v_mfma_f32_16x16x32_bf16 v[76:79], v[104:107], v[190:193], v[76:79]
	v_mfma_f32_16x16x32_bf16 v[72:75], v[128:131], v[190:193], v[72:75]
	v_mfma_f32_16x16x32_bf16 v[136:139], v[116:119], v[164:167], v[136:139]
	v_mfma_f32_16x16x32_bf16 v[132:135], v[140:143], v[164:167], v[132:135]
	v_mfma_f32_16x16x32_bf16 v[112:115], v[116:119], v[172:175], v[112:115]
	v_mfma_f32_16x16x32_bf16 v[108:111], v[140:143], v[172:175], v[108:111]
	v_mfma_f32_16x16x32_bf16 v[92:95], v[116:119], v[180:183], v[92:95]
	v_mfma_f32_16x16x32_bf16 v[88:91], v[140:143], v[180:183], v[88:91]
	v_mfma_f32_16x16x32_bf16 v[76:79], v[116:119], v[194:197], v[76:79]
	v_mfma_f32_16x16x32_bf16 v[72:75], v[140:143], v[194:197], v[72:75]
	s_setprio 0
	s_setprio 1
	v_mfma_f32_16x16x32_bf16 v[124:127], v[144:147], v[160:163], v[124:127]
	v_mfma_f32_16x16x32_bf16 v[120:123], v[152:155], v[160:163], v[120:123]
	v_mfma_f32_16x16x32_bf16 v[100:103], v[144:147], v[168:171], v[100:103]
	v_mfma_f32_16x16x32_bf16 v[96:99], v[152:155], v[168:171], v[96:99]
	v_mfma_f32_16x16x32_bf16 v[84:87], v[144:147], v[176:179], v[84:87]
	v_mfma_f32_16x16x32_bf16 v[80:83], v[152:155], v[176:179], v[80:83]
	v_mfma_f32_16x16x32_bf16 v[68:71], v[144:147], v[190:193], v[68:71]
	v_mfma_f32_16x16x32_bf16 v[64:67], v[152:155], v[190:193], v[64:67]
	v_mfma_f32_16x16x32_bf16 v[124:127], v[148:151], v[164:167], v[124:127]
	v_mfma_f32_16x16x32_bf16 v[120:123], v[156:159], v[164:167], v[120:123]
	v_mfma_f32_16x16x32_bf16 v[100:103], v[148:151], v[172:175], v[100:103]
	v_mfma_f32_16x16x32_bf16 v[96:99], v[156:159], v[172:175], v[96:99]
	v_mfma_f32_16x16x32_bf16 v[84:87], v[148:151], v[180:183], v[84:87]
	v_mfma_f32_16x16x32_bf16 v[80:83], v[156:159], v[180:183], v[80:83]
	v_mfma_f32_16x16x32_bf16 v[68:71], v[148:151], v[194:197], v[68:71]
	v_mfma_f32_16x16x32_bf16 v[64:67], v[156:159], v[194:197], v[64:67]
	s_setprio 0
	s_barrier
; #define PG8_STAGE(bufoff, gbase, voff) do { _Pragma("unroll") for (int _i = 0; _i < 2; ++_i) \
;         { unsigned _vo = (voff)[_i]; asm volatile("" : "+v"(_vo));     \
;         __builtin_amdgcn_global_load_lds((const unsigned*)((const char*)(gbase) + _vo), (PG8_LAS unsigned*)(lds + (bufoff) + ldsw + _i * 8192), 16, 0, 0); } } while (0)
; #define PG8_LDA(dst, b, h) do { _Pragma("unroll") for (int m = 0; m < 4; ++m) _Pragma("unroll") for (int k = 0; k < 2; ++k) dst[m][k] = *(const PG8_LAS bf16x8*)(lds + PG8_SA(b, h) + aoff + m * 2048 + k * 1024); } while (0)
; #define PG8_WAIT_V(n) asm volatile("s_waitcnt vmcnt(" #n ")" ::: "memory")
; #define PG8_WAIT_L(n) asm volatile("s_waitcnt lgkmcnt(" #n ")" ::: "memory")
; #define PG8_BAR __builtin_amdgcn_s_barrier()
; #define PG8_SCHED __builtin_amdgcn_sched_barrier(0)
; template <class Epi, class Sched, bool ALIGN_EPI = false, bool SP2 = false, bool ABLK = false, bool F8 = false>
; __device__ __forceinline__ void gemm_phase(PG8_LAS unsigned char* lds, const Gemm g, const Sched& S, const Epi& E, const int wave_s) {
;     ...
;         for (int t = 0; t < nt; t += 2) {
;             const bool last = (t == nt - 2);
;             const char* a1 = cA + (size_t)(t + 1) * kstepA;
;             const char* a2 = last ? nA : cA + (size_t)(t + 2) * kstepA; const char* b2 = last ? nB : cB + (size_t)(t + 2) * kstep;
;             const char* a3 = a2 + kstepA; const char* b3 = b2 + kstep;
;     ...
;             PG8_LDA(At, 1, 1); PG8_STAGE(PG8_SB(1, 0), b3, voffB); PG8_STAGE(PG8_SB(1, 1), b3 + hstep, voffB); PG8_STAGE(PG8_SA(1, 0), a3, voffA);
;             PG8_WAIT_V(8); PG8_WAIT_L(0); PG8_BAR; PG8_MMA(1, 0, At, B0); PG8_MMA(1, 1, At, B1); PG8_BAR; PG8_SCHED;
;     ...
;         if constexpr (ALIGN_EPI) { if (wr == 0) PG8_BAR; }
	v_mov_b32_e32 v184, v223
	ds_read_b128 v[160:163], v232 offset:49152
	ds_read_b128 v[164:167], v232 offset:50176
	ds_read_b128 v[168:171], v232 offset:51200
	ds_read_b128 v[172:175], v232 offset:52224
	ds_read_b128 v[176:179], v232 offset:53248
	ds_read_b128 v[180:183], v232 offset:54272
	ds_read_b128 v[190:193], v232 offset:55296
	ds_read_b128 v[194:197], v232 offset:56320
	s_add_i32 s56, s72, s3
	v_lshl_add_u64 v[198:199], s[54:55], 0, v[184:185]
	v_lshl_add_u64 v[198:199], v[198:199], 0, s[14:15]
	s_mov_b32 m0, s56
	v_mov_b32_e32 v184, v225
	global_load_lds_dwordx4 v[198:199], off
	s_add_i32 m0, s56, 0x2000
	s_nop 0
	v_lshl_add_u64 v[198:199], s[54:55], 0, v[184:185]
	s_add_u32 s54, s54, 0x160080
	v_lshl_add_u64 v[198:199], v[198:199], 0, s[14:15]
	s_addc_u32 s55, s55, 0
	v_mov_b32_e32 v184, v223
	s_add_i32 s56, s73, s3
	global_load_lds_dwordx4 v[198:199], off
	s_mov_b32 m0, s56
	s_nop 0
	global_load_lds_dwordx4 v184, s[54:55]
	v_mov_b32_e32 v184, v225
	s_add_i32 m0, s56, 0x2000
	s_nop 0
	global_load_lds_dwordx4 v184, s[54:55]
	v_mov_b32_e32 v184, v222
	s_mov_b32 m0, s59
	s_nop 0
	global_load_lds_dwordx4 v184, s[52:53]
	v_mov_b32_e32 v184, v224
	s_mov_b32 m0, s60
	s_nop 0
	global_load_lds_dwordx4 v184, s[52:53]
	s_waitcnt vmcnt(8)
	s_waitcnt lgkmcnt(0)
	s_barrier
	s_setprio 1
	s_waitcnt lgkmcnt(0)
	v_mfma_f32_16x16x32_bf16 v[60:63], v[104:107], v[160:163], v[60:63]
	v_mfma_f32_16x16x32_bf16 v[56:59], v[128:131], v[160:163], v[56:59]
	v_mfma_f32_16x16x32_bf16 v[44:47], v[104:107], v[168:171], v[44:47]
	v_mfma_f32_16x16x32_bf16 v[40:43], v[128:131], v[168:171], v[40:43]
	v_mfma_f32_16x16x32_bf16 v[28:31], v[104:107], v[176:179], v[28:31]
	v_mfma_f32_16x16x32_bf16 v[24:27], v[128:131], v[176:179], v[24:27]
	v_mfma_f32_16x16x32_bf16 v[12:15], v[104:107], v[190:193], v[12:15]
	v_mfma_f32_16x16x32_bf16 v[8:11], v[128:131], v[190:193], v[8:11]
	v_mfma_f32_16x16x32_bf16 v[60:63], v[116:119], v[164:167], v[60:63]
	v_mfma_f32_16x16x32_bf16 v[56:59], v[140:143], v[164:167], v[56:59]
	v_mfma_f32_16x16x32_bf16 v[44:47], v[116:119], v[172:175], v[44:47]
	v_mfma_f32_16x16x32_bf16 v[40:43], v[140:143], v[172:175], v[40:43]
	v_mfma_f32_16x16x32_bf16 v[28:31], v[116:119], v[180:183], v[28:31]
	v_mfma_f32_16x16x32_bf16 v[24:27], v[140:143], v[180:183], v[24:27]
	v_mfma_f32_16x16x32_bf16 v[12:15], v[116:119], v[194:197], v[12:15]
	v_mfma_f32_16x16x32_bf16 v[8:11], v[140:143], v[194:197], v[8:11]
	s_setprio 0
	s_setprio 1
	v_mfma_f32_16x16x32_bf16 v[52:55], v[144:147], v[160:163], v[52:55]
	v_mfma_f32_16x16x32_bf16 v[48:51], v[152:155], v[160:163], v[48:51]
	v_mfma_f32_16x16x32_bf16 v[36:39], v[144:147], v[168:171], v[36:39]
	v_mfma_f32_16x16x32_bf16 v[32:35], v[152:155], v[168:171], v[32:35]
	v_mfma_f32_16x16x32_bf16 v[20:23], v[144:147], v[176:179], v[20:23]
	v_mfma_f32_16x16x32_bf16 v[16:19], v[152:155], v[176:179], v[16:19]
	v_mfma_f32_16x16x32_bf16 v[4:7], v[144:147], v[190:193], v[4:7]
	v_mfma_f32_16x16x32_bf16 v[0:3], v[152:155], v[190:193], v[0:3]
	v_mfma_f32_16x16x32_bf16 v[52:55], v[148:151], v[164:167], v[52:55]
	v_mfma_f32_16x16x32_bf16 v[48:51], v[156:159], v[164:167], v[48:51]
	v_mfma_f32_16x16x32_bf16 v[36:39], v[148:151], v[172:175], v[36:39]
	v_mfma_f32_16x16x32_bf16 v[32:35], v[156:159], v[172:175], v[32:35]
	v_mfma_f32_16x16x32_bf16 v[20:23], v[148:151], v[180:183], v[20:23]
	v_mfma_f32_16x16x32_bf16 v[16:19], v[156:159], v[180:183], v[16:19]
	v_mfma_f32_16x16x32_bf16 v[4:7], v[148:151], v[194:197], v[4:7]
	v_mfma_f32_16x16x32_bf16 v[0:3], v[156:159], v[194:197], v[0:3]
	s_setprio 0
	s_barrier
	s_add_i32 s77, s77, 2
	s_add_u32 s67, s67, 0x100
	s_addc_u32 s76, s76, 0
	s_add_u32 s50, s50, 0x10000
	s_addc_u32 s51, s51, 0
	s_cmpk_gt_u32 s77, 0x55
	s_cbranch_scc0 .LBB0_304
	s_and_b64 vcc, exec, s[36:37]
	s_cbranch_vccz .LBB0_307
	s_barrier

; #define PG8_STAGE(bufoff, gbase, voff) do { _Pragma("unroll") for (int _i = 0; _i < 2; ++_i) \
;         { unsigned _vo = (voff)[_i]; asm volatile("" : "+v"(_vo));     \
;         __builtin_amdgcn_global_load_lds((const unsigned*)((const char*)(gbase) + _vo), (PG8_LAS unsigned*)(lds + (bufoff) + ldsw + _i * 8192), 16, 0, 0); } } while (0)
; #define PG8_LDA(dst, b, h) do { _Pragma("unroll") for (int m = 0; m < 4; ++m) _Pragma("unroll") for (int k = 0; k < 2; ++k) dst[m][k] = *(const PG8_LAS bf16x8*)(lds + PG8_SA(b, h) + aoff + m * 2048 + k * 1024); } while (0)
; #define PG8_LDB(dst, b, h) do { _Pragma("unroll") for (int n = 0; n < 2; ++n) _Pragma("unroll") for (int k = 0; k < 2; ++k) dst[n][k] = *(const PG8_LAS bf16x8*)(lds + PG8_SB(b, h) + boff + n * 2048 + k * 1024); } while (0)
; #define PG8_WAIT_V(n) asm volatile("s_waitcnt vmcnt(" #n ")" ::: "memory")
; #define PG8_WAIT_L(n) asm volatile("s_waitcnt lgkmcnt(" #n ")" ::: "memory")
; #define PG8_BAR __builtin_amdgcn_s_barrier()
; #define PG8_SCHED __builtin_amdgcn_sched_barrier(0)
; template <class Epi, class Sched, bool ALIGN_EPI = false, bool SP2 = false, bool ABLK = false, bool F8 = false>
; __device__ __forceinline__ void gemm_phase(PG8_LAS unsigned char* lds, const Gemm g, const Sched& S, const Epi& E, const int wave_s) {
;     ...
;             PG8_LDB(B0, 0, 0); PG8_LDB(B1, 0, 1); PG8_SCHED; PG8_LDA(At, 0, 0); PG8_STAGE(PG8_SA(1, 1), a1 + hstepA, voffA);
;             PG8_WAIT_V(8); PG8_WAIT_L(0); PG8_BAR; PG8_MMA(0, 0, At, B0); PG8_MMA(0, 1, At, B1); PG8_BAR; PG8_SCHED;
;             PG8_LDA(At, 0, 1); PG8_STAGE(PG8_SB(0, 0), b2, voffB); PG8_STAGE(PG8_SB(0, 1), b2 + hstep, voffB); PG8_STAGE(PG8_SA(0, 0), a2, voffA);
;             PG8_WAIT_V(8); PG8_WAIT_L(0); PG8_BAR; PG8_MMA(1, 0, At, B0); PG8_MMA(1, 1, At, B1); PG8_BAR; PG8_SCHED;
.LBB0_395:
	ds_read_b128 v[140:143], v176
	ds_read_b128 v[144:147], v176 offset:1024
	ds_read_b128 v[148:151], v176 offset:2048
	ds_read_b128 v[152:155], v176 offset:3072
	ds_read_b128 v[188:191], v177
	ds_read_b128 v[192:195], v177 offset:1024
	ds_read_b128 v[196:199], v177 offset:2048
	ds_read_b128 v[200:203], v177 offset:3072
	s_add_u32 s64, s62, 0xfff80080
	s_addc_u32 s65, s63, -1
	s_cmp_eq_u32 vcc_lo, 28
	s_cselect_b32 s65, s20, s65
	s_cselect_b32 s64, s23, s64
	s_cselect_b32 s67, s51, s61
	s_cselect_b32 s66, s53, s59
	v_mov_b32_e32 v128, v158
	ds_read_b128 v[204:207], v178
	ds_read_b128 v[208:211], v178 offset:1024
	ds_read_b128 v[212:215], v178 offset:2048
	ds_read_b128 v[216:219], v178 offset:3072
	ds_read_b128 v[220:223], v178 offset:4096
	ds_read_b128 v[224:227], v178 offset:5120
	ds_read_b128 v[230:233], v178 offset:6144
	ds_read_b128 v[234:237], v178 offset:7168
	s_add_i32 m0, s78, 0xc000
	s_nop 0
	global_load_lds_dwordx4 v128, s[62:63]
	v_mov_b32_e32 v128, v160
	s_add_i32 m0, s78, 0xe000
	s_nop 0
	global_load_lds_dwordx4 v128, s[62:63]
	s_waitcnt vmcnt(8)
	s_waitcnt lgkmcnt(0)
	s_barrier
	s_setprio 1
	s_waitcnt lgkmcnt(0)
	v_mfma_f32_16x16x32_bf16 v[124:127], v[140:143], v[204:207], v[124:127]
	v_mfma_f32_16x16x32_bf16 v[120:123], v[148:151], v[204:207], v[120:123]
	v_mfma_f32_16x16x32_bf16 v[108:111], v[140:143], v[212:215], v[108:111]
	v_mfma_f32_16x16x32_bf16 v[104:107], v[148:151], v[212:215], v[104:107]
	v_mfma_f32_16x16x32_bf16 v[92:95], v[140:143], v[220:223], v[92:95]
	v_mfma_f32_16x16x32_bf16 v[88:91], v[148:151], v[220:223], v[88:91]
	v_mfma_f32_16x16x32_bf16 v[76:79], v[140:143], v[230:233], v[76:79]
	v_mfma_f32_16x16x32_bf16 v[72:75], v[148:151], v[230:233], v[72:75]
	v_mfma_f32_16x16x32_bf16 v[124:127], v[144:147], v[208:211], v[124:127]
	v_mfma_f32_16x16x32_bf16 v[120:123], v[152:155], v[208:211], v[120:123]
	v_mfma_f32_16x16x32_bf16 v[108:111], v[144:147], v[216:219], v[108:111]
	v_mfma_f32_16x16x32_bf16 v[104:107], v[152:155], v[216:219], v[104:107]
	v_mfma_f32_16x16x32_bf16 v[92:95], v[144:147], v[224:227], v[92:95]
	v_mfma_f32_16x16x32_bf16 v[88:91], v[152:155], v[224:227], v[88:91]
	v_mfma_f32_16x16x32_bf16 v[76:79], v[144:147], v[234:237], v[76:79]
	v_mfma_f32_16x16x32_bf16 v[72:75], v[152:155], v[234:237], v[72:75]
	s_setprio 0
	s_setprio 1
	v_mfma_f32_16x16x32_bf16 v[116:119], v[188:191], v[204:207], v[116:119]
	v_mfma_f32_16x16x32_bf16 v[112:115], v[196:199], v[204:207], v[112:115]
	v_mfma_f32_16x16x32_bf16 v[100:103], v[188:191], v[212:215], v[100:103]
	v_mfma_f32_16x16x32_bf16 v[96:99], v[196:199], v[212:215], v[96:99]
	v_mfma_f32_16x16x32_bf16 v[84:87], v[188:191], v[220:223], v[84:87]
	v_mfma_f32_16x16x32_bf16 v[80:83], v[196:199], v[220:223], v[80:83]
	v_mfma_f32_16x16x32_bf16 v[68:71], v[188:191], v[230:233], v[68:71]
	v_mfma_f32_16x16x32_bf16 v[64:67], v[196:199], v[230:233], v[64:67]
	v_mfma_f32_16x16x32_bf16 v[116:119], v[192:195], v[208:211], v[116:119]
	v_mfma_f32_16x16x32_bf16 v[112:115], v[200:203], v[208:211], v[112:115]
	v_mfma_f32_16x16x32_bf16 v[100:103], v[192:195], v[216:219], v[100:103]
	v_mfma_f32_16x16x32_bf16 v[96:99], v[200:203], v[216:219], v[96:99]
	v_mfma_f32_16x16x32_bf16 v[84:87], v[192:195], v[224:227], v[84:87]
	v_mfma_f32_16x16x32_bf16 v[80:83], v[200:203], v[224:227], v[80:83]
	v_mfma_f32_16x16x32_bf16 v[68:71], v[192:195], v[234:237], v[68:71]
	v_mfma_f32_16x16x32_bf16 v[64:67], v[200:203], v[234:237], v[64:67]
	s_setprio 0
	s_barrier
	v_mov_b32_e32 v128, v159
	s_add_i32 s72, s21, s3
	ds_read_b128 v[204:207], v178 offset:16384
	ds_read_b128 v[208:211], v178 offset:17408
	ds_read_b128 v[212:215], v178 offset:18432
	ds_read_b128 v[216:219], v178 offset:19456
	ds_read_b128 v[220:223], v178 offset:20480
	ds_read_b128 v[224:227], v178 offset:21504
	ds_read_b128 v[230:233], v178 offset:22528
	ds_read_b128 v[234:237], v178 offset:23552
	s_mov_b32 m0, s72
	s_nop 0
	global_load_lds_dwordx4 v128, s[66:67]
	v_mov_b32_e32 v128, v161
	s_add_i32 m0, s72, 0x2000
	s_add_u32 s72, s66, 0x80000
	global_load_lds_dwordx4 v128, s[66:67]
	s_addc_u32 s73, s67, 0
	v_mov_b32_e32 v128, v159
	s_add_i32 s96, s22, s3
	s_mov_b32 m0, s96
	s_nop 0
	global_load_lds_dwordx4 v128, s[72:73]
	v_mov_b32_e32 v128, v161
	s_add_i32 m0, s96, 0x2000
	s_nop 0
	global_load_lds_dwordx4 v128, s[72:73]
	v_mov_b32_e32 v128, v158
	s_mov_b32 m0, s78
	s_nop 0
	global_load_lds_dwordx4 v128, s[64:65]
	v_mov_b32_e32 v128, v160
	s_mov_b32 m0, s79
	s_nop 0
	global_load_lds_dwordx4 v128, s[64:65]
	s_waitcnt vmcnt(8)
	s_waitcnt lgkmcnt(0)
	s_barrier
; #define PG8_STAGE(bufoff, gbase, voff) do { _Pragma("unroll") for (int _i = 0; _i < 2; ++_i) \
;         { unsigned _vo = (voff)[_i]; asm volatile("" : "+v"(_vo));     \
;         __builtin_amdgcn_global_load_lds((const unsigned*)((const char*)(gbase) + _vo), (PG8_LAS unsigned*)(lds + (bufoff) + ldsw + _i * 8192), 16, 0, 0); } } while (0)
; #define PG8_LDA(dst, b, h) do { _Pragma("unroll") for (int m = 0; m < 4; ++m) _Pragma("unroll") for (int k = 0; k < 2; ++k) dst[m][k] = *(const PG8_LAS bf16x8*)(lds + PG8_SA(b, h) + aoff + m * 2048 + k * 1024); } while (0)
; #define PG8_LDB(dst, b, h) do { _Pragma("unroll") for (int n = 0; n < 2; ++n) _Pragma("unroll") for (int k = 0; k < 2; ++k) dst[n][k] = *(const PG8_LAS bf16x8*)(lds + PG8_SB(b, h) + boff + n * 2048 + k * 1024); } while (0)
; #define PG8_WAIT_V(n) asm volatile("s_waitcnt vmcnt(" #n ")" ::: "memory")
; #define PG8_WAIT_L(n) asm volatile("s_waitcnt lgkmcnt(" #n ")" ::: "memory")
; #define PG8_BAR __builtin_amdgcn_s_barrier()
; #define PG8_SCHED __builtin_amdgcn_sched_barrier(0)
; template <class Epi, class Sched, bool ALIGN_EPI = false, bool SP2 = false, bool ABLK = false, bool F8 = false>
; __device__ __forceinline__ void gemm_phase(PG8_LAS unsigned char* lds, const Gemm g, const Sched& S, const Epi& E, const int wave_s) {
;     ...
;             PG8_WAIT_V(8); PG8_WAIT_L(0); PG8_BAR; PG8_MMA(1, 0, At, B0); PG8_MMA(1, 1, At, B1); PG8_BAR; PG8_SCHED;
;             PG8_LDB(B0, 1, 0); PG8_LDB(B1, 1, 1); PG8_SCHED; PG8_LDA(At, 1, 0); PG8_STAGE(PG8_SA(0, 1), a2 + hstepA, voffA);
;             PG8_WAIT_V(8); PG8_WAIT_L(0); PG8_BAR; PG8_MMA(0, 0, At, B0); PG8_MMA(0, 1, At, B1); PG8_BAR; PG8_SCHED;
	s_setprio 1
	s_waitcnt lgkmcnt(0)
	v_mfma_f32_16x16x32_bf16 v[60:63], v[140:143], v[204:207], v[60:63]
	v_mfma_f32_16x16x32_bf16 v[56:59], v[148:151], v[204:207], v[56:59]
	v_mfma_f32_16x16x32_bf16 v[44:47], v[140:143], v[212:215], v[44:47]
	v_mfma_f32_16x16x32_bf16 v[40:43], v[148:151], v[212:215], v[40:43]
	v_mfma_f32_16x16x32_bf16 v[28:31], v[140:143], v[220:223], v[28:31]
	v_mfma_f32_16x16x32_bf16 v[24:27], v[148:151], v[220:223], v[24:27]
	v_mfma_f32_16x16x32_bf16 v[12:15], v[140:143], v[230:233], v[12:15]
	v_mfma_f32_16x16x32_bf16 v[8:11], v[148:151], v[230:233], v[8:11]
	v_mfma_f32_16x16x32_bf16 v[60:63], v[144:147], v[208:211], v[60:63]
	v_mfma_f32_16x16x32_bf16 v[56:59], v[152:155], v[208:211], v[56:59]
	v_mfma_f32_16x16x32_bf16 v[44:47], v[144:147], v[216:219], v[44:47]
	v_mfma_f32_16x16x32_bf16 v[40:43], v[152:155], v[216:219], v[40:43]
	v_mfma_f32_16x16x32_bf16 v[28:31], v[144:147], v[224:227], v[28:31]
	v_mfma_f32_16x16x32_bf16 v[24:27], v[152:155], v[224:227], v[24:27]
	v_mfma_f32_16x16x32_bf16 v[12:15], v[144:147], v[234:237], v[12:15]
	v_mfma_f32_16x16x32_bf16 v[8:11], v[152:155], v[234:237], v[8:11]
	s_setprio 0
	s_setprio 1
	v_mfma_f32_16x16x32_bf16 v[52:55], v[188:191], v[204:207], v[52:55]
	v_mfma_f32_16x16x32_bf16 v[48:51], v[196:199], v[204:207], v[48:51]
	v_mfma_f32_16x16x32_bf16 v[36:39], v[188:191], v[212:215], v[36:39]
	v_mfma_f32_16x16x32_bf16 v[32:35], v[196:199], v[212:215], v[32:35]
	v_mfma_f32_16x16x32_bf16 v[20:23], v[188:191], v[220:223], v[20:23]
	v_mfma_f32_16x16x32_bf16 v[16:19], v[196:199], v[220:223], v[16:19]
	v_mfma_f32_16x16x32_bf16 v[4:7], v[188:191], v[230:233], v[4:7]
	v_mfma_f32_16x16x32_bf16 v[0:3], v[196:199], v[230:233], v[0:3]
	v_mfma_f32_16x16x32_bf16 v[52:55], v[192:195], v[208:211], v[52:55]
	v_mfma_f32_16x16x32_bf16 v[48:51], v[200:203], v[208:211], v[48:51]
	v_mfma_f32_16x16x32_bf16 v[36:39], v[192:195], v[216:219], v[36:39]
	v_mfma_f32_16x16x32_bf16 v[32:35], v[200:203], v[216:219], v[32:35]
	v_mfma_f32_16x16x32_bf16 v[20:23], v[192:195], v[224:227], v[20:23]
	v_mfma_f32_16x16x32_bf16 v[16:19], v[200:203], v[224:227], v[16:19]
	v_mfma_f32_16x16x32_bf16 v[4:7], v[192:195], v[234:237], v[4:7]
	v_mfma_f32_16x16x32_bf16 v[0:3], v[200:203], v[234:237], v[0:3]
	s_setprio 0
	s_barrier
	s_add_i32 s96, 0, 0x18000
	v_add_u32_e32 v128, s96, v165
	s_add_i32 vcc_hi, 0, 0x1c000
	ds_read_b128 v[140:143], v128
	ds_read_b128 v[144:147], v128 offset:1024
	ds_read_b128 v[148:151], v128 offset:2048
	ds_read_b128 v[152:155], v128 offset:3072
	v_add_u32_e32 v128, vcc_hi, v165
	ds_read_b128 v[188:191], v128
	ds_read_b128 v[192:195], v128 offset:1024
	ds_read_b128 v[196:199], v128 offset:2048
	ds_read_b128 v[200:203], v128 offset:3072
	s_add_u32 s72, s64, 0x80000
	v_mov_b32_e32 v128, v158
	s_mov_b32 m0, s80
	ds_read_b128 v[204:207], v178 offset:32768
	ds_read_b128 v[208:211], v178 offset:33792
	ds_read_b128 v[212:215], v178 offset:34816
	ds_read_b128 v[216:219], v178 offset:35840
	ds_read_b128 v[220:223], v178 offset:36864
	ds_read_b128 v[224:227], v178 offset:37888
	ds_read_b128 v[230:233], v178 offset:38912
	ds_read_b128 v[234:237], v178 offset:39936
	s_addc_u32 s73, s65, 0
	s_nop 0
	global_load_lds_dwordx4 v128, s[72:73]
	v_mov_b32_e32 v128, v160
	s_mov_b32 m0, s81
	s_nop 0
	global_load_lds_dwordx4 v128, s[72:73]
	s_waitcnt vmcnt(8)
	s_waitcnt lgkmcnt(0)
	s_barrier
	s_setprio 1
	s_waitcnt lgkmcnt(0)
	v_mfma_f32_16x16x32_bf16 v[124:127], v[140:143], v[204:207], v[124:127]
	v_mfma_f32_16x16x32_bf16 v[120:123], v[148:151], v[204:207], v[120:123]
	v_mfma_f32_16x16x32_bf16 v[108:111], v[140:143], v[212:215], v[108:111]
	v_mfma_f32_16x16x32_bf16 v[104:107], v[148:151], v[212:215], v[104:107]
	v_mfma_f32_16x16x32_bf16 v[92:95], v[140:143], v[220:223], v[92:95]
	v_mfma_f32_16x16x32_bf16 v[88:91], v[148:151], v[220:223], v[88:91]
	v_mfma_f32_16x16x32_bf16 v[76:79], v[140:143], v[230:233], v[76:79]
	v_mfma_f32_16x16x32_bf16 v[72:75], v[148:151], v[230:233], v[72:75]
	v_mfma_f32_16x16x32_bf16 v[124:127], v[144:147], v[208:211], v[124:127]
	v_mfma_f32_16x16x32_bf16 v[120:123], v[152:155], v[208:211], v[120:123]
	v_mfma_f32_16x16x32_bf16 v[108:111], v[144:147], v[216:219], v[108:111]
	v_mfma_f32_16x16x32_bf16 v[104:107], v[152:155], v[216:219], v[104:107]
	v_mfma_f32_16x16x32_bf16 v[92:95], v[144:147], v[224:227], v[92:95]
	v_mfma_f32_16x16x32_bf16 v[88:91], v[152:155], v[224:227], v[88:91]
	v_mfma_f32_16x16x32_bf16 v[76:79], v[144:147], v[234:237], v[76:79]
	v_mfma_f32_16x16x32_bf16 v[72:75], v[152:155], v[234:237], v[72:75]
	s_setprio 0
	s_setprio 1
	v_mfma_f32_16x16x32_bf16 v[116:119], v[188:191], v[204:207], v[116:119]
	v_mfma_f32_16x16x32_bf16 v[112:115], v[196:199], v[204:207], v[112:115]
	v_mfma_f32_16x16x32_bf16 v[100:103], v[188:191], v[212:215], v[100:103]
	v_mfma_f32_16x16x32_bf16 v[96:99], v[196:199], v[212:215], v[96:99]
	v_mfma_f32_16x16x32_bf16 v[84:87], v[188:191], v[220:223], v[84:87]
	v_mfma_f32_16x16x32_bf16 v[80:83], v[196:199], v[220:223], v[80:83]
	v_mfma_f32_16x16x32_bf16 v[68:71], v[188:191], v[230:233], v[68:71]
	v_mfma_f32_16x16x32_bf16 v[64:67], v[196:199], v[230:233], v[64:67]
	v_mfma_f32_16x16x32_bf16 v[116:119], v[192:195], v[208:211], v[116:119]
	v_mfma_f32_16x16x32_bf16 v[112:115], v[200:203], v[208:211], v[112:115]
	v_mfma_f32_16x16x32_bf16 v[100:103], v[192:195], v[216:219], v[100:103]
	v_mfma_f32_16x16x32_bf16 v[96:99], v[200:203], v[216:219], v[96:99]
	v_mfma_f32_16x16x32_bf16 v[84:87], v[192:195], v[224:227], v[84:87]
	v_mfma_f32_16x16x32_bf16 v[80:83], v[200:203], v[224:227], v[80:83]
	v_mfma_f32_16x16x32_bf16 v[68:71], v[192:195], v[234:237], v[68:71]
	v_mfma_f32_16x16x32_bf16 v[64:67], v[200:203], v[234:237], v[64:67]
	s_setprio 0
	s_barrier
; #define PG8_STAGE(bufoff, gbase, voff) do { _Pragma("unroll") for (int _i = 0; _i < 2; ++_i) \
;         { unsigned _vo = (voff)[_i]; asm volatile("" : "+v"(_vo));     \
;         __builtin_amdgcn_global_load_lds((const unsigned*)((const char*)(gbase) + _vo), (PG8_LAS unsigned*)(lds + (bufoff) + ldsw + _i * 8192), 16, 0, 0); } } while (0)
; #define PG8_LDA(dst, b, h) do { _Pragma("unroll") for (int m = 0; m < 4; ++m) _Pragma("unroll") for (int k = 0; k < 2; ++k) dst[m][k] = *(const PG8_LAS bf16x8*)(lds + PG8_SA(b, h) + aoff + m * 2048 + k * 1024); } while (0)
; #define PG8_WAIT_V(n) asm volatile("s_waitcnt vmcnt(" #n ")" ::: "memory")
; #define PG8_WAIT_L(n) asm volatile("s_waitcnt lgkmcnt(" #n ")" ::: "memory")
; #define PG8_BAR __builtin_amdgcn_s_barrier()
; #define PG8_SCHED __builtin_amdgcn_sched_barrier(0)
; template <class Epi, class Sched, bool ALIGN_EPI = false, bool SP2 = false, bool ABLK = false, bool F8 = false>
; __device__ __forceinline__ void gemm_phase(PG8_LAS unsigned char* lds, const Gemm g, const Sched& S, const Epi& E, const int wave_s) {
;     ...
;         for (int t = 0; t < nt; t += 2) {
;             const bool last = (t == nt - 2);
;             const char* a1 = cA + (size_t)(t + 1) * kstepA;
;             const char* a2 = last ? nA : cA + (size_t)(t + 2) * kstepA; const char* b2 = last ? nB : cB + (size_t)(t + 2) * kstep;
;             const char* a3 = a2 + kstepA; const char* b3 = b2 + kstep;
;     ...
;             PG8_LDA(At, 1, 1); PG8_STAGE(PG8_SB(1, 0), b3, voffB); PG8_STAGE(PG8_SB(1, 1), b3 + hstep, voffB); PG8_STAGE(PG8_SA(1, 0), a3, voffA);
;             PG8_WAIT_V(8); PG8_WAIT_L(0); PG8_BAR; PG8_MMA(1, 0, At, B0); PG8_MMA(1, 1, At, B1); PG8_BAR; PG8_SCHED;
;     ...
;         if constexpr (ALIGN_EPI) { if (wr == 0) PG8_BAR; }
	v_mov_b32_e32 v128, v159
	ds_read_b128 v[204:207], v178 offset:49152
	ds_read_b128 v[208:211], v178 offset:50176
	ds_read_b128 v[212:215], v178 offset:51200
	ds_read_b128 v[216:219], v178 offset:52224
	ds_read_b128 v[220:223], v178 offset:53248
	ds_read_b128 v[224:227], v178 offset:54272
	ds_read_b128 v[230:233], v178 offset:55296
	ds_read_b128 v[234:237], v178 offset:56320
	s_add_i32 s72, s96, s3
	v_lshl_add_u64 v[156:157], s[66:67], 0, v[128:129]
	v_lshl_add_u64 v[156:157], v[156:157], 0, s[12:13]
	s_mov_b32 m0, s72
	v_mov_b32_e32 v128, v161
	global_load_lds_dwordx4 v[156:157], off
	s_add_i32 m0, s72, 0x2000
	s_nop 0
	v_lshl_add_u64 v[156:157], s[66:67], 0, v[128:129]
	s_add_u32 s66, s66, 0x80080
	v_lshl_add_u64 v[156:157], v[156:157], 0, s[12:13]
	s_addc_u32 s67, s67, 0
	v_mov_b32_e32 v128, v159
	s_add_i32 s72, vcc_hi, s3
	global_load_lds_dwordx4 v[156:157], off
	s_mov_b32 m0, s72
	s_nop 0
	global_load_lds_dwordx4 v128, s[66:67]
	v_mov_b32_e32 v128, v161
	s_add_i32 m0, s72, 0x2000
	s_nop 0
	global_load_lds_dwordx4 v128, s[66:67]
	v_mov_b32_e32 v128, v158
	s_mov_b32 m0, s46
	v_lshl_add_u64 v[156:157], s[64:65], 0, v[128:129]
	v_lshl_add_u64 v[156:157], v[156:157], 0, s[12:13]
	v_mov_b32_e32 v128, v160
	global_load_lds_dwordx4 v[156:157], off
	s_mov_b32 m0, s47
	v_lshl_add_u64 v[156:157], s[64:65], 0, v[128:129]
	v_lshl_add_u64 v[156:157], v[156:157], 0, s[12:13]
	global_load_lds_dwordx4 v[156:157], off
	s_waitcnt vmcnt(8)
	s_waitcnt lgkmcnt(0)
	s_barrier
	s_setprio 1
	s_waitcnt lgkmcnt(0)
	v_mfma_f32_16x16x32_bf16 v[60:63], v[140:143], v[204:207], v[60:63]
	v_mfma_f32_16x16x32_bf16 v[56:59], v[148:151], v[204:207], v[56:59]
	v_mfma_f32_16x16x32_bf16 v[44:47], v[140:143], v[212:215], v[44:47]
	v_mfma_f32_16x16x32_bf16 v[40:43], v[148:151], v[212:215], v[40:43]
	v_mfma_f32_16x16x32_bf16 v[28:31], v[140:143], v[220:223], v[28:31]
	v_mfma_f32_16x16x32_bf16 v[24:27], v[148:151], v[220:223], v[24:27]
	v_mfma_f32_16x16x32_bf16 v[12:15], v[140:143], v[230:233], v[12:15]
	v_mfma_f32_16x16x32_bf16 v[8:11], v[148:151], v[230:233], v[8:11]
	v_mfma_f32_16x16x32_bf16 v[60:63], v[144:147], v[208:211], v[60:63]
	v_mfma_f32_16x16x32_bf16 v[56:59], v[152:155], v[208:211], v[56:59]
	v_mfma_f32_16x16x32_bf16 v[44:47], v[144:147], v[216:219], v[44:47]
	v_mfma_f32_16x16x32_bf16 v[40:43], v[152:155], v[216:219], v[40:43]
	v_mfma_f32_16x16x32_bf16 v[28:31], v[144:147], v[224:227], v[28:31]
	v_mfma_f32_16x16x32_bf16 v[24:27], v[152:155], v[224:227], v[24:27]
	v_mfma_f32_16x16x32_bf16 v[12:15], v[144:147], v[234:237], v[12:15]
	v_mfma_f32_16x16x32_bf16 v[8:11], v[152:155], v[234:237], v[8:11]
	s_setprio 0
	s_setprio 1
	v_mfma_f32_16x16x32_bf16 v[52:55], v[188:191], v[204:207], v[52:55]
	v_mfma_f32_16x16x32_bf16 v[48:51], v[196:199], v[204:207], v[48:51]
	v_mfma_f32_16x16x32_bf16 v[36:39], v[188:191], v[212:215], v[36:39]
	v_mfma_f32_16x16x32_bf16 v[32:35], v[196:199], v[212:215], v[32:35]
	v_mfma_f32_16x16x32_bf16 v[20:23], v[188:191], v[220:223], v[20:23]
	v_mfma_f32_16x16x32_bf16 v[16:19], v[196:199], v[220:223], v[16:19]
	v_mfma_f32_16x16x32_bf16 v[4:7], v[188:191], v[230:233], v[4:7]
	v_mfma_f32_16x16x32_bf16 v[0:3], v[196:199], v[230:233], v[0:3]
	v_mfma_f32_16x16x32_bf16 v[52:55], v[192:195], v[208:211], v[52:55]
	v_mfma_f32_16x16x32_bf16 v[48:51], v[200:203], v[208:211], v[48:51]
	v_mfma_f32_16x16x32_bf16 v[36:39], v[192:195], v[216:219], v[36:39]
	v_mfma_f32_16x16x32_bf16 v[32:35], v[200:203], v[216:219], v[32:35]
	v_mfma_f32_16x16x32_bf16 v[20:23], v[192:195], v[224:227], v[20:23]
	v_mfma_f32_16x16x32_bf16 v[16:19], v[200:203], v[224:227], v[16:19]
	v_mfma_f32_16x16x32_bf16 v[4:7], v[192:195], v[234:237], v[4:7]
	v_mfma_f32_16x16x32_bf16 v[0:3], v[200:203], v[234:237], v[0:3]
	s_setprio 0
	s_barrier
	s_add_i32 vcc_lo, vcc_lo, 2
	s_add_u32 s62, s62, 0x100
	s_addc_u32 s63, s63, 0
	s_add_u32 s59, s59, 0x100
	s_addc_u32 s61, s61, 0
	s_cmp_gt_u32 vcc_lo, 29
	s_cbranch_scc0 .LBB0_395
	s_and_b64 vcc, exec, s[36:37]
	s_cbranch_vccz .LBB0_398
	s_barrier

; #define PG8_STAGE(bufoff, gbase, voff) do { _Pragma("unroll") for (int _i = 0; _i < 2; ++_i) \
;         { unsigned _vo = (voff)[_i]; asm volatile("" : "+v"(_vo));     \
;         __builtin_amdgcn_global_load_lds((const unsigned*)((const char*)(gbase) + _vo), (PG8_LAS unsigned*)(lds + (bufoff) + ldsw + _i * 8192), 16, 0, 0); } } while (0)
; #define PG8_LDA(dst, b, h) do { _Pragma("unroll") for (int m = 0; m < 4; ++m) _Pragma("unroll") for (int k = 0; k < 2; ++k) dst[m][k] = *(const PG8_LAS bf16x8*)(lds + PG8_SA(b, h) + aoff + m * 2048 + k * 1024); } while (0)
; #define PG8_LDB(dst, b, h) do { _Pragma("unroll") for (int n = 0; n < 2; ++n) _Pragma("unroll") for (int k = 0; k < 2; ++k) dst[n][k] = *(const PG8_LAS bf16x8*)(lds + PG8_SB(b, h) + boff + n * 2048 + k * 1024); } while (0)
; #define PG8_WAIT_V(n) asm volatile("s_waitcnt vmcnt(" #n ")" ::: "memory")
; #define PG8_WAIT_L(n) asm volatile("s_waitcnt lgkmcnt(" #n ")" ::: "memory")
; #define PG8_BAR __builtin_amdgcn_s_barrier()
; #define PG8_SCHED __builtin_amdgcn_sched_barrier(0)
; template <class Epi, class Sched, bool ALIGN_EPI = false, bool SP2 = false, bool ABLK = false, bool F8 = false>
; __device__ __forceinline__ void gemm_phase(PG8_LAS unsigned char* lds, const Gemm g, const Sched& S, const Epi& E, const int wave_s) {
;     ...
;             PG8_LDB(B0, 0, 0); PG8_LDB(B1, 0, 1); PG8_SCHED; PG8_LDA(At, 0, 0); PG8_STAGE(PG8_SA(1, 1), a1 + hstepA, voffA);
;             PG8_WAIT_V(8); PG8_WAIT_L(0); PG8_BAR; PG8_MMA(0, 0, At, B0); PG8_MMA(0, 1, At, B1); PG8_BAR; PG8_SCHED;
;             PG8_LDA(At, 0, 1); PG8_STAGE(PG8_SB(0, 0), b2, voffB); PG8_STAGE(PG8_SB(0, 1), b2 + hstep, voffB); PG8_STAGE(PG8_SA(0, 0), a2, voffA);
;             PG8_WAIT_V(8); PG8_WAIT_L(0); PG8_BAR; PG8_MMA(1, 0, At, B0); PG8_MMA(1, 1, At, B1); PG8_BAR; PG8_SCHED;
.LBB0_592:
	ds_read_b128 v[64:67], v236
	ds_read_b128 v[68:71], v236 offset:1024
	ds_read_b128 v[76:79], v236 offset:2048
	ds_read_b128 v[80:83], v236 offset:3072
	ds_read_b128 v[88:91], v237
	ds_read_b128 v[100:103], v237 offset:1024
	ds_read_b128 v[112:115], v237 offset:2048
	ds_read_b128 v[124:127], v237 offset:3072
	s_add_u32 s62, s60, 0xfffc0080
	s_addc_u32 s63, s61, -1
	s_cmp_eq_u32 s76, 12
	s_cselect_b32 s63, s51, s63
	s_cselect_b32 s62, s57, s62
	s_cselect_b32 s65, s49, s75
	s_cselect_b32 s64, s67, s74
	v_mov_b32_e32 v192, v229
	ds_read_b128 v[136:139], v238
	ds_read_b128 v[144:147], v238 offset:1024
	ds_read_b128 v[160:163], v238 offset:2048
	ds_read_b128 v[164:167], v238 offset:3072
	ds_read_b128 v[176:179], v238 offset:4096
	ds_read_b128 v[180:183], v238 offset:5120
	ds_read_b128 v[184:187], v238 offset:6144
	ds_read_b128 v[188:191], v238 offset:7168
	s_add_i32 m0, s20, 0xc000
	s_nop 0
	global_load_lds_dwordx4 v192, s[60:61]
	v_mov_b32_e32 v192, v231
	s_add_i32 m0, s20, 0xe000
	s_nop 0
	global_load_lds_dwordx4 v192, s[60:61]
	s_waitcnt vmcnt(8)
	s_waitcnt lgkmcnt(0)
	s_barrier
	s_setprio 1
	s_waitcnt lgkmcnt(0)
	v_mfma_f32_16x16x32_bf16 v[172:175], v[64:67], v[136:139], v[172:175]
	v_mfma_f32_16x16x32_bf16 v[168:171], v[76:79], v[136:139], v[168:171]
	v_mfma_f32_16x16x32_bf16 v[148:151], v[64:67], v[160:163], v[148:151]
	v_mfma_f32_16x16x32_bf16 v[140:143], v[76:79], v[160:163], v[140:143]
	v_mfma_f32_16x16x32_bf16 v[120:123], v[64:67], v[176:179], v[120:123]
	v_mfma_f32_16x16x32_bf16 v[116:119], v[76:79], v[176:179], v[116:119]
	v_mfma_f32_16x16x32_bf16 v[96:99], v[64:67], v[184:187], v[96:99]
	v_mfma_f32_16x16x32_bf16 v[92:95], v[76:79], v[184:187], v[92:95]
	v_mfma_f32_16x16x32_bf16 v[172:175], v[68:71], v[144:147], v[172:175]
	v_mfma_f32_16x16x32_bf16 v[168:171], v[80:83], v[144:147], v[168:171]
	v_mfma_f32_16x16x32_bf16 v[148:151], v[68:71], v[164:167], v[148:151]
	v_mfma_f32_16x16x32_bf16 v[140:143], v[80:83], v[164:167], v[140:143]
	v_mfma_f32_16x16x32_bf16 v[120:123], v[68:71], v[180:183], v[120:123]
	v_mfma_f32_16x16x32_bf16 v[116:119], v[80:83], v[180:183], v[116:119]
	v_mfma_f32_16x16x32_bf16 v[96:99], v[68:71], v[188:191], v[96:99]
	v_mfma_f32_16x16x32_bf16 v[92:95], v[80:83], v[188:191], v[92:95]
	s_setprio 0
	s_setprio 1
	v_mfma_f32_16x16x32_bf16 v[156:159], v[88:91], v[136:139], v[156:159]
	v_mfma_f32_16x16x32_bf16 v[132:135], v[88:91], v[160:163], v[132:135]
	v_mfma_f32_16x16x32_bf16 v[128:131], v[112:115], v[160:163], v[128:131]
	v_mfma_f32_16x16x32_bf16 v[108:111], v[88:91], v[176:179], v[108:111]
	v_mfma_f32_16x16x32_bf16 v[104:107], v[112:115], v[176:179], v[104:107]
	v_mfma_f32_16x16x32_bf16 v[84:87], v[88:91], v[184:187], v[84:87]
	v_mfma_f32_16x16x32_bf16 v[72:75], v[112:115], v[184:187], v[72:75]
	v_mfma_f32_16x16x32_bf16 v[156:159], v[100:103], v[144:147], v[156:159]
	v_mfma_f32_16x16x32_bf16 v[136:139], v[112:115], v[136:139], v[152:155]
	v_mfma_f32_16x16x32_bf16 v[132:135], v[100:103], v[164:167], v[132:135]
	v_mfma_f32_16x16x32_bf16 v[128:131], v[124:127], v[164:167], v[128:131]
	v_mfma_f32_16x16x32_bf16 v[108:111], v[100:103], v[180:183], v[108:111]
	v_mfma_f32_16x16x32_bf16 v[104:107], v[124:127], v[180:183], v[104:107]
	v_mfma_f32_16x16x32_bf16 v[84:87], v[100:103], v[188:191], v[84:87]
	v_mfma_f32_16x16x32_bf16 v[72:75], v[124:127], v[188:191], v[72:75]
	v_mfma_f32_16x16x32_bf16 v[136:139], v[124:127], v[144:147], v[136:139]
	s_setprio 0
	s_barrier
	v_mov_b32_e32 v192, v230
	s_add_i32 s72, s59, s3
	ds_read_b128 v[144:147], v238 offset:16384
	ds_read_b128 v[152:155], v238 offset:17408
	ds_read_b128 v[160:163], v238 offset:18432
	ds_read_b128 v[164:167], v238 offset:19456
	ds_read_b128 v[176:179], v238 offset:20480
	ds_read_b128 v[180:183], v238 offset:21504
	ds_read_b128 v[184:187], v238 offset:22528
	ds_read_b128 v[188:191], v238 offset:23552
	s_mov_b32 m0, s72
	s_nop 0
	global_load_lds_dwordx4 v192, s[64:65]
	v_mov_b32_e32 v192, v232
	s_add_i32 m0, s72, 0x2000
	s_add_u32 s72, s64, 0x40000
	global_load_lds_dwordx4 v192, s[64:65]
	s_addc_u32 s73, s65, 0
	v_mov_b32_e32 v192, v230
	s_add_i32 s77, s66, s3
	s_mov_b32 m0, s77
	s_nop 0
	global_load_lds_dwordx4 v192, s[72:73]
	v_mov_b32_e32 v192, v232
	s_add_i32 m0, s77, 0x2000
	s_nop 0
	global_load_lds_dwordx4 v192, s[72:73]
	v_mov_b32_e32 v192, v229
	s_mov_b32 m0, s20
	s_nop 0
	global_load_lds_dwordx4 v192, s[62:63]
	v_mov_b32_e32 v192, v231
	s_mov_b32 m0, s21
	s_nop 0
	global_load_lds_dwordx4 v192, s[62:63]
	s_waitcnt vmcnt(8)
	s_waitcnt lgkmcnt(0)
	s_barrier
; #define PG8_STAGE(bufoff, gbase, voff) do { _Pragma("unroll") for (int _i = 0; _i < 2; ++_i) \
;         { unsigned _vo = (voff)[_i]; asm volatile("" : "+v"(_vo));     \
;         __builtin_amdgcn_global_load_lds((const unsigned*)((const char*)(gbase) + _vo), (PG8_LAS unsigned*)(lds + (bufoff) + ldsw + _i * 8192), 16, 0, 0); } } while (0)
; #define PG8_LDA(dst, b, h) do { _Pragma("unroll") for (int m = 0; m < 4; ++m) _Pragma("unroll") for (int k = 0; k < 2; ++k) dst[m][k] = *(const PG8_LAS bf16x8*)(lds + PG8_SA(b, h) + aoff + m * 2048 + k * 1024); } while (0)
; #define PG8_LDB(dst, b, h) do { _Pragma("unroll") for (int n = 0; n < 2; ++n) _Pragma("unroll") for (int k = 0; k < 2; ++k) dst[n][k] = *(const PG8_LAS bf16x8*)(lds + PG8_SB(b, h) + boff + n * 2048 + k * 1024); } while (0)
; #define PG8_WAIT_V(n) asm volatile("s_waitcnt vmcnt(" #n ")" ::: "memory")
; #define PG8_WAIT_L(n) asm volatile("s_waitcnt lgkmcnt(" #n ")" ::: "memory")
; #define PG8_BAR __builtin_amdgcn_s_barrier()
; #define PG8_SCHED __builtin_amdgcn_sched_barrier(0)
; template <class Epi, class Sched, bool ALIGN_EPI = false, bool SP2 = false, bool ABLK = false, bool F8 = false>
; __device__ __forceinline__ void gemm_phase(PG8_LAS unsigned char* lds, const Gemm g, const Sched& S, const Epi& E, const int wave_s) {
;     ...
;             PG8_WAIT_V(8); PG8_WAIT_L(0); PG8_BAR; PG8_MMA(1, 0, At, B0); PG8_MMA(1, 1, At, B1); PG8_BAR; PG8_SCHED;
;             PG8_LDB(B0, 1, 0); PG8_LDB(B1, 1, 1); PG8_SCHED; PG8_LDA(At, 1, 0); PG8_STAGE(PG8_SA(0, 1), a2 + hstepA, voffA);
;             PG8_WAIT_V(8); PG8_WAIT_L(0); PG8_BAR; PG8_MMA(0, 0, At, B0); PG8_MMA(0, 1, At, B1); PG8_BAR; PG8_SCHED;
	s_setprio 1
	s_waitcnt lgkmcnt(0)
	v_mfma_f32_16x16x32_bf16 v[60:63], v[64:67], v[144:147], v[60:63]
	v_mfma_f32_16x16x32_bf16 v[56:59], v[76:79], v[144:147], v[56:59]
	v_mfma_f32_16x16x32_bf16 v[44:47], v[64:67], v[160:163], v[44:47]
	v_mfma_f32_16x16x32_bf16 v[40:43], v[76:79], v[160:163], v[40:43]
	v_mfma_f32_16x16x32_bf16 v[28:31], v[64:67], v[176:179], v[28:31]
	v_mfma_f32_16x16x32_bf16 v[24:27], v[76:79], v[176:179], v[24:27]
	v_mfma_f32_16x16x32_bf16 v[12:15], v[64:67], v[184:187], v[12:15]
	v_mfma_f32_16x16x32_bf16 v[8:11], v[76:79], v[184:187], v[8:11]
	v_mfma_f32_16x16x32_bf16 v[60:63], v[68:71], v[152:155], v[60:63]
	v_mfma_f32_16x16x32_bf16 v[56:59], v[80:83], v[152:155], v[56:59]
	v_mfma_f32_16x16x32_bf16 v[44:47], v[68:71], v[164:167], v[44:47]
	v_mfma_f32_16x16x32_bf16 v[40:43], v[80:83], v[164:167], v[40:43]
	v_mfma_f32_16x16x32_bf16 v[28:31], v[68:71], v[180:183], v[28:31]
	v_mfma_f32_16x16x32_bf16 v[24:27], v[80:83], v[180:183], v[24:27]
	v_mfma_f32_16x16x32_bf16 v[12:15], v[68:71], v[188:191], v[12:15]
	v_mfma_f32_16x16x32_bf16 v[8:11], v[80:83], v[188:191], v[8:11]
	s_setprio 0
	s_setprio 1
	v_mfma_f32_16x16x32_bf16 v[52:55], v[88:91], v[144:147], v[52:55]
	v_mfma_f32_16x16x32_bf16 v[48:51], v[112:115], v[144:147], v[48:51]
	v_mfma_f32_16x16x32_bf16 v[36:39], v[88:91], v[160:163], v[36:39]
	v_mfma_f32_16x16x32_bf16 v[32:35], v[112:115], v[160:163], v[32:35]
	v_mfma_f32_16x16x32_bf16 v[20:23], v[88:91], v[176:179], v[20:23]
	v_mfma_f32_16x16x32_bf16 v[16:19], v[112:115], v[176:179], v[16:19]
	v_mfma_f32_16x16x32_bf16 v[4:7], v[88:91], v[184:187], v[4:7]
	v_mfma_f32_16x16x32_bf16 v[0:3], v[112:115], v[184:187], v[0:3]
	v_mfma_f32_16x16x32_bf16 v[52:55], v[100:103], v[152:155], v[52:55]
	v_mfma_f32_16x16x32_bf16 v[48:51], v[124:127], v[152:155], v[48:51]
	v_mfma_f32_16x16x32_bf16 v[36:39], v[100:103], v[164:167], v[36:39]
	v_mfma_f32_16x16x32_bf16 v[32:35], v[124:127], v[164:167], v[32:35]
	v_mfma_f32_16x16x32_bf16 v[20:23], v[100:103], v[180:183], v[20:23]
	v_mfma_f32_16x16x32_bf16 v[16:19], v[124:127], v[180:183], v[16:19]
	v_mfma_f32_16x16x32_bf16 v[4:7], v[100:103], v[188:191], v[4:7]
	v_mfma_f32_16x16x32_bf16 v[0:3], v[124:127], v[188:191], v[0:3]
	s_setprio 0
	s_barrier
	s_add_i32 s77, 0, 0x18000
	s_add_i32 s78, 0, 0x1c000
	v_add_u32_e32 v80, s77, v234
	v_add_u32_e32 v124, s78, v234
	ds_read_b128 v[64:67], v80
	ds_read_b128 v[68:71], v80 offset:1024
	ds_read_b128 v[76:79], v80 offset:2048
	ds_read_b128 v[80:83], v80 offset:3072
	ds_read_b128 v[88:91], v124
	ds_read_b128 v[100:103], v124 offset:1024
	ds_read_b128 v[112:115], v124 offset:2048
	ds_read_b128 v[124:127], v124 offset:3072
	s_add_u32 s72, s62, 0x40000
	v_mov_b32_e32 v192, v229
	s_mov_b32 m0, s22
	ds_read_b128 v[144:147], v238 offset:32768
	ds_read_b128 v[152:155], v238 offset:33792
	ds_read_b128 v[160:163], v238 offset:34816
	ds_read_b128 v[164:167], v238 offset:35840
	ds_read_b128 v[176:179], v238 offset:36864
	ds_read_b128 v[180:183], v238 offset:37888
	ds_read_b128 v[184:187], v238 offset:38912
	ds_read_b128 v[188:191], v238 offset:39936
	s_addc_u32 s73, s63, 0
	s_nop 0
	global_load_lds_dwordx4 v192, s[72:73]
	v_mov_b32_e32 v192, v231
	s_mov_b32 m0, s23
	s_nop 0
	global_load_lds_dwordx4 v192, s[72:73]
	s_waitcnt vmcnt(8)
	s_waitcnt lgkmcnt(0)
	s_barrier
	s_setprio 1
	s_waitcnt lgkmcnt(0)
	v_mfma_f32_16x16x32_bf16 v[172:175], v[64:67], v[144:147], v[172:175]
	v_mfma_f32_16x16x32_bf16 v[168:171], v[76:79], v[144:147], v[168:171]
	v_mfma_f32_16x16x32_bf16 v[148:151], v[64:67], v[160:163], v[148:151]
	v_mfma_f32_16x16x32_bf16 v[140:143], v[76:79], v[160:163], v[140:143]
	v_mfma_f32_16x16x32_bf16 v[120:123], v[64:67], v[176:179], v[120:123]
	v_mfma_f32_16x16x32_bf16 v[116:119], v[76:79], v[176:179], v[116:119]
	v_mfma_f32_16x16x32_bf16 v[96:99], v[64:67], v[184:187], v[96:99]
	v_mfma_f32_16x16x32_bf16 v[92:95], v[76:79], v[184:187], v[92:95]
	v_mfma_f32_16x16x32_bf16 v[172:175], v[68:71], v[152:155], v[172:175]
	v_mfma_f32_16x16x32_bf16 v[168:171], v[80:83], v[152:155], v[168:171]
	v_mfma_f32_16x16x32_bf16 v[148:151], v[68:71], v[164:167], v[148:151]
	v_mfma_f32_16x16x32_bf16 v[140:143], v[80:83], v[164:167], v[140:143]
	v_mfma_f32_16x16x32_bf16 v[120:123], v[68:71], v[180:183], v[120:123]
	v_mfma_f32_16x16x32_bf16 v[116:119], v[80:83], v[180:183], v[116:119]
	v_mfma_f32_16x16x32_bf16 v[96:99], v[68:71], v[188:191], v[96:99]
	v_mfma_f32_16x16x32_bf16 v[92:95], v[80:83], v[188:191], v[92:95]
	s_setprio 0
	s_setprio 1
	v_mfma_f32_16x16x32_bf16 v[156:159], v[88:91], v[144:147], v[156:159]
	v_mfma_f32_16x16x32_bf16 v[136:139], v[112:115], v[144:147], v[136:139]
	v_mfma_f32_16x16x32_bf16 v[132:135], v[88:91], v[160:163], v[132:135]
	v_mfma_f32_16x16x32_bf16 v[128:131], v[112:115], v[160:163], v[128:131]
	v_mfma_f32_16x16x32_bf16 v[108:111], v[88:91], v[176:179], v[108:111]
	v_mfma_f32_16x16x32_bf16 v[104:107], v[112:115], v[176:179], v[104:107]
	v_mfma_f32_16x16x32_bf16 v[84:87], v[88:91], v[184:187], v[84:87]
	v_mfma_f32_16x16x32_bf16 v[72:75], v[112:115], v[184:187], v[72:75]
	v_mfma_f32_16x16x32_bf16 v[156:159], v[100:103], v[152:155], v[156:159]
	v_mfma_f32_16x16x32_bf16 v[152:155], v[124:127], v[152:155], v[136:139]
	v_mfma_f32_16x16x32_bf16 v[132:135], v[100:103], v[164:167], v[132:135]
	v_mfma_f32_16x16x32_bf16 v[128:131], v[124:127], v[164:167], v[128:131]
	v_mfma_f32_16x16x32_bf16 v[108:111], v[100:103], v[180:183], v[108:111]
	v_mfma_f32_16x16x32_bf16 v[104:107], v[124:127], v[180:183], v[104:107]
	v_mfma_f32_16x16x32_bf16 v[84:87], v[100:103], v[188:191], v[84:87]
	v_mfma_f32_16x16x32_bf16 v[72:75], v[124:127], v[188:191], v[72:75]
	s_setprio 0
	s_barrier
; #define PG8_STAGE(bufoff, gbase, voff) do { _Pragma("unroll") for (int _i = 0; _i < 2; ++_i) \
;         { unsigned _vo = (voff)[_i]; asm volatile("" : "+v"(_vo));     \
;         __builtin_amdgcn_global_load_lds((const unsigned*)((const char*)(gbase) + _vo), (PG8_LAS unsigned*)(lds + (bufoff) + ldsw + _i * 8192), 16, 0, 0); } } while (0)
; #define PG8_LDA(dst, b, h) do { _Pragma("unroll") for (int m = 0; m < 4; ++m) _Pragma("unroll") for (int k = 0; k < 2; ++k) dst[m][k] = *(const PG8_LAS bf16x8*)(lds + PG8_SA(b, h) + aoff + m * 2048 + k * 1024); } while (0)
; #define PG8_WAIT_V(n) asm volatile("s_waitcnt vmcnt(" #n ")" ::: "memory")
; #define PG8_WAIT_L(n) asm volatile("s_waitcnt lgkmcnt(" #n ")" ::: "memory")
; #define PG8_BAR __builtin_amdgcn_s_barrier()
; #define PG8_SCHED __builtin_amdgcn_sched_barrier(0)
; template <class Epi, class Sched, bool ALIGN_EPI = false, bool SP2 = false, bool ABLK = false, bool F8 = false>
; __device__ __forceinline__ void gemm_phase(PG8_LAS unsigned char* lds, const Gemm g, const Sched& S, const Epi& E, const int wave_s) {
;     ...
;         for (int t = 0; t < nt; t += 2) {
;             const bool last = (t == nt - 2);
;             const char* a1 = cA + (size_t)(t + 1) * kstepA;
;             const char* a2 = last ? nA : cA + (size_t)(t + 2) * kstepA; const char* b2 = last ? nB : cB + (size_t)(t + 2) * kstep;
;             const char* a3 = a2 + kstepA; const char* b3 = b2 + kstep;
;     ...
;             PG8_LDA(At, 1, 1); PG8_STAGE(PG8_SB(1, 0), b3, voffB); PG8_STAGE(PG8_SB(1, 1), b3 + hstep, voffB); PG8_STAGE(PG8_SA(1, 0), a3, voffA);
;             PG8_WAIT_V(8); PG8_WAIT_L(0); PG8_BAR; PG8_MMA(1, 0, At, B0); PG8_MMA(1, 1, At, B1); PG8_BAR; PG8_SCHED;
;     ...
;         if constexpr (ALIGN_EPI) { if (wr == 0) PG8_BAR; }
	v_mov_b32_e32 v200, v230
	ds_read_b128 v[136:139], v238 offset:49152
	ds_read_b128 v[144:147], v238 offset:50176
	ds_read_b128 v[160:163], v238 offset:51200
	ds_read_b128 v[164:167], v238 offset:52224
	ds_read_b128 v[176:179], v238 offset:53248
	ds_read_b128 v[180:183], v238 offset:54272
	ds_read_b128 v[184:187], v238 offset:55296
	ds_read_b128 v[188:191], v238 offset:56320
	s_add_i32 s72, s77, s3
	v_lshl_add_u64 v[192:193], s[64:65], 0, v[200:201]
	v_lshl_add_u64 v[192:193], v[192:193], 0, s[42:43]
	s_mov_b32 m0, s72
	v_mov_b32_e32 v200, v232
	global_load_lds_dwordx4 v[192:193], off
	s_add_i32 m0, s72, 0x2000
	v_lshl_add_u64 v[192:193], s[64:65], 0, v[200:201]
	v_lshl_add_u64 v[192:193], v[192:193], 0, s[42:43]
	s_add_u32 s64, s64, 0x40080
	global_load_lds_dwordx4 v[192:193], off
	s_addc_u32 s65, s65, 0
	v_mov_b32_e32 v192, v230
	s_add_i32 s72, s78, s3
	s_mov_b32 m0, s72
	v_mov_b32_e32 v200, v229
	global_load_lds_dwordx4 v192, s[64:65]
	v_mov_b32_e32 v192, v232
	s_add_i32 m0, s72, 0x2000
	s_nop 0
	global_load_lds_dwordx4 v192, s[64:65]
	s_mov_b32 m0, s46
	v_lshl_add_u64 v[192:193], s[62:63], 0, v[200:201]
	v_lshl_add_u64 v[192:193], v[192:193], 0, s[42:43]
	v_mov_b32_e32 v200, v231
	global_load_lds_dwordx4 v[192:193], off
	s_mov_b32 m0, s47
	v_lshl_add_u64 v[192:193], s[62:63], 0, v[200:201]
	v_lshl_add_u64 v[192:193], v[192:193], 0, s[42:43]
	global_load_lds_dwordx4 v[192:193], off
	s_waitcnt vmcnt(8)
	s_waitcnt lgkmcnt(0)
	s_barrier
	s_setprio 1
	s_waitcnt lgkmcnt(0)
	v_mfma_f32_16x16x32_bf16 v[60:63], v[64:67], v[136:139], v[60:63]
	v_mfma_f32_16x16x32_bf16 v[56:59], v[76:79], v[136:139], v[56:59]
	v_mfma_f32_16x16x32_bf16 v[44:47], v[64:67], v[160:163], v[44:47]
	v_mfma_f32_16x16x32_bf16 v[40:43], v[76:79], v[160:163], v[40:43]
	v_mfma_f32_16x16x32_bf16 v[28:31], v[64:67], v[176:179], v[28:31]
	v_mfma_f32_16x16x32_bf16 v[24:27], v[76:79], v[176:179], v[24:27]
	v_mfma_f32_16x16x32_bf16 v[12:15], v[64:67], v[184:187], v[12:15]
	v_mfma_f32_16x16x32_bf16 v[8:11], v[76:79], v[184:187], v[8:11]
	v_mfma_f32_16x16x32_bf16 v[60:63], v[68:71], v[144:147], v[60:63]
	v_mfma_f32_16x16x32_bf16 v[56:59], v[80:83], v[144:147], v[56:59]
	v_mfma_f32_16x16x32_bf16 v[44:47], v[68:71], v[164:167], v[44:47]
	v_mfma_f32_16x16x32_bf16 v[40:43], v[80:83], v[164:167], v[40:43]
	v_mfma_f32_16x16x32_bf16 v[28:31], v[68:71], v[180:183], v[28:31]
	v_mfma_f32_16x16x32_bf16 v[24:27], v[80:83], v[180:183], v[24:27]
	v_mfma_f32_16x16x32_bf16 v[12:15], v[68:71], v[188:191], v[12:15]
	v_mfma_f32_16x16x32_bf16 v[8:11], v[80:83], v[188:191], v[8:11]
	s_setprio 0
	s_setprio 1
	v_mfma_f32_16x16x32_bf16 v[52:55], v[88:91], v[136:139], v[52:55]
	v_mfma_f32_16x16x32_bf16 v[48:51], v[112:115], v[136:139], v[48:51]
	v_mfma_f32_16x16x32_bf16 v[36:39], v[88:91], v[160:163], v[36:39]
	v_mfma_f32_16x16x32_bf16 v[32:35], v[112:115], v[160:163], v[32:35]
	v_mfma_f32_16x16x32_bf16 v[20:23], v[88:91], v[176:179], v[20:23]
	v_mfma_f32_16x16x32_bf16 v[16:19], v[112:115], v[176:179], v[16:19]
	v_mfma_f32_16x16x32_bf16 v[4:7], v[88:91], v[184:187], v[4:7]
	v_mfma_f32_16x16x32_bf16 v[0:3], v[112:115], v[184:187], v[0:3]
	v_mfma_f32_16x16x32_bf16 v[52:55], v[100:103], v[144:147], v[52:55]
	v_mfma_f32_16x16x32_bf16 v[48:51], v[124:127], v[144:147], v[48:51]
	v_mfma_f32_16x16x32_bf16 v[36:39], v[100:103], v[164:167], v[36:39]
	v_mfma_f32_16x16x32_bf16 v[32:35], v[124:127], v[164:167], v[32:35]
	v_mfma_f32_16x16x32_bf16 v[20:23], v[100:103], v[180:183], v[20:23]
	v_mfma_f32_16x16x32_bf16 v[16:19], v[124:127], v[180:183], v[16:19]
	v_mfma_f32_16x16x32_bf16 v[4:7], v[100:103], v[188:191], v[4:7]
	v_mfma_f32_16x16x32_bf16 v[0:3], v[124:127], v[188:191], v[0:3]
	s_setprio 0
	s_barrier
	s_add_i32 s76, s76, 2
	s_add_u32 s60, s60, 0x100
	s_addc_u32 s61, s61, 0
	s_add_u32 s74, s74, 0x100
	s_addc_u32 s75, s75, 0
	s_cmp_gt_u32 s76, 13
	s_cbranch_scc0 .LBB0_592
	s_and_b64 vcc, exec, s[36:37]
	s_cbranch_vccz .LBB0_595
	s_barrier

; #define PG8_STAGE(bufoff, gbase, voff) do { _Pragma("unroll") for (int _i = 0; _i < 2; ++_i) \
;         { unsigned _vo = (voff)[_i]; asm volatile("" : "+v"(_vo));     \
;         __builtin_amdgcn_global_load_lds((const unsigned*)((const char*)(gbase) + _vo), (PG8_LAS unsigned*)(lds + (bufoff) + ldsw + _i * 8192), 16, 0, 0); } } while (0)
; #define PG8_LDA(dst, b, h) do { _Pragma("unroll") for (int m = 0; m < 4; ++m) _Pragma("unroll") for (int k = 0; k < 2; ++k) dst[m][k] = *(const PG8_LAS bf16x8*)(lds + PG8_SA(b, h) + aoff + m * 2048 + k * 1024); } while (0)
; #define PG8_LDB(dst, b, h) do { _Pragma("unroll") for (int n = 0; n < 2; ++n) _Pragma("unroll") for (int k = 0; k < 2; ++k) dst[n][k] = *(const PG8_LAS bf16x8*)(lds + PG8_SB(b, h) + boff + n * 2048 + k * 1024); } while (0)
; #define PG8_WAIT_V(n) asm volatile("s_waitcnt vmcnt(" #n ")" ::: "memory")
; #define PG8_WAIT_L(n) asm volatile("s_waitcnt lgkmcnt(" #n ")" ::: "memory")
; #define PG8_BAR __builtin_amdgcn_s_barrier()
; #define PG8_SCHED __builtin_amdgcn_sched_barrier(0)
; template <class Epi, class Sched, bool ALIGN_EPI = false, bool SP2 = false, bool ABLK = false, bool F8 = false>
; __device__ __forceinline__ void gemm_phase(PG8_LAS unsigned char* lds, const Gemm g, const Sched& S, const Epi& E, const int wave_s) {
;     ...
;             PG8_LDB(B0, 0, 0); PG8_LDB(B1, 0, 1); PG8_SCHED; PG8_LDA(At, 0, 0); PG8_STAGE(PG8_SA(1, 1), a1 + hstepA, voffA);
;             PG8_WAIT_V(8); PG8_WAIT_L(0); PG8_BAR; PG8_MMA(0, 0, At, B0); PG8_MMA(0, 1, At, B1); PG8_BAR; PG8_SCHED;
;             PG8_LDA(At, 0, 1); PG8_STAGE(PG8_SB(0, 0), b2, voffB); PG8_STAGE(PG8_SB(0, 1), b2 + hstep, voffB); PG8_STAGE(PG8_SA(0, 0), a2, voffA);
;             PG8_WAIT_V(8); PG8_WAIT_L(0); PG8_BAR; PG8_MMA(1, 0, At, B0); PG8_MMA(1, 1, At, B1); PG8_BAR; PG8_SCHED;
.LBB0_686:
	v_add_u32_e32 v0, s47, v166
	s_waitcnt lgkmcnt(0)
	ds_read_b128 v[136:139], v0
	ds_read_b128 v[140:143], v0 offset:1024
	ds_read_b128 v[144:147], v0 offset:2048
	ds_read_b128 v[148:151], v0 offset:3072
	v_add_u32_e32 v0, s74, v166
	ds_read_b128 v[152:155], v0
	ds_read_b128 v[156:159], v0 offset:1024
	ds_read_b128 v[172:175], v0 offset:2048
	ds_read_b128 v[176:179], v0 offset:3072
	s_add_u32 s64, s62, 0xfff80080
	s_addc_u32 s65, s63, -1
	s_cmp_eq_u32 s81, 12
	s_cselect_b32 s65, s13, s65
	s_cselect_b32 s64, s57, s64
	s_cselect_b32 s67, s55, s80
	s_cselect_b32 s66, s78, s79
	v_mov_b32_e32 v0, v162
	ds_read_b128 v[180:183], v167
	ds_read_b128 v[184:187], v167 offset:1024
	ds_read_b128 v[188:191], v167 offset:2048
	ds_read_b128 v[192:195], v167 offset:3072
	ds_read_b128 v[196:199], v167 offset:4096
	ds_read_b128 v[200:203], v167 offset:5120
	ds_read_b128 v[204:207], v167 offset:6144
	ds_read_b128 v[208:211], v167 offset:7168
	s_add_i32 m0, s20, 0xc000
	s_nop 0
	global_load_lds_dwordx4 v0, s[62:63]
	v_mov_b32_e32 v0, v164
	s_add_i32 m0, s20, 0xe000
	s_nop 0
	global_load_lds_dwordx4 v0, s[62:63]
	s_waitcnt vmcnt(8)
	s_waitcnt lgkmcnt(0)
	s_barrier
	s_setprio 1
	s_waitcnt lgkmcnt(0)
	v_mfma_f32_16x16x32_bf16 v[128:131], v[136:139], v[180:183], v[128:131]
	v_mfma_f32_16x16x32_bf16 v[124:127], v[144:147], v[180:183], v[124:127]
	v_mfma_f32_16x16x32_bf16 v[120:123], v[136:139], v[188:191], v[120:123]
	v_mfma_f32_16x16x32_bf16 v[116:119], v[144:147], v[188:191], v[116:119]
	v_mfma_f32_16x16x32_bf16 v[112:115], v[136:139], v[196:199], v[112:115]
	v_mfma_f32_16x16x32_bf16 v[108:111], v[144:147], v[196:199], v[108:111]
	v_mfma_f32_16x16x32_bf16 v[104:107], v[136:139], v[204:207], v[104:107]
	v_mfma_f32_16x16x32_bf16 v[100:103], v[144:147], v[204:207], v[100:103]
	v_mfma_f32_16x16x32_bf16 v[128:131], v[140:143], v[184:187], v[128:131]
	v_mfma_f32_16x16x32_bf16 v[124:127], v[148:151], v[184:187], v[124:127]
	v_mfma_f32_16x16x32_bf16 v[120:123], v[140:143], v[192:195], v[120:123]
	v_mfma_f32_16x16x32_bf16 v[116:119], v[148:151], v[192:195], v[116:119]
	v_mfma_f32_16x16x32_bf16 v[112:115], v[140:143], v[200:203], v[112:115]
	v_mfma_f32_16x16x32_bf16 v[108:111], v[148:151], v[200:203], v[108:111]
	v_mfma_f32_16x16x32_bf16 v[104:107], v[140:143], v[208:211], v[104:107]
	v_mfma_f32_16x16x32_bf16 v[100:103], v[148:151], v[208:211], v[100:103]
	s_setprio 0
	s_setprio 1
	v_mfma_f32_16x16x32_bf16 v[92:95], v[152:155], v[180:183], v[92:95]
	v_mfma_f32_16x16x32_bf16 v[84:87], v[172:175], v[180:183], v[84:87]
	v_mfma_f32_16x16x32_bf16 v[76:79], v[152:155], v[188:191], v[76:79]
	v_mfma_f32_16x16x32_bf16 v[68:71], v[172:175], v[188:191], v[68:71]
	v_mfma_f32_16x16x32_bf16 v[60:63], v[152:155], v[196:199], v[60:63]
	v_mfma_f32_16x16x32_bf16 v[52:55], v[172:175], v[196:199], v[52:55]
	v_mfma_f32_16x16x32_bf16 v[44:47], v[152:155], v[204:207], v[44:47]
	v_mfma_f32_16x16x32_bf16 v[36:39], v[172:175], v[204:207], v[36:39]
	v_mfma_f32_16x16x32_bf16 v[92:95], v[156:159], v[184:187], v[92:95]
	v_mfma_f32_16x16x32_bf16 v[84:87], v[176:179], v[184:187], v[84:87]
	v_mfma_f32_16x16x32_bf16 v[76:79], v[156:159], v[192:195], v[76:79]
	v_mfma_f32_16x16x32_bf16 v[68:71], v[176:179], v[192:195], v[68:71]
	v_mfma_f32_16x16x32_bf16 v[60:63], v[156:159], v[200:203], v[60:63]
	v_mfma_f32_16x16x32_bf16 v[52:55], v[176:179], v[200:203], v[52:55]
	v_mfma_f32_16x16x32_bf16 v[44:47], v[156:159], v[208:211], v[44:47]
	v_mfma_f32_16x16x32_bf16 v[36:39], v[176:179], v[208:211], v[36:39]
	s_setprio 0
	s_barrier
	v_mov_b32_e32 v0, v163
	s_add_i32 s72, s47, s3
	ds_read_b128 v[180:183], v167 offset:16384
	ds_read_b128 v[184:187], v167 offset:17408
	ds_read_b128 v[188:191], v167 offset:18432
	ds_read_b128 v[192:195], v167 offset:19456
	ds_read_b128 v[196:199], v167 offset:20480
	ds_read_b128 v[200:203], v167 offset:21504
	ds_read_b128 v[204:207], v167 offset:22528
	ds_read_b128 v[208:211], v167 offset:23552
	s_mov_b32 m0, s72
	s_nop 0
	global_load_lds_dwordx4 v0, s[66:67]
	v_mov_b32_e32 v0, v165
	s_add_i32 m0, s72, 0x2000
	s_add_u32 s72, s66, 0x80000
	global_load_lds_dwordx4 v0, s[66:67]
	s_addc_u32 s73, s67, 0
	v_mov_b32_e32 v0, v163
	s_add_i32 s82, s74, s3
	s_mov_b32 m0, s82
	s_nop 0
	global_load_lds_dwordx4 v0, s[72:73]
	v_mov_b32_e32 v0, v165
	s_add_i32 m0, s82, 0x2000
	s_nop 0
	global_load_lds_dwordx4 v0, s[72:73]
	v_mov_b32_e32 v0, v162
	s_mov_b32 m0, s20
	s_nop 0
	global_load_lds_dwordx4 v0, s[64:65]
	v_mov_b32_e32 v0, v164
	s_mov_b32 m0, s21
	s_nop 0
	global_load_lds_dwordx4 v0, s[64:65]
	s_waitcnt vmcnt(8)
	s_waitcnt lgkmcnt(0)
	s_barrier
; #define PG8_STAGE(bufoff, gbase, voff) do { _Pragma("unroll") for (int _i = 0; _i < 2; ++_i) \
;         { unsigned _vo = (voff)[_i]; asm volatile("" : "+v"(_vo));     \
;         __builtin_amdgcn_global_load_lds((const unsigned*)((const char*)(gbase) + _vo), (PG8_LAS unsigned*)(lds + (bufoff) + ldsw + _i * 8192), 16, 0, 0); } } while (0)
; #define PG8_LDA(dst, b, h) do { _Pragma("unroll") for (int m = 0; m < 4; ++m) _Pragma("unroll") for (int k = 0; k < 2; ++k) dst[m][k] = *(const PG8_LAS bf16x8*)(lds + PG8_SA(b, h) + aoff + m * 2048 + k * 1024); } while (0)
; #define PG8_LDB(dst, b, h) do { _Pragma("unroll") for (int n = 0; n < 2; ++n) _Pragma("unroll") for (int k = 0; k < 2; ++k) dst[n][k] = *(const PG8_LAS bf16x8*)(lds + PG8_SB(b, h) + boff + n * 2048 + k * 1024); } while (0)
; #define PG8_WAIT_V(n) asm volatile("s_waitcnt vmcnt(" #n ")" ::: "memory")
; #define PG8_WAIT_L(n) asm volatile("s_waitcnt lgkmcnt(" #n ")" ::: "memory")
; #define PG8_BAR __builtin_amdgcn_s_barrier()
; #define PG8_SCHED __builtin_amdgcn_sched_barrier(0)
; template <class Epi, class Sched, bool ALIGN_EPI = false, bool SP2 = false, bool ABLK = false, bool F8 = false>
; __device__ __forceinline__ void gemm_phase(PG8_LAS unsigned char* lds, const Gemm g, const Sched& S, const Epi& E, const int wave_s) {
;     ...
;             PG8_WAIT_V(8); PG8_WAIT_L(0); PG8_BAR; PG8_MMA(1, 0, At, B0); PG8_MMA(1, 1, At, B1); PG8_BAR; PG8_SCHED;
;             PG8_LDB(B0, 1, 0); PG8_LDB(B1, 1, 1); PG8_SCHED; PG8_LDA(At, 1, 0); PG8_STAGE(PG8_SA(0, 1), a2 + hstepA, voffA);
;             PG8_WAIT_V(8); PG8_WAIT_L(0); PG8_BAR; PG8_MMA(0, 0, At, B0); PG8_MMA(0, 1, At, B1); PG8_BAR; PG8_SCHED;
	s_setprio 1
	s_waitcnt lgkmcnt(0)
	v_mfma_f32_16x16x32_bf16 v[96:99], v[136:139], v[180:183], v[96:99]
	v_mfma_f32_16x16x32_bf16 v[88:91], v[144:147], v[180:183], v[88:91]
	v_mfma_f32_16x16x32_bf16 v[80:83], v[136:139], v[188:191], v[80:83]
	v_mfma_f32_16x16x32_bf16 v[72:75], v[144:147], v[188:191], v[72:75]
	v_mfma_f32_16x16x32_bf16 v[64:67], v[136:139], v[196:199], v[64:67]
	v_mfma_f32_16x16x32_bf16 v[56:59], v[144:147], v[196:199], v[56:59]
	v_mfma_f32_16x16x32_bf16 v[48:51], v[136:139], v[204:207], v[48:51]
	v_mfma_f32_16x16x32_bf16 v[40:43], v[144:147], v[204:207], v[40:43]
	v_mfma_f32_16x16x32_bf16 v[96:99], v[140:143], v[184:187], v[96:99]
	v_mfma_f32_16x16x32_bf16 v[88:91], v[148:151], v[184:187], v[88:91]
	v_mfma_f32_16x16x32_bf16 v[80:83], v[140:143], v[192:195], v[80:83]
	v_mfma_f32_16x16x32_bf16 v[72:75], v[148:151], v[192:195], v[72:75]
	v_mfma_f32_16x16x32_bf16 v[64:67], v[140:143], v[200:203], v[64:67]
	v_mfma_f32_16x16x32_bf16 v[56:59], v[148:151], v[200:203], v[56:59]
	v_mfma_f32_16x16x32_bf16 v[48:51], v[140:143], v[208:211], v[48:51]
	v_mfma_f32_16x16x32_bf16 v[40:43], v[148:151], v[208:211], v[40:43]
	s_setprio 0
	s_setprio 1
	v_mfma_f32_16x16x32_bf16 v[32:35], v[152:155], v[180:183], v[32:35]
	v_mfma_f32_16x16x32_bf16 v[28:31], v[172:175], v[180:183], v[28:31]
	v_mfma_f32_16x16x32_bf16 v[24:27], v[152:155], v[188:191], v[24:27]
	v_mfma_f32_16x16x32_bf16 v[20:23], v[172:175], v[188:191], v[20:23]
	v_mfma_f32_16x16x32_bf16 v[16:19], v[152:155], v[196:199], v[16:19]
	v_mfma_f32_16x16x32_bf16 v[12:15], v[172:175], v[196:199], v[12:15]
	v_mfma_f32_16x16x32_bf16 v[8:11], v[152:155], v[204:207], v[8:11]
	v_mfma_f32_16x16x32_bf16 v[2:5], v[172:175], v[204:207], v[4:7]
	v_mfma_f32_16x16x32_bf16 v[32:35], v[156:159], v[184:187], v[32:35]
	v_mfma_f32_16x16x32_bf16 v[28:31], v[176:179], v[184:187], v[28:31]
	v_mfma_f32_16x16x32_bf16 v[24:27], v[156:159], v[192:195], v[24:27]
	v_mfma_f32_16x16x32_bf16 v[20:23], v[176:179], v[192:195], v[20:23]
	v_mfma_f32_16x16x32_bf16 v[16:19], v[156:159], v[200:203], v[16:19]
	v_mfma_f32_16x16x32_bf16 v[12:15], v[176:179], v[200:203], v[12:15]
	v_mfma_f32_16x16x32_bf16 v[8:11], v[156:159], v[208:211], v[8:11]
	v_mfma_f32_16x16x32_bf16 v[2:5], v[176:179], v[208:211], v[2:5]
	s_setprio 0
	s_barrier
	s_add_i32 s82, 0, 0x18000
	v_add_u32_e32 v0, s82, v166
	s_add_i32 s83, 0, 0x1c000
	ds_read_b128 v[136:139], v0
	ds_read_b128 v[140:143], v0 offset:1024
	ds_read_b128 v[144:147], v0 offset:2048
	ds_read_b128 v[148:151], v0 offset:3072
	v_add_u32_e32 v0, s83, v166
	ds_read_b128 v[152:155], v0
	ds_read_b128 v[156:159], v0 offset:1024
	ds_read_b128 v[172:175], v0 offset:2048
	ds_read_b128 v[176:179], v0 offset:3072
	s_add_u32 s72, s64, 0x80000
	v_mov_b32_e32 v0, v162
	s_mov_b32 m0, s22
	ds_read_b128 v[180:183], v167 offset:32768
	ds_read_b128 v[184:187], v167 offset:33792
	ds_read_b128 v[188:191], v167 offset:34816
	ds_read_b128 v[192:195], v167 offset:35840
	ds_read_b128 v[196:199], v167 offset:36864
	ds_read_b128 v[200:203], v167 offset:37888
	ds_read_b128 v[204:207], v167 offset:38912
	ds_read_b128 v[208:211], v167 offset:39936
	s_addc_u32 s73, s65, 0
	s_nop 0
	global_load_lds_dwordx4 v0, s[72:73]
	v_mov_b32_e32 v0, v164
	s_mov_b32 m0, s23
	s_nop 0
	global_load_lds_dwordx4 v0, s[72:73]
	s_waitcnt vmcnt(8)
	s_waitcnt lgkmcnt(0)
	s_barrier
	s_setprio 1
	s_waitcnt lgkmcnt(0)
	v_mfma_f32_16x16x32_bf16 v[128:131], v[136:139], v[180:183], v[128:131]
	v_mfma_f32_16x16x32_bf16 v[124:127], v[144:147], v[180:183], v[124:127]
	v_mfma_f32_16x16x32_bf16 v[120:123], v[136:139], v[188:191], v[120:123]
	v_mfma_f32_16x16x32_bf16 v[116:119], v[144:147], v[188:191], v[116:119]
	v_mfma_f32_16x16x32_bf16 v[112:115], v[136:139], v[196:199], v[112:115]
	v_mfma_f32_16x16x32_bf16 v[108:111], v[144:147], v[196:199], v[108:111]
	v_mfma_f32_16x16x32_bf16 v[104:107], v[136:139], v[204:207], v[104:107]
	v_mfma_f32_16x16x32_bf16 v[100:103], v[144:147], v[204:207], v[100:103]
	v_mfma_f32_16x16x32_bf16 v[128:131], v[140:143], v[184:187], v[128:131]
	v_mfma_f32_16x16x32_bf16 v[124:127], v[148:151], v[184:187], v[124:127]
	v_mfma_f32_16x16x32_bf16 v[120:123], v[140:143], v[192:195], v[120:123]
	v_mfma_f32_16x16x32_bf16 v[116:119], v[148:151], v[192:195], v[116:119]
	v_mfma_f32_16x16x32_bf16 v[112:115], v[140:143], v[200:203], v[112:115]
	v_mfma_f32_16x16x32_bf16 v[108:111], v[148:151], v[200:203], v[108:111]
	v_mfma_f32_16x16x32_bf16 v[104:107], v[140:143], v[208:211], v[104:107]
	v_mfma_f32_16x16x32_bf16 v[100:103], v[148:151], v[208:211], v[100:103]
	s_setprio 0
	s_setprio 1
	v_mfma_f32_16x16x32_bf16 v[92:95], v[152:155], v[180:183], v[92:95]
	v_mfma_f32_16x16x32_bf16 v[84:87], v[172:175], v[180:183], v[84:87]
	v_mfma_f32_16x16x32_bf16 v[76:79], v[152:155], v[188:191], v[76:79]
	v_mfma_f32_16x16x32_bf16 v[68:71], v[172:175], v[188:191], v[68:71]
	v_mfma_f32_16x16x32_bf16 v[60:63], v[152:155], v[196:199], v[60:63]
	v_mfma_f32_16x16x32_bf16 v[52:55], v[172:175], v[196:199], v[52:55]
	v_mfma_f32_16x16x32_bf16 v[44:47], v[152:155], v[204:207], v[44:47]
	v_mfma_f32_16x16x32_bf16 v[36:39], v[172:175], v[204:207], v[36:39]
	v_mfma_f32_16x16x32_bf16 v[92:95], v[156:159], v[184:187], v[92:95]
	v_mfma_f32_16x16x32_bf16 v[84:87], v[176:179], v[184:187], v[84:87]
	v_mfma_f32_16x16x32_bf16 v[76:79], v[156:159], v[192:195], v[76:79]
	v_mfma_f32_16x16x32_bf16 v[68:71], v[176:179], v[192:195], v[68:71]
	v_mfma_f32_16x16x32_bf16 v[60:63], v[156:159], v[200:203], v[60:63]
	v_mfma_f32_16x16x32_bf16 v[52:55], v[176:179], v[200:203], v[52:55]
	v_mfma_f32_16x16x32_bf16 v[44:47], v[156:159], v[208:211], v[44:47]
	v_mfma_f32_16x16x32_bf16 v[36:39], v[176:179], v[208:211], v[36:39]
	s_setprio 0
	s_barrier
; #define PG8_STAGE(bufoff, gbase, voff) do { _Pragma("unroll") for (int _i = 0; _i < 2; ++_i) \
;         { unsigned _vo = (voff)[_i]; asm volatile("" : "+v"(_vo));     \
;         __builtin_amdgcn_global_load_lds((const unsigned*)((const char*)(gbase) + _vo), (PG8_LAS unsigned*)(lds + (bufoff) + ldsw + _i * 8192), 16, 0, 0); } } while (0)
; #define PG8_LDA(dst, b, h) do { _Pragma("unroll") for (int m = 0; m < 4; ++m) _Pragma("unroll") for (int k = 0; k < 2; ++k) dst[m][k] = *(const PG8_LAS bf16x8*)(lds + PG8_SA(b, h) + aoff + m * 2048 + k * 1024); } while (0)
; #define PG8_WAIT_V(n) asm volatile("s_waitcnt vmcnt(" #n ")" ::: "memory")
; #define PG8_WAIT_L(n) asm volatile("s_waitcnt lgkmcnt(" #n ")" ::: "memory")
; #define PG8_BAR __builtin_amdgcn_s_barrier()
; #define PG8_SCHED __builtin_amdgcn_sched_barrier(0)
; template <class Epi, class Sched, bool ALIGN_EPI = false, bool SP2 = false, bool ABLK = false, bool F8 = false>
; __device__ __forceinline__ void gemm_phase(PG8_LAS unsigned char* lds, const Gemm g, const Sched& S, const Epi& E, const int wave_s) {
;     ...
;         for (int t = 0; t < nt; t += 2) {
;             const bool last = (t == nt - 2);
;             const char* a1 = cA + (size_t)(t + 1) * kstepA;
;             const char* a2 = last ? nA : cA + (size_t)(t + 2) * kstepA; const char* b2 = last ? nB : cB + (size_t)(t + 2) * kstep;
;             const char* a3 = a2 + kstepA; const char* b3 = b2 + kstep;
;     ...
;             PG8_LDA(At, 1, 1); PG8_STAGE(PG8_SB(1, 0), b3, voffB); PG8_STAGE(PG8_SB(1, 1), b3 + hstep, voffB); PG8_STAGE(PG8_SA(1, 0), a3, voffA);
;             PG8_WAIT_V(8); PG8_WAIT_L(0); PG8_BAR; PG8_MMA(1, 0, At, B0); PG8_MMA(1, 1, At, B1); PG8_BAR; PG8_SCHED;
;     ...
;         if constexpr (ALIGN_EPI) { if (wr == 0) PG8_BAR; }
	v_mov_b32_e32 v0, v163
	ds_read_b128 v[180:183], v167 offset:49152
	ds_read_b128 v[184:187], v167 offset:50176
	ds_read_b128 v[188:191], v167 offset:51200
	ds_read_b128 v[192:195], v167 offset:52224
	ds_read_b128 v[196:199], v167 offset:53248
	ds_read_b128 v[200:203], v167 offset:54272
	ds_read_b128 v[204:207], v167 offset:55296
	ds_read_b128 v[208:211], v167 offset:56320
	s_add_i32 s72, s82, s3
	v_lshl_add_u64 v[6:7], s[66:67], 0, v[0:1]
	v_lshl_add_u64 v[6:7], v[6:7], 0, s[50:51]
	s_mov_b32 m0, s72
	v_mov_b32_e32 v0, v165
	global_load_lds_dwordx4 v[6:7], off
	s_add_i32 m0, s72, 0x2000
	s_nop 0
	v_lshl_add_u64 v[6:7], s[66:67], 0, v[0:1]
	s_add_u32 s66, s66, 0x80080
	v_lshl_add_u64 v[6:7], v[6:7], 0, s[50:51]
	s_addc_u32 s67, s67, 0
	v_mov_b32_e32 v0, v163
	s_add_i32 s72, s83, s3
	global_load_lds_dwordx4 v[6:7], off
	s_mov_b32 m0, s72
	s_nop 0
	global_load_lds_dwordx4 v0, s[66:67]
	v_mov_b32_e32 v0, v165
	s_add_i32 m0, s72, 0x2000
	s_nop 0
	global_load_lds_dwordx4 v0, s[66:67]
	v_mov_b32_e32 v0, v162
	s_mov_b32 m0, s33
	v_lshl_add_u64 v[6:7], s[64:65], 0, v[0:1]
	v_lshl_add_u64 v[6:7], v[6:7], 0, s[50:51]
	v_mov_b32_e32 v0, v164
	global_load_lds_dwordx4 v[6:7], off
	s_mov_b32 m0, s46
	v_lshl_add_u64 v[6:7], s[64:65], 0, v[0:1]
	v_lshl_add_u64 v[6:7], v[6:7], 0, s[50:51]
	global_load_lds_dwordx4 v[6:7], off
	s_waitcnt vmcnt(8)
	s_waitcnt lgkmcnt(0)
	s_barrier
	s_setprio 1
	s_waitcnt lgkmcnt(0)
	v_mfma_f32_16x16x32_bf16 v[96:99], v[136:139], v[180:183], v[96:99]
	v_mfma_f32_16x16x32_bf16 v[88:91], v[144:147], v[180:183], v[88:91]
	v_mfma_f32_16x16x32_bf16 v[80:83], v[136:139], v[188:191], v[80:83]
	v_mfma_f32_16x16x32_bf16 v[72:75], v[144:147], v[188:191], v[72:75]
	v_mfma_f32_16x16x32_bf16 v[64:67], v[136:139], v[196:199], v[64:67]
	v_mfma_f32_16x16x32_bf16 v[56:59], v[144:147], v[196:199], v[56:59]
	v_mfma_f32_16x16x32_bf16 v[48:51], v[136:139], v[204:207], v[48:51]
	v_mfma_f32_16x16x32_bf16 v[40:43], v[144:147], v[204:207], v[40:43]
	v_mfma_f32_16x16x32_bf16 v[96:99], v[140:143], v[184:187], v[96:99]
	v_mfma_f32_16x16x32_bf16 v[88:91], v[148:151], v[184:187], v[88:91]
	v_mfma_f32_16x16x32_bf16 v[80:83], v[140:143], v[192:195], v[80:83]
	v_mfma_f32_16x16x32_bf16 v[72:75], v[148:151], v[192:195], v[72:75]
	v_mfma_f32_16x16x32_bf16 v[64:67], v[140:143], v[200:203], v[64:67]
	v_mfma_f32_16x16x32_bf16 v[56:59], v[148:151], v[200:203], v[56:59]
	v_mfma_f32_16x16x32_bf16 v[48:51], v[140:143], v[208:211], v[48:51]
	v_mfma_f32_16x16x32_bf16 v[40:43], v[148:151], v[208:211], v[40:43]
	s_setprio 0
	s_setprio 1
	v_mfma_f32_16x16x32_bf16 v[32:35], v[152:155], v[180:183], v[32:35]
	v_mfma_f32_16x16x32_bf16 v[28:31], v[172:175], v[180:183], v[28:31]
	v_mfma_f32_16x16x32_bf16 v[24:27], v[152:155], v[188:191], v[24:27]
	v_mfma_f32_16x16x32_bf16 v[20:23], v[172:175], v[188:191], v[20:23]
	v_mfma_f32_16x16x32_bf16 v[16:19], v[152:155], v[196:199], v[16:19]
	v_mfma_f32_16x16x32_bf16 v[12:15], v[172:175], v[196:199], v[12:15]
	v_mfma_f32_16x16x32_bf16 v[6:9], v[152:155], v[204:207], v[8:11]
	v_mfma_f32_16x16x32_bf16 v[2:5], v[172:175], v[204:207], v[2:5]
	v_mfma_f32_16x16x32_bf16 v[32:35], v[156:159], v[184:187], v[32:35]
	v_mfma_f32_16x16x32_bf16 v[28:31], v[176:179], v[184:187], v[28:31]
	v_mfma_f32_16x16x32_bf16 v[24:27], v[156:159], v[192:195], v[24:27]
	v_mfma_f32_16x16x32_bf16 v[20:23], v[176:179], v[192:195], v[20:23]
	v_mfma_f32_16x16x32_bf16 v[16:19], v[156:159], v[200:203], v[16:19]
	v_mfma_f32_16x16x32_bf16 v[12:15], v[176:179], v[200:203], v[12:15]
	v_mfma_f32_16x16x32_bf16 v[8:11], v[156:159], v[208:211], v[6:9]
	v_mfma_f32_16x16x32_bf16 v[4:7], v[176:179], v[208:211], v[2:5]
	s_setprio 0
	s_barrier
	s_add_i32 s81, s81, 2
	s_add_u32 s62, s62, 0x100
	s_addc_u32 s63, s63, 0
	s_add_u32 s79, s79, 0x100
	s_addc_u32 s80, s80, 0
	s_cmp_gt_u32 s81, 13
	s_cbranch_scc0 .LBB0_686
	s_and_b64 vcc, exec, s[36:37]
	s_cbranch_vccz .LBB0_689
	s_barrier

; #define PG8_STAGE(bufoff, gbase, voff) do { _Pragma("unroll") for (int _i = 0; _i < 2; ++_i) \
;         { unsigned _vo = (voff)[_i]; asm volatile("" : "+v"(_vo));     \
;         __builtin_amdgcn_global_load_lds((const unsigned*)((const char*)(gbase) + _vo), (PG8_LAS unsigned*)(lds + (bufoff) + ldsw + _i * 8192), 16, 0, 0); } } while (0)
; #define PG8_LDA(dst, b, h) do { _Pragma("unroll") for (int m = 0; m < 4; ++m) _Pragma("unroll") for (int k = 0; k < 2; ++k) dst[m][k] = *(const PG8_LAS bf16x8*)(lds + PG8_SA(b, h) + aoff + m * 2048 + k * 1024); } while (0)
; #define PG8_LDB(dst, b, h) do { _Pragma("unroll") for (int n = 0; n < 2; ++n) _Pragma("unroll") for (int k = 0; k < 2; ++k) dst[n][k] = *(const PG8_LAS bf16x8*)(lds + PG8_SB(b, h) + boff + n * 2048 + k * 1024); } while (0)
; #define PG8_WAIT_V(n) asm volatile("s_waitcnt vmcnt(" #n ")" ::: "memory")
; #define PG8_WAIT_L(n) asm volatile("s_waitcnt lgkmcnt(" #n ")" ::: "memory")
; #define PG8_BAR __builtin_amdgcn_s_barrier()
; #define PG8_SCHED __builtin_amdgcn_sched_barrier(0)
; template <class Epi, class Sched, bool ALIGN_EPI = false, bool SP2 = false, bool ABLK = false, bool F8 = false>
; __device__ __forceinline__ void gemm_phase(PG8_LAS unsigned char* lds, const Gemm g, const Sched& S, const Epi& E, const int wave_s) {
;     ...
;             PG8_LDB(B0, 0, 0); PG8_LDB(B1, 0, 1); PG8_SCHED; PG8_LDA(At, 0, 0); PG8_STAGE(PG8_SA(1, 1), a1 + hstepA, voffA);
;             PG8_WAIT_V(8); PG8_WAIT_L(0); PG8_BAR; PG8_MMA(0, 0, At, B0); PG8_MMA(0, 1, At, B1); PG8_BAR; PG8_SCHED;
;             PG8_LDA(At, 0, 1); PG8_STAGE(PG8_SB(0, 0), b2, voffB); PG8_STAGE(PG8_SB(0, 1), b2 + hstep, voffB); PG8_STAGE(PG8_SA(0, 0), a2, voffA);
;             PG8_WAIT_V(8); PG8_WAIT_L(0); PG8_BAR; PG8_MMA(1, 0, At, B0); PG8_MMA(1, 1, At, B1); PG8_BAR; PG8_SCHED;
;             PG8_LDB(B0, 1, 0); PG8_LDB(B1, 1, 1); PG8_SCHED; PG8_LDA(At, 1, 0); PG8_STAGE(PG8_SA(0, 1), a2 + hstepA, voffA);
;             PG8_WAIT_V(8); PG8_WAIT_L(0); PG8_BAR; PG8_MMA(0, 0, At, B0); PG8_MMA(0, 1, At, B1); PG8_BAR; PG8_SCHED;
.LBB0_810:
	v_add_u32_e32 v128, s61, v142
	ds_read_b128 v[148:151], v128
	ds_read_b128 v[152:155], v128 offset:1024
	ds_read_b128 v[156:159], v128 offset:2048
	ds_read_b128 v[160:163], v128 offset:3072
	v_add_u32_e32 v128, s62, v142
	ds_read_b128 v[164:167], v128
	ds_read_b128 v[168:171], v128 offset:1024
	ds_read_b128 v[172:175], v128 offset:2048
	ds_read_b128 v[176:179], v128 offset:3072
	s_add_u32 s58, s54, 0xfffc0080
	s_addc_u32 s59, s55, -1
	s_and_b64 s[56:57], s[56:57], exec
	s_cselect_b32 s57, s59, s43
	s_cselect_b32 s56, s58, s66
	s_cselect_b32 s59, s73, s41
	s_cselect_b32 s58, s72, s67
	v_mov_b32_e32 v128, v147
	ds_read_b128 v[180:183], v143
	ds_read_b128 v[184:187], v143 offset:1024
	ds_read_b128 v[188:191], v143 offset:2048
	ds_read_b128 v[192:195], v143 offset:3072
	ds_read_b128 v[196:199], v143 offset:4096
	ds_read_b128 v[200:203], v143 offset:5120
	ds_read_b128 v[204:207], v143 offset:6144
	ds_read_b128 v[208:211], v143 offset:7168
	s_add_i32 m0, s20, 0xc000
	s_nop 0
	global_load_lds_dwordx4 v128, s[54:55]
	v_mov_b32_e32 v128, v140
	s_add_i32 m0, s20, 0xe000
	s_nop 0
	global_load_lds_dwordx4 v128, s[54:55]
	s_waitcnt vmcnt(8)
	s_waitcnt lgkmcnt(0)
	s_barrier
	s_setprio 1
	s_waitcnt lgkmcnt(0)
	v_mfma_scale_f32_16x16x128_f8f6f4 v[124:127], v[148:155], v[180:187], v[124:127], v144, v144 op_sel_hi:[0,0,0]
	v_mfma_scale_f32_16x16x128_f8f6f4 v[116:119], v[156:163], v[180:187], v[116:119], v144, v144 op_sel_hi:[0,0,0]
	v_mfma_scale_f32_16x16x128_f8f6f4 v[108:111], v[148:155], v[188:195], v[108:111], v144, v144 op_sel_hi:[0,0,0]
	v_mfma_scale_f32_16x16x128_f8f6f4 v[100:103], v[156:163], v[188:195], v[100:103], v144, v144 op_sel_hi:[0,0,0]
	v_mfma_scale_f32_16x16x128_f8f6f4 v[212:215], v[148:155], v[196:203], v[92:95], v144, v144 op_sel_hi:[0,0,0]
	v_mfma_scale_f32_16x16x128_f8f6f4 v[216:219], v[156:163], v[196:203], v[84:87], v144, v144 op_sel_hi:[0,0,0]
	v_mfma_scale_f32_16x16x128_f8f6f4 v[220:223], v[148:155], v[204:211], v[76:79], v144, v144 op_sel_hi:[0,0,0]
	v_mfma_scale_f32_16x16x128_f8f6f4 v[224:227], v[156:163], v[204:211], v[68:71], v144, v144 op_sel_hi:[0,0,0]
	s_setprio 0
	s_setprio 1
	v_mfma_scale_f32_16x16x128_f8f6f4 v[120:123], v[164:171], v[180:187], v[120:123], v144, v144 op_sel_hi:[0,0,0]
	v_mfma_scale_f32_16x16x128_f8f6f4 v[112:115], v[172:179], v[180:187], v[112:115], v144, v144 op_sel_hi:[0,0,0]
	v_mfma_scale_f32_16x16x128_f8f6f4 v[104:107], v[164:171], v[188:195], v[104:107], v144, v144 op_sel_hi:[0,0,0]
	v_mfma_scale_f32_16x16x128_f8f6f4 v[96:99], v[172:179], v[188:195], v[96:99], v144, v144 op_sel_hi:[0,0,0]
	v_mfma_scale_f32_16x16x128_f8f6f4 v[180:183], v[164:171], v[196:203], v[88:91], v144, v144 op_sel_hi:[0,0,0]
	v_mfma_scale_f32_16x16x128_f8f6f4 v[184:187], v[172:179], v[196:203], v[80:83], v144, v144 op_sel_hi:[0,0,0]
	v_mfma_scale_f32_16x16x128_f8f6f4 v[188:191], v[164:171], v[204:211], v[72:75], v144, v144 op_sel_hi:[0,0,0]
	v_mfma_scale_f32_16x16x128_f8f6f4 v[192:195], v[172:179], v[204:211], v[64:67], v144, v144 op_sel_hi:[0,0,0]
	s_setprio 0
	s_barrier
	v_mov_b32_e32 v128, v254
	s_add_i32 s76, s61, s3
	s_nop 2
	ds_read_b128 v[64:67], v143 offset:16384
	ds_read_b128 v[68:71], v143 offset:17408
	ds_read_b128 v[72:75], v143 offset:18432
	ds_read_b128 v[76:79], v143 offset:19456
	ds_read_b128 v[80:83], v143 offset:20480
	ds_read_b128 v[84:87], v143 offset:21504
	ds_read_b128 v[88:91], v143 offset:22528
	ds_read_b128 v[92:95], v143 offset:23552
	s_mov_b32 m0, s76
	s_nop 0
	global_load_lds_dwordx4 v128, s[58:59]
	v_mov_b32_e32 v128, v141
	s_add_i32 m0, s76, 0x2000
	s_add_u32 s76, s58, 0x40000
	global_load_lds_dwordx4 v128, s[58:59]
	s_addc_u32 s77, s59, 0
	v_mov_b32_e32 v128, v254
	s_add_i32 s78, s62, s3
	s_mov_b32 m0, s78
	s_nop 0
	global_load_lds_dwordx4 v128, s[76:77]
	v_mov_b32_e32 v128, v141
	s_add_i32 m0, s78, 0x2000
	s_nop 0
	global_load_lds_dwordx4 v128, s[76:77]
	v_mov_b32_e32 v128, v147
	s_mov_b32 m0, s20
	s_nop 0
	global_load_lds_dwordx4 v128, s[56:57]
	v_mov_b32_e32 v128, v140
	s_mov_b32 m0, s21
	s_nop 0
	global_load_lds_dwordx4 v128, s[56:57]
	s_waitcnt vmcnt(8)
	s_waitcnt lgkmcnt(0)
	s_barrier
	s_setprio 1
	s_waitcnt lgkmcnt(0)
	v_mfma_scale_f32_16x16x128_f8f6f4 v[60:63], v[148:155], v[64:71], v[60:63], v144, v144 op_sel_hi:[0,0,0]
	v_mfma_scale_f32_16x16x128_f8f6f4 v[52:55], v[156:163], v[64:71], v[52:55], v144, v144 op_sel_hi:[0,0,0]
	v_mfma_scale_f32_16x16x128_f8f6f4 v[44:47], v[148:155], v[72:79], v[44:47], v144, v144 op_sel_hi:[0,0,0]
	v_mfma_scale_f32_16x16x128_f8f6f4 v[204:207], v[156:163], v[72:79], v[36:39], v144, v144 op_sel_hi:[0,0,0]
	v_mfma_scale_f32_16x16x128_f8f6f4 v[208:211], v[148:155], v[80:87], v[28:31], v144, v144 op_sel_hi:[0,0,0]
	v_mfma_scale_f32_16x16x128_f8f6f4 v[230:233], v[156:163], v[80:87], v[20:23], v144, v144 op_sel_hi:[0,0,0]
	v_mfma_scale_f32_16x16x128_f8f6f4 v[234:237], v[148:155], v[88:95], v[12:15], v144, v144 op_sel_hi:[0,0,0]
	v_mfma_scale_f32_16x16x128_f8f6f4 v[238:241], v[156:163], v[88:95], v[4:7], v144, v144 op_sel_hi:[0,0,0]
	s_setprio 0
	s_setprio 1
	v_mfma_scale_f32_16x16x128_f8f6f4 v[56:59], v[164:171], v[64:71], v[56:59], v144, v144 op_sel_hi:[0,0,0]
	v_mfma_scale_f32_16x16x128_f8f6f4 v[48:51], v[172:179], v[64:71], v[48:51], v144, v144 op_sel_hi:[0,0,0]
	v_mfma_scale_f32_16x16x128_f8f6f4 v[40:43], v[164:171], v[72:79], v[40:43], v144, v144 op_sel_hi:[0,0,0]
	v_mfma_scale_f32_16x16x128_f8f6f4 v[242:245], v[172:179], v[72:79], v[32:35], v144, v144 op_sel_hi:[0,0,0]
	v_mfma_scale_f32_16x16x128_f8f6f4 v[246:249], v[164:171], v[80:87], v[24:27], v144, v144 op_sel_hi:[0,0,0]
	v_mfma_scale_f32_16x16x128_f8f6f4 v[250:253], v[172:179], v[80:87], v[16:19], v144, v144 op_sel_hi:[0,0,0]
	v_mfma_scale_f32_16x16x128_f8f6f4 v[132:135], v[164:171], v[88:95], v[8:11], v144, v144 op_sel_hi:[0,0,0]
	v_mfma_scale_f32_16x16x128_f8f6f4 v[136:139], v[172:179], v[88:95], v[0:3], v144, v144 op_sel_hi:[0,0,0]
	s_setprio 0
	s_barrier
; #define PG8_STAGE(bufoff, gbase, voff) do { _Pragma("unroll") for (int _i = 0; _i < 2; ++_i) \
;         { unsigned _vo = (voff)[_i]; asm volatile("" : "+v"(_vo));     \
;         __builtin_amdgcn_global_load_lds((const unsigned*)((const char*)(gbase) + _vo), (PG8_LAS unsigned*)(lds + (bufoff) + ldsw + _i * 8192), 16, 0, 0); } } while (0)
; #define PG8_LDA(dst, b, h) do { _Pragma("unroll") for (int m = 0; m < 4; ++m) _Pragma("unroll") for (int k = 0; k < 2; ++k) dst[m][k] = *(const PG8_LAS bf16x8*)(lds + PG8_SA(b, h) + aoff + m * 2048 + k * 1024); } while (0)
; #define PG8_LDB(dst, b, h) do { _Pragma("unroll") for (int n = 0; n < 2; ++n) _Pragma("unroll") for (int k = 0; k < 2; ++k) dst[n][k] = *(const PG8_LAS bf16x8*)(lds + PG8_SB(b, h) + boff + n * 2048 + k * 1024); } while (0)
; #define PG8_WAIT_V(n) asm volatile("s_waitcnt vmcnt(" #n ")" ::: "memory")
; #define PG8_WAIT_L(n) asm volatile("s_waitcnt lgkmcnt(" #n ")" ::: "memory")
; #define PG8_BAR __builtin_amdgcn_s_barrier()
; #define PG8_SCHED __builtin_amdgcn_sched_barrier(0)
; template <class Epi, class Sched, bool ALIGN_EPI = false, bool SP2 = false, bool ABLK = false, bool F8 = false>
; __device__ __forceinline__ void gemm_phase(PG8_LAS unsigned char* lds, const Gemm g, const Sched& S, const Epi& E, const int wave_s) {
;     ...
;         for (int t = 0; t < nt; t += 2) {
;             const bool last = (t == nt - 2);
;             const char* a1 = cA + (size_t)(t + 1) * kstepA;
;             const char* a2 = last ? nA : cA + (size_t)(t + 2) * kstepA; const char* b2 = last ? nB : cB + (size_t)(t + 2) * kstep;
;             const char* a3 = a2 + kstepA; const char* b3 = b2 + kstep;
;     ...
;             PG8_LDB(B0, 1, 0); PG8_LDB(B1, 1, 1); PG8_SCHED; PG8_LDA(At, 1, 0); PG8_STAGE(PG8_SA(0, 1), a2 + hstepA, voffA);
;             PG8_WAIT_V(8); PG8_WAIT_L(0); PG8_BAR; PG8_MMA(0, 0, At, B0); PG8_MMA(0, 1, At, B1); PG8_BAR; PG8_SCHED;
;             PG8_LDA(At, 1, 1); PG8_STAGE(PG8_SB(1, 0), b3, voffB); PG8_STAGE(PG8_SB(1, 1), b3 + hstep, voffB); PG8_STAGE(PG8_SA(1, 0), a3, voffA);
;             PG8_WAIT_V(8); PG8_WAIT_L(0); PG8_BAR; PG8_MMA(1, 0, At, B0); PG8_MMA(1, 1, At, B1); PG8_BAR; PG8_SCHED;
	s_add_i32 s78, 0, 0x18000
	s_nop 2
	v_add_u32_e32 v8, s78, v142
	s_add_i32 s79, 0, 0x1c000
	ds_read_b128 v[0:3], v8
	ds_read_b128 v[4:7], v8 offset:1024
	ds_read_b128 v[148:151], v8 offset:2048
	ds_read_b128 v[152:155], v8 offset:3072
	v_add_u32_e32 v8, s79, v142
	ds_read_b128 v[156:159], v8
	ds_read_b128 v[160:163], v8 offset:1024
	ds_read_b128 v[164:167], v8 offset:2048
	ds_read_b128 v[168:171], v8 offset:3072
	s_add_u32 s76, s56, 0x40000
	v_mov_b32_e32 v64, v147
	s_mov_b32 m0, s22
	ds_read_b128 v[8:11], v143 offset:32768
	ds_read_b128 v[12:15], v143 offset:33792
	ds_read_b128 v[16:19], v143 offset:34816
	ds_read_b128 v[20:23], v143 offset:35840
	ds_read_b128 v[24:27], v143 offset:36864
	ds_read_b128 v[28:31], v143 offset:37888
	ds_read_b128 v[32:35], v143 offset:38912
	ds_read_b128 v[36:39], v143 offset:39936
	s_addc_u32 s77, s57, 0
	s_nop 0
	global_load_lds_dwordx4 v64, s[76:77]
	v_mov_b32_e32 v64, v140
	s_mov_b32 m0, s23
	s_nop 0
	global_load_lds_dwordx4 v64, s[76:77]
	s_waitcnt vmcnt(8)
	s_waitcnt lgkmcnt(0)
	s_barrier
	s_setprio 1
	s_waitcnt lgkmcnt(0)
	v_mfma_scale_f32_16x16x128_f8f6f4 v[124:127], v[0:7], v[8:15], v[124:127], v144, v144 op_sel_hi:[0,0,0]
	v_mfma_scale_f32_16x16x128_f8f6f4 v[116:119], v[148:155], v[8:15], v[116:119], v144, v144 op_sel_hi:[0,0,0]
	v_mfma_scale_f32_16x16x128_f8f6f4 v[108:111], v[0:7], v[16:23], v[108:111], v144, v144 op_sel_hi:[0,0,0]
	v_mfma_scale_f32_16x16x128_f8f6f4 v[100:103], v[148:155], v[16:23], v[100:103], v144, v144 op_sel_hi:[0,0,0]
	v_mfma_scale_f32_16x16x128_f8f6f4 v[92:95], v[0:7], v[24:31], v[212:215], v144, v144 op_sel_hi:[0,0,0]
	v_mfma_scale_f32_16x16x128_f8f6f4 v[84:87], v[148:155], v[24:31], v[216:219], v144, v144 op_sel_hi:[0,0,0]
	v_mfma_scale_f32_16x16x128_f8f6f4 v[76:79], v[0:7], v[32:39], v[220:223], v144, v144 op_sel_hi:[0,0,0]
	v_mfma_scale_f32_16x16x128_f8f6f4 v[68:71], v[148:155], v[32:39], v[224:227], v144, v144 op_sel_hi:[0,0,0]
	s_setprio 0
	s_setprio 1
	v_mfma_scale_f32_16x16x128_f8f6f4 v[120:123], v[156:163], v[8:15], v[120:123], v144, v144 op_sel_hi:[0,0,0]
	v_mfma_scale_f32_16x16x128_f8f6f4 v[112:115], v[164:171], v[8:15], v[112:115], v144, v144 op_sel_hi:[0,0,0]
	v_mfma_scale_f32_16x16x128_f8f6f4 v[104:107], v[156:163], v[16:23], v[104:107], v144, v144 op_sel_hi:[0,0,0]
	v_mfma_scale_f32_16x16x128_f8f6f4 v[96:99], v[164:171], v[16:23], v[96:99], v144, v144 op_sel_hi:[0,0,0]
	v_mfma_scale_f32_16x16x128_f8f6f4 v[88:91], v[156:163], v[24:31], v[180:183], v144, v144 op_sel_hi:[0,0,0]
	v_mfma_scale_f32_16x16x128_f8f6f4 v[80:83], v[164:171], v[24:31], v[184:187], v144, v144 op_sel_hi:[0,0,0]
	v_mfma_scale_f32_16x16x128_f8f6f4 v[72:75], v[156:163], v[32:39], v[188:191], v144, v144 op_sel_hi:[0,0,0]
	v_mfma_scale_f32_16x16x128_f8f6f4 v[64:67], v[164:171], v[32:39], v[192:195], v144, v144 op_sel_hi:[0,0,0]
	s_setprio 0
	s_barrier
	v_mov_b32_e32 v128, v254
	ds_read_b128 v[172:175], v143 offset:49152
	ds_read_b128 v[176:179], v143 offset:50176
	ds_read_b128 v[180:183], v143 offset:51200
	ds_read_b128 v[184:187], v143 offset:52224
	ds_read_b128 v[188:191], v143 offset:53248
	ds_read_b128 v[192:195], v143 offset:54272
	ds_read_b128 v[196:199], v143 offset:55296
	ds_read_b128 v[200:203], v143 offset:56320
	s_add_i32 s76, s78, s3
	v_lshl_add_u64 v[8:9], s[58:59], 0, v[128:129]
	v_lshl_add_u64 v[8:9], v[8:9], 0, s[12:13]
	s_mov_b32 m0, s76
	v_mov_b32_e32 v128, v141
	global_load_lds_dwordx4 v[8:9], off
	s_add_i32 m0, s76, 0x2000
	v_lshl_add_u64 v[8:9], s[58:59], 0, v[128:129]
	v_lshl_add_u64 v[8:9], v[8:9], 0, s[12:13]
	s_add_u32 s58, s58, 0x40080
	global_load_lds_dwordx4 v[8:9], off
	s_addc_u32 s59, s59, 0
	v_mov_b32_e32 v8, v254
	s_add_i32 s76, s79, s3
	s_mov_b32 m0, s76
	v_mov_b32_e32 v128, v147
	global_load_lds_dwordx4 v8, s[58:59]
	v_mov_b32_e32 v8, v141
	s_add_i32 m0, s76, 0x2000
	s_nop 0
	global_load_lds_dwordx4 v8, s[58:59]
	s_mov_b32 m0, s33
	v_lshl_add_u64 v[8:9], s[56:57], 0, v[128:129]
	v_lshl_add_u64 v[8:9], v[8:9], 0, s[12:13]
	v_mov_b32_e32 v128, v140
	global_load_lds_dwordx4 v[8:9], off
	s_mov_b32 m0, s51
	v_lshl_add_u64 v[8:9], s[56:57], 0, v[128:129]
	v_lshl_add_u64 v[8:9], v[8:9], 0, s[12:13]
	global_load_lds_dwordx4 v[8:9], off
	s_waitcnt vmcnt(8)
	s_waitcnt lgkmcnt(0)
	s_barrier
	s_setprio 1
	s_waitcnt lgkmcnt(0)
	v_mfma_scale_f32_16x16x128_f8f6f4 v[60:63], v[0:7], v[172:179], v[60:63], v144, v144 op_sel_hi:[0,0,0]
	v_mfma_scale_f32_16x16x128_f8f6f4 v[52:55], v[148:155], v[172:179], v[52:55], v144, v144 op_sel_hi:[0,0,0]
	v_mfma_scale_f32_16x16x128_f8f6f4 v[44:47], v[0:7], v[180:187], v[44:47], v144, v144 op_sel_hi:[0,0,0]
	v_mfma_scale_f32_16x16x128_f8f6f4 v[36:39], v[148:155], v[180:187], v[204:207], v144, v144 op_sel_hi:[0,0,0]
	v_mfma_scale_f32_16x16x128_f8f6f4 v[28:31], v[0:7], v[188:195], v[208:211], v144, v144 op_sel_hi:[0,0,0]
	v_mfma_scale_f32_16x16x128_f8f6f4 v[20:23], v[148:155], v[188:195], v[230:233], v144, v144 op_sel_hi:[0,0,0]
	v_mfma_scale_f32_16x16x128_f8f6f4 v[12:15], v[0:7], v[196:203], v[234:237], v144, v144 op_sel_hi:[0,0,0]
	v_mfma_scale_f32_16x16x128_f8f6f4 v[4:7], v[148:155], v[196:203], v[238:241], v144, v144 op_sel_hi:[0,0,0]
	s_setprio 0
	s_setprio 1
	v_mfma_scale_f32_16x16x128_f8f6f4 v[56:59], v[156:163], v[172:179], v[56:59], v144, v144 op_sel_hi:[0,0,0]
	v_mfma_scale_f32_16x16x128_f8f6f4 v[48:51], v[164:171], v[172:179], v[48:51], v144, v144 op_sel_hi:[0,0,0]
	v_mfma_scale_f32_16x16x128_f8f6f4 v[40:43], v[156:163], v[180:187], v[40:43], v144, v144 op_sel_hi:[0,0,0]
	v_mfma_scale_f32_16x16x128_f8f6f4 v[32:35], v[164:171], v[180:187], v[242:245], v144, v144 op_sel_hi:[0,0,0]
	v_mfma_scale_f32_16x16x128_f8f6f4 v[24:27], v[156:163], v[188:195], v[246:249], v144, v144 op_sel_hi:[0,0,0]
	v_mfma_scale_f32_16x16x128_f8f6f4 v[16:19], v[164:171], v[188:195], v[250:253], v144, v144 op_sel_hi:[0,0,0]
	v_mfma_scale_f32_16x16x128_f8f6f4 v[8:11], v[156:163], v[196:203], v[132:135], v144, v144 op_sel_hi:[0,0,0]
	v_mfma_scale_f32_16x16x128_f8f6f4 v[0:3], v[164:171], v[196:203], v[136:139], v144, v144 op_sel_hi:[0,0,0]
	s_setprio 0
	s_barrier
	s_add_i32 s74, s74, 2
	s_add_u32 s54, s54, 0x100
	s_addc_u32 s55, s55, 0
	s_add_u32 s72, s72, 0x100
	s_addc_u32 s73, s73, 0
	s_cmp_gt_u32 s74, 13
	s_cbranch_scc1 .LBB0_813

; #define PG8_STAGE(bufoff, gbase, voff) do { _Pragma("unroll") for (int _i = 0; _i < 2; ++_i) \
;         { unsigned _vo = (voff)[_i]; asm volatile("" : "+v"(_vo));     \
;         __builtin_amdgcn_global_load_lds((const unsigned*)((const char*)(gbase) + _vo), (PG8_LAS unsigned*)(lds + (bufoff) + ldsw + _i * 8192), 16, 0, 0); } } while (0)
; #define PG8_LDA(dst, b, h) do { _Pragma("unroll") for (int m = 0; m < 4; ++m) _Pragma("unroll") for (int k = 0; k < 2; ++k) dst[m][k] = *(const PG8_LAS bf16x8*)(lds + PG8_SA(b, h) + aoff + m * 2048 + k * 1024); } while (0)
; #define PG8_LDB(dst, b, h) do { _Pragma("unroll") for (int n = 0; n < 2; ++n) _Pragma("unroll") for (int k = 0; k < 2; ++k) dst[n][k] = *(const PG8_LAS bf16x8*)(lds + PG8_SB(b, h) + boff + n * 2048 + k * 1024); } while (0)
; #define PG8_WAIT_V(n) asm volatile("s_waitcnt vmcnt(" #n ")" ::: "memory")
; #define PG8_WAIT_L(n) asm volatile("s_waitcnt lgkmcnt(" #n ")" ::: "memory")
; #define PG8_BAR __builtin_amdgcn_s_barrier()
; #define PG8_SCHED __builtin_amdgcn_sched_barrier(0)
; template <class Epi, class Sched, bool ALIGN_EPI = false, bool SP2 = false, bool ABLK = false, bool F8 = false>
; __device__ __forceinline__ void gemm_phase(PG8_LAS unsigned char* lds, const Gemm g, const Sched& S, const Epi& E, const int wave_s) {
;     ...
;             PG8_LDB(B0, 0, 0); PG8_LDB(B1, 0, 1); PG8_SCHED; PG8_LDA(At, 0, 0); PG8_STAGE(PG8_SA(1, 1), a1 + hstepA, voffA);
;             PG8_WAIT_V(8); PG8_WAIT_L(0); PG8_BAR; PG8_MMA(0, 0, At, B0); PG8_MMA(0, 1, At, B1); PG8_BAR; PG8_SCHED;
;             PG8_LDA(At, 0, 1); PG8_STAGE(PG8_SB(0, 0), b2, voffB); PG8_STAGE(PG8_SB(0, 1), b2 + hstep, voffB); PG8_STAGE(PG8_SA(0, 0), a2, voffA);
;             PG8_WAIT_V(8); PG8_WAIT_L(0); PG8_BAR; PG8_MMA(1, 0, At, B0); PG8_MMA(1, 1, At, B1); PG8_BAR; PG8_SCHED;
.LBB0_894:
	ds_read_b128 v[104:107], v230
	ds_read_b128 v[116:119], v230 offset:1024
	ds_read_b128 v[128:131], v230 offset:2048
	ds_read_b128 v[140:143], v230 offset:3072
	ds_read_b128 v[144:147], v231
	ds_read_b128 v[148:151], v231 offset:1024
	ds_read_b128 v[152:155], v231 offset:2048
	ds_read_b128 v[156:159], v231 offset:3072
	s_add_u32 s46, s44, 0x4000
	s_addc_u32 s47, s45, 0
	s_cmpk_eq_i32 s62, 0x54
	s_cselect_b32 s50, s12, s46
	s_cselect_b32 s51, s13, s47
	s_cselect_b32 s48, s42, s60
	s_cselect_b32 s49, s43, s61
	s_add_u32 s46, s50, 0x8000
	s_addc_u32 s47, s51, 0
	v_mov_b32_e32 v184, v222
	ds_read_b128 v[160:163], v232
	ds_read_b128 v[164:167], v232 offset:1024
	ds_read_b128 v[168:171], v232 offset:2048
	ds_read_b128 v[172:175], v232 offset:3072
	ds_read_b128 v[176:179], v232 offset:4096
	ds_read_b128 v[180:183], v232 offset:5120
	ds_read_b128 v[190:193], v232 offset:6144
	ds_read_b128 v[194:197], v232 offset:7168
	s_add_i32 m0, s20, 0xc000
	s_nop 0
	global_load_lds_dwordx4 v184, s[44:45]
	v_mov_b32_e32 v184, v224
	s_add_i32 m0, s20, 0xe000
	s_nop 0
	global_load_lds_dwordx4 v184, s[44:45]
	s_waitcnt vmcnt(8)
	s_waitcnt lgkmcnt(0)
	s_barrier
	s_setprio 1
	s_waitcnt lgkmcnt(0)
	v_mfma_f32_16x16x32_bf16 v[136:139], v[104:107], v[160:163], v[136:139]
	v_mfma_f32_16x16x32_bf16 v[132:135], v[128:131], v[160:163], v[132:135]
	v_mfma_f32_16x16x32_bf16 v[112:115], v[104:107], v[168:171], v[112:115]
	v_mfma_f32_16x16x32_bf16 v[108:111], v[128:131], v[168:171], v[108:111]
	v_mfma_f32_16x16x32_bf16 v[92:95], v[104:107], v[176:179], v[92:95]
	v_mfma_f32_16x16x32_bf16 v[88:91], v[128:131], v[176:179], v[88:91]
	v_mfma_f32_16x16x32_bf16 v[76:79], v[104:107], v[190:193], v[76:79]
	v_mfma_f32_16x16x32_bf16 v[72:75], v[128:131], v[190:193], v[72:75]
	v_mfma_f32_16x16x32_bf16 v[136:139], v[116:119], v[164:167], v[136:139]
	v_mfma_f32_16x16x32_bf16 v[132:135], v[140:143], v[164:167], v[132:135]
	v_mfma_f32_16x16x32_bf16 v[112:115], v[116:119], v[172:175], v[112:115]
	v_mfma_f32_16x16x32_bf16 v[108:111], v[140:143], v[172:175], v[108:111]
	v_mfma_f32_16x16x32_bf16 v[92:95], v[116:119], v[180:183], v[92:95]
	v_mfma_f32_16x16x32_bf16 v[88:91], v[140:143], v[180:183], v[88:91]
	v_mfma_f32_16x16x32_bf16 v[76:79], v[116:119], v[194:197], v[76:79]
	v_mfma_f32_16x16x32_bf16 v[72:75], v[140:143], v[194:197], v[72:75]
	s_setprio 0
	s_setprio 1
	v_mfma_f32_16x16x32_bf16 v[124:127], v[144:147], v[160:163], v[124:127]
	v_mfma_f32_16x16x32_bf16 v[120:123], v[152:155], v[160:163], v[120:123]
	v_mfma_f32_16x16x32_bf16 v[100:103], v[144:147], v[168:171], v[100:103]
	v_mfma_f32_16x16x32_bf16 v[96:99], v[152:155], v[168:171], v[96:99]
	v_mfma_f32_16x16x32_bf16 v[84:87], v[144:147], v[176:179], v[84:87]
	v_mfma_f32_16x16x32_bf16 v[80:83], v[152:155], v[176:179], v[80:83]
	v_mfma_f32_16x16x32_bf16 v[68:71], v[144:147], v[190:193], v[68:71]
	v_mfma_f32_16x16x32_bf16 v[64:67], v[152:155], v[190:193], v[64:67]
	v_mfma_f32_16x16x32_bf16 v[124:127], v[148:151], v[164:167], v[124:127]
	v_mfma_f32_16x16x32_bf16 v[120:123], v[156:159], v[164:167], v[120:123]
	v_mfma_f32_16x16x32_bf16 v[100:103], v[148:151], v[172:175], v[100:103]
	v_mfma_f32_16x16x32_bf16 v[96:99], v[156:159], v[172:175], v[96:99]
	v_mfma_f32_16x16x32_bf16 v[84:87], v[148:151], v[180:183], v[84:87]
	v_mfma_f32_16x16x32_bf16 v[80:83], v[156:159], v[180:183], v[80:83]
	v_mfma_f32_16x16x32_bf16 v[68:71], v[148:151], v[194:197], v[68:71]
	v_mfma_f32_16x16x32_bf16 v[64:67], v[156:159], v[194:197], v[64:67]
	s_setprio 0
	s_barrier
	v_mov_b32_e32 v184, v223
	s_add_i32 s63, s54, s3
	ds_read_b128 v[160:163], v232 offset:16384
	ds_read_b128 v[164:167], v232 offset:17408
	ds_read_b128 v[168:171], v232 offset:18432
	ds_read_b128 v[172:175], v232 offset:19456
	ds_read_b128 v[176:179], v232 offset:20480
	ds_read_b128 v[180:183], v232 offset:21504
	ds_read_b128 v[190:193], v232 offset:22528
	ds_read_b128 v[194:197], v232 offset:23552
	s_mov_b32 m0, s63
	s_nop 0
	global_load_lds_dwordx4 v184, s[48:49]
	v_mov_b32_e32 v184, v225
	s_add_i32 m0, s63, 0x2000
	s_add_u32 s64, s48, 0x160000
	global_load_lds_dwordx4 v184, s[48:49]
	s_addc_u32 s65, s49, 0
	v_mov_b32_e32 v184, v223
	s_add_i32 s63, s55, s3
	s_mov_b32 m0, s63
	s_nop 0
	global_load_lds_dwordx4 v184, s[64:65]
	v_mov_b32_e32 v184, v225
	s_add_i32 m0, s63, 0x2000
	s_nop 0
	global_load_lds_dwordx4 v184, s[64:65]
	v_mov_b32_e32 v184, v222
	s_mov_b32 m0, s20
	s_nop 0
	global_load_lds_dwordx4 v184, s[50:51]
	v_mov_b32_e32 v184, v224
	s_mov_b32 m0, s21
	s_nop 0
	global_load_lds_dwordx4 v184, s[50:51]
	s_waitcnt vmcnt(8)
	s_waitcnt lgkmcnt(0)
	s_barrier
; #define PG8_STAGE(bufoff, gbase, voff) do { _Pragma("unroll") for (int _i = 0; _i < 2; ++_i) \
;         { unsigned _vo = (voff)[_i]; asm volatile("" : "+v"(_vo));     \
;         __builtin_amdgcn_global_load_lds((const unsigned*)((const char*)(gbase) + _vo), (PG8_LAS unsigned*)(lds + (bufoff) + ldsw + _i * 8192), 16, 0, 0); } } while (0)
; #define PG8_LDA(dst, b, h) do { _Pragma("unroll") for (int m = 0; m < 4; ++m) _Pragma("unroll") for (int k = 0; k < 2; ++k) dst[m][k] = *(const PG8_LAS bf16x8*)(lds + PG8_SA(b, h) + aoff + m * 2048 + k * 1024); } while (0)
; #define PG8_LDB(dst, b, h) do { _Pragma("unroll") for (int n = 0; n < 2; ++n) _Pragma("unroll") for (int k = 0; k < 2; ++k) dst[n][k] = *(const PG8_LAS bf16x8*)(lds + PG8_SB(b, h) + boff + n * 2048 + k * 1024); } while (0)
; #define PG8_WAIT_V(n) asm volatile("s_waitcnt vmcnt(" #n ")" ::: "memory")
; #define PG8_WAIT_L(n) asm volatile("s_waitcnt lgkmcnt(" #n ")" ::: "memory")
; #define PG8_BAR __builtin_amdgcn_s_barrier()
; #define PG8_SCHED __builtin_amdgcn_sched_barrier(0)
; template <class Epi, class Sched, bool ALIGN_EPI = false, bool SP2 = false, bool ABLK = false, bool F8 = false>
; __device__ __forceinline__ void gemm_phase(PG8_LAS unsigned char* lds, const Gemm g, const Sched& S, const Epi& E, const int wave_s) {
;     ...
;             PG8_LDB(B0, 0, 0); PG8_LDB(B1, 0, 1); PG8_SCHED; PG8_LDA(At, 0, 0); PG8_STAGE(PG8_SA(1, 1), a1 + hstepA, voffA);
;             PG8_WAIT_V(8); PG8_WAIT_L(0); PG8_BAR; PG8_MMA(0, 0, At, B0); PG8_MMA(0, 1, At, B1); PG8_BAR; PG8_SCHED;
;             PG8_LDA(At, 0, 1); PG8_STAGE(PG8_SB(0, 0), b2, voffB); PG8_STAGE(PG8_SB(0, 1), b2 + hstep, voffB); PG8_STAGE(PG8_SA(0, 0), a2, voffA);
;             PG8_WAIT_V(8); PG8_WAIT_L(0); PG8_BAR; PG8_MMA(1, 0, At, B0); PG8_MMA(1, 1, At, B1); PG8_BAR; PG8_SCHED;
;             PG8_LDB(B0, 1, 0); PG8_LDB(B1, 1, 1); PG8_SCHED; PG8_LDA(At, 1, 0); PG8_STAGE(PG8_SA(0, 1), a2 + hstepA, voffA);
;             PG8_WAIT_V(8); PG8_WAIT_L(0); PG8_BAR; PG8_MMA(0, 0, At, B0); PG8_MMA(0, 1, At, B1); PG8_BAR; PG8_SCHED;
;             PG8_LDA(At, 1, 1); PG8_STAGE(PG8_SB(1, 0), b3, voffB); PG8_STAGE(PG8_SB(1, 1), b3 + hstep, voffB); PG8_STAGE(PG8_SA(1, 0), a3, voffA);
;             PG8_WAIT_V(8); PG8_WAIT_L(0); PG8_BAR; PG8_MMA(1, 0, At, B0); PG8_MMA(1, 1, At, B1); PG8_BAR; PG8_SCHED;
	s_setprio 1
	s_waitcnt lgkmcnt(0)
	v_mfma_f32_16x16x32_bf16 v[60:63], v[104:107], v[160:163], v[60:63]
	v_mfma_f32_16x16x32_bf16 v[56:59], v[128:131], v[160:163], v[56:59]
	v_mfma_f32_16x16x32_bf16 v[44:47], v[104:107], v[168:171], v[44:47]
	v_mfma_f32_16x16x32_bf16 v[40:43], v[128:131], v[168:171], v[40:43]
	v_mfma_f32_16x16x32_bf16 v[28:31], v[104:107], v[176:179], v[28:31]
	v_mfma_f32_16x16x32_bf16 v[24:27], v[128:131], v[176:179], v[24:27]
	v_mfma_f32_16x16x32_bf16 v[12:15], v[104:107], v[190:193], v[12:15]
	v_mfma_f32_16x16x32_bf16 v[8:11], v[128:131], v[190:193], v[8:11]
	v_mfma_f32_16x16x32_bf16 v[60:63], v[116:119], v[164:167], v[60:63]
	v_mfma_f32_16x16x32_bf16 v[56:59], v[140:143], v[164:167], v[56:59]
	v_mfma_f32_16x16x32_bf16 v[44:47], v[116:119], v[172:175], v[44:47]
	v_mfma_f32_16x16x32_bf16 v[40:43], v[140:143], v[172:175], v[40:43]
	v_mfma_f32_16x16x32_bf16 v[28:31], v[116:119], v[180:183], v[28:31]
	v_mfma_f32_16x16x32_bf16 v[24:27], v[140:143], v[180:183], v[24:27]
	v_mfma_f32_16x16x32_bf16 v[12:15], v[116:119], v[194:197], v[12:15]
	v_mfma_f32_16x16x32_bf16 v[8:11], v[140:143], v[194:197], v[8:11]
	s_setprio 0
	s_setprio 1
	v_mfma_f32_16x16x32_bf16 v[52:55], v[144:147], v[160:163], v[52:55]
	v_mfma_f32_16x16x32_bf16 v[48:51], v[152:155], v[160:163], v[48:51]
	v_mfma_f32_16x16x32_bf16 v[36:39], v[144:147], v[168:171], v[36:39]
	v_mfma_f32_16x16x32_bf16 v[32:35], v[152:155], v[168:171], v[32:35]
	v_mfma_f32_16x16x32_bf16 v[20:23], v[144:147], v[176:179], v[20:23]
	v_mfma_f32_16x16x32_bf16 v[16:19], v[152:155], v[176:179], v[16:19]
	v_mfma_f32_16x16x32_bf16 v[4:7], v[144:147], v[190:193], v[4:7]
	v_mfma_f32_16x16x32_bf16 v[0:3], v[152:155], v[190:193], v[0:3]
	v_mfma_f32_16x16x32_bf16 v[52:55], v[148:151], v[164:167], v[52:55]
	v_mfma_f32_16x16x32_bf16 v[48:51], v[156:159], v[164:167], v[48:51]
	v_mfma_f32_16x16x32_bf16 v[36:39], v[148:151], v[172:175], v[36:39]
	v_mfma_f32_16x16x32_bf16 v[32:35], v[156:159], v[172:175], v[32:35]
	v_mfma_f32_16x16x32_bf16 v[20:23], v[148:151], v[180:183], v[20:23]
	v_mfma_f32_16x16x32_bf16 v[16:19], v[156:159], v[180:183], v[16:19]
	v_mfma_f32_16x16x32_bf16 v[4:7], v[148:151], v[194:197], v[4:7]
	v_mfma_f32_16x16x32_bf16 v[0:3], v[156:159], v[194:197], v[0:3]
	s_setprio 0
	s_barrier
	s_add_i32 s63, 0, 0x18000
	s_add_i32 s64, 0, 0x1c000
	v_add_u32_e32 v140, s63, v227
	v_add_u32_e32 v156, s64, v227
	ds_read_b128 v[104:107], v140
	ds_read_b128 v[116:119], v140 offset:1024
	ds_read_b128 v[128:131], v140 offset:2048
	ds_read_b128 v[140:143], v140 offset:3072
	ds_read_b128 v[144:147], v156
	ds_read_b128 v[148:151], v156 offset:1024
	ds_read_b128 v[152:155], v156 offset:2048
	ds_read_b128 v[156:159], v156 offset:3072
	s_add_u32 s50, s50, 0x4000
	v_mov_b32_e32 v184, v222
	s_mov_b32 m0, s22
	ds_read_b128 v[160:163], v232 offset:32768
	ds_read_b128 v[164:167], v232 offset:33792
	ds_read_b128 v[168:171], v232 offset:34816
	ds_read_b128 v[172:175], v232 offset:35840
	ds_read_b128 v[176:179], v232 offset:36864
	ds_read_b128 v[180:183], v232 offset:37888
	ds_read_b128 v[190:193], v232 offset:38912
	ds_read_b128 v[194:197], v232 offset:39936
	s_addc_u32 s51, s51, 0
	s_nop 0
	global_load_lds_dwordx4 v184, s[50:51]
	v_mov_b32_e32 v184, v224
	s_mov_b32 m0, s23
	s_nop 0
	global_load_lds_dwordx4 v184, s[50:51]
	s_waitcnt vmcnt(8)
	s_waitcnt lgkmcnt(0)
	s_barrier
	s_setprio 1
	s_waitcnt lgkmcnt(0)
	v_mfma_f32_16x16x32_bf16 v[136:139], v[104:107], v[160:163], v[136:139]
	v_mfma_f32_16x16x32_bf16 v[132:135], v[128:131], v[160:163], v[132:135]
	v_mfma_f32_16x16x32_bf16 v[112:115], v[104:107], v[168:171], v[112:115]
	v_mfma_f32_16x16x32_bf16 v[108:111], v[128:131], v[168:171], v[108:111]
	v_mfma_f32_16x16x32_bf16 v[92:95], v[104:107], v[176:179], v[92:95]
	v_mfma_f32_16x16x32_bf16 v[88:91], v[128:131], v[176:179], v[88:91]
	v_mfma_f32_16x16x32_bf16 v[76:79], v[104:107], v[190:193], v[76:79]
	v_mfma_f32_16x16x32_bf16 v[72:75], v[128:131], v[190:193], v[72:75]
	v_mfma_f32_16x16x32_bf16 v[136:139], v[116:119], v[164:167], v[136:139]
	v_mfma_f32_16x16x32_bf16 v[132:135], v[140:143], v[164:167], v[132:135]
	v_mfma_f32_16x16x32_bf16 v[112:115], v[116:119], v[172:175], v[112:115]
	v_mfma_f32_16x16x32_bf16 v[108:111], v[140:143], v[172:175], v[108:111]
	v_mfma_f32_16x16x32_bf16 v[92:95], v[116:119], v[180:183], v[92:95]
	v_mfma_f32_16x16x32_bf16 v[88:91], v[140:143], v[180:183], v[88:91]
	v_mfma_f32_16x16x32_bf16 v[76:79], v[116:119], v[194:197], v[76:79]
	v_mfma_f32_16x16x32_bf16 v[72:75], v[140:143], v[194:197], v[72:75]
	s_setprio 0
	s_setprio 1
	v_mfma_f32_16x16x32_bf16 v[124:127], v[144:147], v[160:163], v[124:127]
	v_mfma_f32_16x16x32_bf16 v[120:123], v[152:155], v[160:163], v[120:123]
	v_mfma_f32_16x16x32_bf16 v[100:103], v[144:147], v[168:171], v[100:103]
	v_mfma_f32_16x16x32_bf16 v[96:99], v[152:155], v[168:171], v[96:99]
	v_mfma_f32_16x16x32_bf16 v[84:87], v[144:147], v[176:179], v[84:87]
	v_mfma_f32_16x16x32_bf16 v[80:83], v[152:155], v[176:179], v[80:83]
	v_mfma_f32_16x16x32_bf16 v[68:71], v[144:147], v[190:193], v[68:71]
	v_mfma_f32_16x16x32_bf16 v[64:67], v[152:155], v[190:193], v[64:67]
	v_mfma_f32_16x16x32_bf16 v[124:127], v[148:151], v[164:167], v[124:127]
	v_mfma_f32_16x16x32_bf16 v[120:123], v[156:159], v[164:167], v[120:123]
	v_mfma_f32_16x16x32_bf16 v[100:103], v[148:151], v[172:175], v[100:103]
	v_mfma_f32_16x16x32_bf16 v[96:99], v[156:159], v[172:175], v[96:99]
	v_mfma_f32_16x16x32_bf16 v[84:87], v[148:151], v[180:183], v[84:87]
	v_mfma_f32_16x16x32_bf16 v[80:83], v[156:159], v[180:183], v[80:83]
	v_mfma_f32_16x16x32_bf16 v[68:71], v[148:151], v[194:197], v[68:71]
	v_mfma_f32_16x16x32_bf16 v[64:67], v[156:159], v[194:197], v[64:67]
	s_setprio 0
	s_barrier
; #define PG8_STAGE(bufoff, gbase, voff) do { _Pragma("unroll") for (int _i = 0; _i < 2; ++_i) \
;         { unsigned _vo = (voff)[_i]; asm volatile("" : "+v"(_vo));     \
;         __builtin_amdgcn_global_load_lds((const unsigned*)((const char*)(gbase) + _vo), (PG8_LAS unsigned*)(lds + (bufoff) + ldsw + _i * 8192), 16, 0, 0); } } while (0)
; #define PG8_LDA(dst, b, h) do { _Pragma("unroll") for (int m = 0; m < 4; ++m) _Pragma("unroll") for (int k = 0; k < 2; ++k) dst[m][k] = *(const PG8_LAS bf16x8*)(lds + PG8_SA(b, h) + aoff + m * 2048 + k * 1024); } while (0)
; #define PG8_BAR __builtin_amdgcn_s_barrier()
; template <class Epi, class Sched, bool ALIGN_EPI = false, bool SP2 = false, bool ABLK = false, bool F8 = false>
; __device__ __forceinline__ void gemm_phase(PG8_LAS unsigned char* lds, const Gemm g, const Sched& S, const Epi& E, const int wave_s) {
;     ...
;         for (int t = 0; t < nt; t += 2) {
;             const bool last = (t == nt - 2);
;             const char* a1 = cA + (size_t)(t + 1) * kstepA;
;             const char* a2 = last ? nA : cA + (size_t)(t + 2) * kstepA; const char* b2 = last ? nB : cB + (size_t)(t + 2) * kstep;
;             const char* a3 = a2 + kstepA; const char* b3 = b2 + kstep;
;             if (last && has_next) { S.a_ready(nxt); if constexpr (Epi::PREF) E.prefetch(nxt, wid, lane); }
;             if constexpr (SP2) {
;             PG8_LDB(B0, 0, 0); PG8_LDB(B1, 0, 1); PG8_SCHED; PG8_LDA(At, 0, 0); PG8_STAGE(PG8_SA(1, 1), a1 + hstepA, voffA);
;             PG8_WAIT_V(8); PG8_WAIT_L(0); PG8_BAR; PG8_MMA(0, 0, At, B0); PG8_MMA(0, 1, At, B1); PG8_BAR; PG8_SCHED;
;             PG8_LDA(At, 0, 1); PG8_STAGE(PG8_SB(0, 0), b2, voffB); PG8_STAGE(PG8_SB(0, 1), b2 + hstep, voffB); PG8_STAGE(PG8_SA(0, 0), a2, voffA);
;             PG8_WAIT_V(8); PG8_WAIT_L(0); PG8_BAR; PG8_MMA(1, 0, At, B0); PG8_MMA(1, 1, At, B1); PG8_BAR; PG8_SCHED;
;             PG8_LDB(B0, 1, 0); PG8_LDB(B1, 1, 1); PG8_SCHED; PG8_LDA(At, 1, 0); PG8_STAGE(PG8_SA(0, 1), a2 + hstepA, voffA);
;             PG8_WAIT_V(8); PG8_WAIT_L(0); PG8_BAR; PG8_MMA(0, 0, At, B0); PG8_MMA(0, 1, At, B1); PG8_BAR; PG8_SCHED;
;             PG8_LDA(At, 1, 1); PG8_STAGE(PG8_SB(1, 0), b3, voffB); PG8_STAGE(PG8_SB(1, 1), b3 + hstep, voffB); PG8_STAGE(PG8_SA(1, 0), a3, voffA);
;             PG8_WAIT_V(8); PG8_WAIT_L(0); PG8_BAR; PG8_MMA(1, 0, At, B0); PG8_MMA(1, 1, At, B1); PG8_BAR; PG8_SCHED;
	v_mov_b32_e32 v184, v223
	ds_read_b128 v[160:163], v232 offset:49152
	ds_read_b128 v[164:167], v232 offset:50176
	ds_read_b128 v[168:171], v232 offset:51200
	ds_read_b128 v[172:175], v232 offset:52224
	ds_read_b128 v[176:179], v232 offset:53248
	ds_read_b128 v[180:183], v232 offset:54272
	ds_read_b128 v[190:193], v232 offset:55296
	ds_read_b128 v[194:197], v232 offset:56320
	s_add_i32 s50, s63, s3
	v_lshl_add_u64 v[198:199], s[48:49], 0, v[184:185]
	v_lshl_add_u64 v[198:199], v[198:199], 0, s[40:41]
	s_mov_b32 m0, s50
	v_mov_b32_e32 v184, v225
	global_load_lds_dwordx4 v[198:199], off
	s_add_i32 m0, s50, 0x2000
	s_nop 0
	v_lshl_add_u64 v[198:199], s[48:49], 0, v[184:185]
	s_add_u32 s48, s48, 0x160080
	v_lshl_add_u64 v[198:199], v[198:199], 0, s[40:41]
	s_addc_u32 s49, s49, 0
	v_mov_b32_e32 v184, v223
	s_add_i32 s50, s64, s3
	global_load_lds_dwordx4 v[198:199], off
	s_mov_b32 m0, s50
	s_nop 0
	global_load_lds_dwordx4 v184, s[48:49]
	v_mov_b32_e32 v184, v225
	s_add_i32 m0, s50, 0x2000
	s_nop 0
	global_load_lds_dwordx4 v184, s[48:49]
	v_mov_b32_e32 v184, v222
	s_mov_b32 m0, s52
	s_nop 0
	global_load_lds_dwordx4 v184, s[46:47]
	v_mov_b32_e32 v184, v224
	s_mov_b32 m0, s53
	s_nop 0
	global_load_lds_dwordx4 v184, s[46:47]
	s_waitcnt vmcnt(8)
	s_waitcnt lgkmcnt(0)
	s_barrier
	s_setprio 1
	s_waitcnt lgkmcnt(0)
	v_mfma_f32_16x16x32_bf16 v[60:63], v[104:107], v[160:163], v[60:63]
	v_mfma_f32_16x16x32_bf16 v[56:59], v[128:131], v[160:163], v[56:59]
	v_mfma_f32_16x16x32_bf16 v[44:47], v[104:107], v[168:171], v[44:47]
	v_mfma_f32_16x16x32_bf16 v[40:43], v[128:131], v[168:171], v[40:43]
	v_mfma_f32_16x16x32_bf16 v[28:31], v[104:107], v[176:179], v[28:31]
	v_mfma_f32_16x16x32_bf16 v[24:27], v[128:131], v[176:179], v[24:27]
	v_mfma_f32_16x16x32_bf16 v[12:15], v[104:107], v[190:193], v[12:15]
	v_mfma_f32_16x16x32_bf16 v[8:11], v[128:131], v[190:193], v[8:11]
	v_mfma_f32_16x16x32_bf16 v[60:63], v[116:119], v[164:167], v[60:63]
	v_mfma_f32_16x16x32_bf16 v[56:59], v[140:143], v[164:167], v[56:59]
	v_mfma_f32_16x16x32_bf16 v[44:47], v[116:119], v[172:175], v[44:47]
	v_mfma_f32_16x16x32_bf16 v[40:43], v[140:143], v[172:175], v[40:43]
	v_mfma_f32_16x16x32_bf16 v[28:31], v[116:119], v[180:183], v[28:31]
	v_mfma_f32_16x16x32_bf16 v[24:27], v[140:143], v[180:183], v[24:27]
	v_mfma_f32_16x16x32_bf16 v[12:15], v[116:119], v[194:197], v[12:15]
	v_mfma_f32_16x16x32_bf16 v[8:11], v[140:143], v[194:197], v[8:11]
	s_setprio 0
	s_setprio 1
	v_mfma_f32_16x16x32_bf16 v[52:55], v[144:147], v[160:163], v[52:55]
	v_mfma_f32_16x16x32_bf16 v[48:51], v[152:155], v[160:163], v[48:51]
	v_mfma_f32_16x16x32_bf16 v[36:39], v[144:147], v[168:171], v[36:39]
	v_mfma_f32_16x16x32_bf16 v[32:35], v[152:155], v[168:171], v[32:35]
	v_mfma_f32_16x16x32_bf16 v[20:23], v[144:147], v[176:179], v[20:23]
	v_mfma_f32_16x16x32_bf16 v[16:19], v[152:155], v[176:179], v[16:19]
	v_mfma_f32_16x16x32_bf16 v[4:7], v[144:147], v[190:193], v[4:7]
	v_mfma_f32_16x16x32_bf16 v[0:3], v[152:155], v[190:193], v[0:3]
	v_mfma_f32_16x16x32_bf16 v[52:55], v[148:151], v[164:167], v[52:55]
	v_mfma_f32_16x16x32_bf16 v[48:51], v[156:159], v[164:167], v[48:51]
	v_mfma_f32_16x16x32_bf16 v[36:39], v[148:151], v[172:175], v[36:39]
	v_mfma_f32_16x16x32_bf16 v[32:35], v[156:159], v[172:175], v[32:35]
	v_mfma_f32_16x16x32_bf16 v[20:23], v[148:151], v[180:183], v[20:23]
	v_mfma_f32_16x16x32_bf16 v[16:19], v[156:159], v[180:183], v[16:19]
	v_mfma_f32_16x16x32_bf16 v[4:7], v[148:151], v[194:197], v[4:7]
	v_mfma_f32_16x16x32_bf16 v[0:3], v[156:159], v[194:197], v[0:3]
	s_setprio 0
	s_barrier
	s_add_i32 s62, s62, 2
	s_add_u32 s60, s60, 0x100
	s_addc_u32 s61, s61, 0
	s_add_u32 s44, s44, 0x10000
	s_addc_u32 s45, s45, 0
	s_cmpk_gt_u32 s62, 0x55
	s_cbranch_scc0 .LBB0_894
	s_and_b64 vcc, exec, s[36:37]
	s_cbranch_vccz .LBB0_897
	s_barrier

;     __device__ bool next(int i, Unit& u) const { const bool r = base.next(i >> 1, u); u.kh = i & 1; return r; }
; #define PG8_LDA(dst, b, h) do { _Pragma("unroll") for (int m = 0; m < 4; ++m) _Pragma("unroll") for (int k = 0; k < 2; ++k) dst[m][k] = *(const PG8_LAS bf16x8*)(lds + PG8_SA(b, h) + aoff + m * 2048 + k * 1024); } while (0)
; template <class Epi, class Sched, bool ALIGN_EPI = false, bool SP2 = false, bool ABLK = false, bool F8 = false>
; __device__ __forceinline__ void gemm_phase(PG8_LAS unsigned char* lds, const Gemm g, const Sched& S, const Epi& E, const int wave_s) {
;     ...
;         const bool has_next = S.next(ui + 1, nxt); nxt.par = (ui + 1) & 1;
;         const char* nA = has_next ? (const char*)g.A + (size_t)nxt.pm * tstep + nxt.kh * khbA : cA; const char* nB = has_next ? (const char*)g.Bt + (size_t)nxt.pn * tstep + nxt.kh * khb : cB;
;         for (int t = 0; t < nt; t += 2) {
;             const bool last = (t == nt - 2);
;             const char* a1 = cA + (size_t)(t + 1) * kstepA;
;             const char* a2 = last ? nA : cA + (size_t)(t + 2) * kstepA; const char* b2 = last ? nB : cB + (size_t)(t + 2) * kstep;
;             const char* a3 = a2 + kstepA; const char* b3 = b2 + kstep;
;             if (last && has_next) { S.a_ready(nxt); if constexpr (Epi::PREF) E.prefetch(nxt, wid, lane); }
;             if constexpr (SP2) {
;             PG8_LDB(B0, 0, 0); PG8_LDB(B1, 0, 1); PG8_SCHED; PG8_LDA(At, 0, 0); PG8_STAGE(PG8_SA(1, 1), a1 + hstepA, voffA);
;             PG8_WAIT_V(8); PG8_WAIT_L(0); PG8_BAR; PG8_MMA(0, 0, At, B0); PG8_MMA(0, 1, At, B1); PG8_BAR; PG8_SCHED;
;             PG8_LDA(At, 0, 1); PG8_STAGE(PG8_SB(0, 0), b2, voffB); PG8_STAGE(PG8_SB(0, 1), b2 + hstep, voffB); PG8_STAGE(PG8_SA(0, 0), a2, voffA);
;             PG8_WAIT_V(8); PG8_WAIT_L(0); PG8_BAR; PG8_MMA(1, 0, At, B0); PG8_MMA(1, 1, At, B1); PG8_BAR; PG8_SCHED;
;             PG8_LDB(B0, 1, 0); PG8_LDB(B1, 1, 1); PG8_SCHED; PG8_LDA(At, 1, 0); PG8_STAGE(PG8_SA(0, 1), a2 + hstepA, voffA);
;             PG8_WAIT_V(8); PG8_WAIT_L(0); PG8_BAR; PG8_MMA(0, 0, At, B0); PG8_MMA(0, 1, At, B1); PG8_BAR; PG8_SCHED;
;             PG8_LDA(At, 1, 1); PG8_STAGE(PG8_SB(1, 0), b3, voffB); PG8_STAGE(PG8_SB(1, 1), b3 + hstep, voffB); PG8_STAGE(PG8_SA(1, 0), a3, voffA);
;             PG8_WAIT_V(8); PG8_WAIT_L(0); PG8_BAR; PG8_MMA(1, 0, At, B0); PG8_MMA(1, 1, At, B1); PG8_BAR; PG8_SCHED;
.LBB0_1010:
	ds_read_b128 v[64:67], v236
	ds_read_b128 v[68:71], v236 offset:1024
	ds_read_b128 v[88:91], v236 offset:2048
	ds_read_b128 v[92:95], v236 offset:3072
	ds_read_b128 v[112:115], v237
	ds_read_b128 v[116:119], v237 offset:1024
	ds_read_b128 v[136:139], v237 offset:2048
	ds_read_b128 v[140:143], v237 offset:3072
	s_add_u32 s52, s50, 0xfff80080
	s_addc_u32 s53, s51, -1
	s_cmp_eq_u32 s62, 28
	s_cselect_b32 s53, s41, s53
	s_cselect_b32 s52, s47, s52
	s_cselect_b32 s55, s13, s61
	s_cselect_b32 s54, s59, s60
	v_mov_b32_e32 v184, v229
	ds_read_b128 v[152:155], v238
	ds_read_b128 v[164:167], v238 offset:1024
	ds_read_b128 v[168:171], v238 offset:2048
	ds_read_b128 v[172:175], v238 offset:3072
	ds_read_b128 v[176:179], v238 offset:4096
	ds_read_b128 v[180:183], v238 offset:5120
	ds_read_b128 v[190:193], v238 offset:6144
	ds_read_b128 v[194:197], v238 offset:7168
	s_add_i32 m0, s20, 0xc000
	s_nop 0
	global_load_lds_dwordx4 v184, s[50:51]
	v_mov_b32_e32 v184, v231
	s_add_i32 m0, s20, 0xe000
	s_nop 0
	global_load_lds_dwordx4 v184, s[50:51]
	s_waitcnt vmcnt(8)
	s_waitcnt lgkmcnt(0)
	s_barrier
	s_setprio 1
	s_waitcnt lgkmcnt(0)
	v_mfma_f32_16x16x32_bf16 v[160:163], v[64:67], v[152:155], v[160:163]
	v_mfma_f32_16x16x32_bf16 v[156:159], v[88:91], v[152:155], v[156:159]
	v_mfma_f32_16x16x32_bf16 v[132:135], v[64:67], v[168:171], v[132:135]
	v_mfma_f32_16x16x32_bf16 v[128:131], v[88:91], v[168:171], v[128:131]
	v_mfma_f32_16x16x32_bf16 v[108:111], v[64:67], v[176:179], v[108:111]
	v_mfma_f32_16x16x32_bf16 v[104:107], v[88:91], v[176:179], v[104:107]
	v_mfma_f32_16x16x32_bf16 v[84:87], v[64:67], v[190:193], v[84:87]
	v_mfma_f32_16x16x32_bf16 v[80:83], v[88:91], v[190:193], v[80:83]
	v_mfma_f32_16x16x32_bf16 v[160:163], v[68:71], v[164:167], v[160:163]
	v_mfma_f32_16x16x32_bf16 v[156:159], v[92:95], v[164:167], v[156:159]
	v_mfma_f32_16x16x32_bf16 v[132:135], v[68:71], v[172:175], v[132:135]
	v_mfma_f32_16x16x32_bf16 v[128:131], v[92:95], v[172:175], v[128:131]
	v_mfma_f32_16x16x32_bf16 v[108:111], v[68:71], v[180:183], v[108:111]
	v_mfma_f32_16x16x32_bf16 v[104:107], v[92:95], v[180:183], v[104:107]
	v_mfma_f32_16x16x32_bf16 v[84:87], v[68:71], v[194:197], v[84:87]
	v_mfma_f32_16x16x32_bf16 v[80:83], v[92:95], v[194:197], v[80:83]
	s_setprio 0
	s_setprio 1
	v_mfma_f32_16x16x32_bf16 v[148:151], v[112:115], v[152:155], v[148:151]
	v_mfma_f32_16x16x32_bf16 v[144:147], v[136:139], v[152:155], v[144:147]
	v_mfma_f32_16x16x32_bf16 v[124:127], v[112:115], v[168:171], v[124:127]
	v_mfma_f32_16x16x32_bf16 v[120:123], v[136:139], v[168:171], v[120:123]
	v_mfma_f32_16x16x32_bf16 v[100:103], v[112:115], v[176:179], v[100:103]
	v_mfma_f32_16x16x32_bf16 v[96:99], v[136:139], v[176:179], v[96:99]
	v_mfma_f32_16x16x32_bf16 v[76:79], v[112:115], v[190:193], v[76:79]
	v_mfma_f32_16x16x32_bf16 v[72:75], v[136:139], v[190:193], v[72:75]
	v_mfma_f32_16x16x32_bf16 v[148:151], v[116:119], v[164:167], v[148:151]
	v_mfma_f32_16x16x32_bf16 v[144:147], v[140:143], v[164:167], v[144:147]
	v_mfma_f32_16x16x32_bf16 v[124:127], v[116:119], v[172:175], v[124:127]
	v_mfma_f32_16x16x32_bf16 v[120:123], v[140:143], v[172:175], v[120:123]
	v_mfma_f32_16x16x32_bf16 v[100:103], v[116:119], v[180:183], v[100:103]
	v_mfma_f32_16x16x32_bf16 v[96:99], v[140:143], v[180:183], v[96:99]
	v_mfma_f32_16x16x32_bf16 v[76:79], v[116:119], v[194:197], v[76:79]
	v_mfma_f32_16x16x32_bf16 v[72:75], v[140:143], v[194:197], v[72:75]
	s_setprio 0
	s_barrier
	v_mov_b32_e32 v184, v230
	s_add_i32 s63, s57, s3
	ds_read_b128 v[152:155], v238 offset:16384
	ds_read_b128 v[164:167], v238 offset:17408
	ds_read_b128 v[168:171], v238 offset:18432
	ds_read_b128 v[172:175], v238 offset:19456
	ds_read_b128 v[176:179], v238 offset:20480
	ds_read_b128 v[180:183], v238 offset:21504
	ds_read_b128 v[190:193], v238 offset:22528
	ds_read_b128 v[194:197], v238 offset:23552
	s_mov_b32 m0, s63
	s_nop 0
	global_load_lds_dwordx4 v184, s[54:55]
	v_mov_b32_e32 v184, v232
	s_add_i32 m0, s63, 0x2000
	s_add_u32 s64, s54, 0x80000
	global_load_lds_dwordx4 v184, s[54:55]
	s_addc_u32 s65, s55, 0
	v_mov_b32_e32 v184, v230
	s_add_i32 s63, s58, s3
	s_mov_b32 m0, s63
	s_nop 0
	global_load_lds_dwordx4 v184, s[64:65]
	v_mov_b32_e32 v184, v232
	s_add_i32 m0, s63, 0x2000
	s_nop 0
	global_load_lds_dwordx4 v184, s[64:65]
	v_mov_b32_e32 v184, v229
	s_mov_b32 m0, s20
	s_nop 0
	global_load_lds_dwordx4 v184, s[52:53]
	v_mov_b32_e32 v184, v231
	s_mov_b32 m0, s21
	s_nop 0
	global_load_lds_dwordx4 v184, s[52:53]
	s_waitcnt vmcnt(8)
	s_waitcnt lgkmcnt(0)
	s_barrier
; #define PG8_STAGE(bufoff, gbase, voff) do { _Pragma("unroll") for (int _i = 0; _i < 2; ++_i) \
;         { unsigned _vo = (voff)[_i]; asm volatile("" : "+v"(_vo));     \
;         __builtin_amdgcn_global_load_lds((const unsigned*)((const char*)(gbase) + _vo), (PG8_LAS unsigned*)(lds + (bufoff) + ldsw + _i * 8192), 16, 0, 0); } } while (0)
; #define PG8_LDA(dst, b, h) do { _Pragma("unroll") for (int m = 0; m < 4; ++m) _Pragma("unroll") for (int k = 0; k < 2; ++k) dst[m][k] = *(const PG8_LAS bf16x8*)(lds + PG8_SA(b, h) + aoff + m * 2048 + k * 1024); } while (0)
; #define PG8_LDB(dst, b, h) do { _Pragma("unroll") for (int n = 0; n < 2; ++n) _Pragma("unroll") for (int k = 0; k < 2; ++k) dst[n][k] = *(const PG8_LAS bf16x8*)(lds + PG8_SB(b, h) + boff + n * 2048 + k * 1024); } while (0)
; #define PG8_WAIT_V(n) asm volatile("s_waitcnt vmcnt(" #n ")" ::: "memory")
; #define PG8_WAIT_L(n) asm volatile("s_waitcnt lgkmcnt(" #n ")" ::: "memory")
; #define PG8_BAR __builtin_amdgcn_s_barrier()
; #define PG8_SCHED __builtin_amdgcn_sched_barrier(0)
; template <class Epi, class Sched, bool ALIGN_EPI = false, bool SP2 = false, bool ABLK = false, bool F8 = false>
; __device__ __forceinline__ void gemm_phase(PG8_LAS unsigned char* lds, const Gemm g, const Sched& S, const Epi& E, const int wave_s) {
;     ...
;             PG8_LDB(B0, 0, 0); PG8_LDB(B1, 0, 1); PG8_SCHED; PG8_LDA(At, 0, 0); PG8_STAGE(PG8_SA(1, 1), a1 + hstepA, voffA);
;             PG8_WAIT_V(8); PG8_WAIT_L(0); PG8_BAR; PG8_MMA(0, 0, At, B0); PG8_MMA(0, 1, At, B1); PG8_BAR; PG8_SCHED;
;             PG8_LDA(At, 0, 1); PG8_STAGE(PG8_SB(0, 0), b2, voffB); PG8_STAGE(PG8_SB(0, 1), b2 + hstep, voffB); PG8_STAGE(PG8_SA(0, 0), a2, voffA);
;             PG8_WAIT_V(8); PG8_WAIT_L(0); PG8_BAR; PG8_MMA(1, 0, At, B0); PG8_MMA(1, 1, At, B1); PG8_BAR; PG8_SCHED;
;             PG8_LDB(B0, 1, 0); PG8_LDB(B1, 1, 1); PG8_SCHED; PG8_LDA(At, 1, 0); PG8_STAGE(PG8_SA(0, 1), a2 + hstepA, voffA);
;             PG8_WAIT_V(8); PG8_WAIT_L(0); PG8_BAR; PG8_MMA(0, 0, At, B0); PG8_MMA(0, 1, At, B1); PG8_BAR; PG8_SCHED;
;             PG8_LDA(At, 1, 1); PG8_STAGE(PG8_SB(1, 0), b3, voffB); PG8_STAGE(PG8_SB(1, 1), b3 + hstep, voffB); PG8_STAGE(PG8_SA(1, 0), a3, voffA);
;             PG8_WAIT_V(8); PG8_WAIT_L(0); PG8_BAR; PG8_MMA(1, 0, At, B0); PG8_MMA(1, 1, At, B1); PG8_BAR; PG8_SCHED;
	s_setprio 1
	s_waitcnt lgkmcnt(0)
	v_mfma_f32_16x16x32_bf16 v[60:63], v[64:67], v[152:155], v[60:63]
	v_mfma_f32_16x16x32_bf16 v[56:59], v[88:91], v[152:155], v[56:59]
	v_mfma_f32_16x16x32_bf16 v[44:47], v[64:67], v[168:171], v[44:47]
	v_mfma_f32_16x16x32_bf16 v[40:43], v[88:91], v[168:171], v[40:43]
	v_mfma_f32_16x16x32_bf16 v[28:31], v[64:67], v[176:179], v[28:31]
	v_mfma_f32_16x16x32_bf16 v[24:27], v[88:91], v[176:179], v[24:27]
	v_mfma_f32_16x16x32_bf16 v[12:15], v[64:67], v[190:193], v[12:15]
	v_mfma_f32_16x16x32_bf16 v[8:11], v[88:91], v[190:193], v[8:11]
	v_mfma_f32_16x16x32_bf16 v[60:63], v[68:71], v[164:167], v[60:63]
	v_mfma_f32_16x16x32_bf16 v[56:59], v[92:95], v[164:167], v[56:59]
	v_mfma_f32_16x16x32_bf16 v[44:47], v[68:71], v[172:175], v[44:47]
	v_mfma_f32_16x16x32_bf16 v[40:43], v[92:95], v[172:175], v[40:43]
	v_mfma_f32_16x16x32_bf16 v[28:31], v[68:71], v[180:183], v[28:31]
	v_mfma_f32_16x16x32_bf16 v[24:27], v[92:95], v[180:183], v[24:27]
	v_mfma_f32_16x16x32_bf16 v[12:15], v[68:71], v[194:197], v[12:15]
	v_mfma_f32_16x16x32_bf16 v[8:11], v[92:95], v[194:197], v[8:11]
	s_setprio 0
	s_setprio 1
	v_mfma_f32_16x16x32_bf16 v[52:55], v[112:115], v[152:155], v[52:55]
	v_mfma_f32_16x16x32_bf16 v[48:51], v[136:139], v[152:155], v[48:51]
	v_mfma_f32_16x16x32_bf16 v[36:39], v[112:115], v[168:171], v[36:39]
	v_mfma_f32_16x16x32_bf16 v[32:35], v[136:139], v[168:171], v[32:35]
	v_mfma_f32_16x16x32_bf16 v[20:23], v[112:115], v[176:179], v[20:23]
	v_mfma_f32_16x16x32_bf16 v[16:19], v[136:139], v[176:179], v[16:19]
	v_mfma_f32_16x16x32_bf16 v[4:7], v[112:115], v[190:193], v[4:7]
	v_mfma_f32_16x16x32_bf16 v[0:3], v[136:139], v[190:193], v[0:3]
	v_mfma_f32_16x16x32_bf16 v[52:55], v[116:119], v[164:167], v[52:55]
	v_mfma_f32_16x16x32_bf16 v[48:51], v[140:143], v[164:167], v[48:51]
	v_mfma_f32_16x16x32_bf16 v[36:39], v[116:119], v[172:175], v[36:39]
	v_mfma_f32_16x16x32_bf16 v[32:35], v[140:143], v[172:175], v[32:35]
	v_mfma_f32_16x16x32_bf16 v[20:23], v[116:119], v[180:183], v[20:23]
	v_mfma_f32_16x16x32_bf16 v[16:19], v[140:143], v[180:183], v[16:19]
	v_mfma_f32_16x16x32_bf16 v[4:7], v[116:119], v[194:197], v[4:7]
	v_mfma_f32_16x16x32_bf16 v[0:3], v[140:143], v[194:197], v[0:3]
	s_setprio 0
	s_barrier
	s_add_i32 s63, 0, 0x18000
	s_add_i32 s66, 0, 0x1c000
	v_add_u32_e32 v92, s63, v234
	v_add_u32_e32 v140, s66, v234
	ds_read_b128 v[64:67], v92
	ds_read_b128 v[68:71], v92 offset:1024
	ds_read_b128 v[88:91], v92 offset:2048
	ds_read_b128 v[92:95], v92 offset:3072
	ds_read_b128 v[112:115], v140
	ds_read_b128 v[116:119], v140 offset:1024
	ds_read_b128 v[136:139], v140 offset:2048
	ds_read_b128 v[140:143], v140 offset:3072
	s_add_u32 s64, s52, 0x80000
	v_mov_b32_e32 v184, v229
	s_mov_b32 m0, s22
	ds_read_b128 v[152:155], v238 offset:32768
	ds_read_b128 v[164:167], v238 offset:33792
	ds_read_b128 v[168:171], v238 offset:34816
	ds_read_b128 v[172:175], v238 offset:35840
	ds_read_b128 v[176:179], v238 offset:36864
	ds_read_b128 v[180:183], v238 offset:37888
	ds_read_b128 v[190:193], v238 offset:38912
	ds_read_b128 v[194:197], v238 offset:39936
	s_addc_u32 s65, s53, 0
	s_nop 0
	global_load_lds_dwordx4 v184, s[64:65]
	v_mov_b32_e32 v184, v231
	s_mov_b32 m0, s23
	s_nop 0
	global_load_lds_dwordx4 v184, s[64:65]
	s_waitcnt vmcnt(8)
	s_waitcnt lgkmcnt(0)
	s_barrier
	s_setprio 1
	s_waitcnt lgkmcnt(0)
	v_mfma_f32_16x16x32_bf16 v[160:163], v[64:67], v[152:155], v[160:163]
	v_mfma_f32_16x16x32_bf16 v[156:159], v[88:91], v[152:155], v[156:159]
	v_mfma_f32_16x16x32_bf16 v[132:135], v[64:67], v[168:171], v[132:135]
	v_mfma_f32_16x16x32_bf16 v[128:131], v[88:91], v[168:171], v[128:131]
	v_mfma_f32_16x16x32_bf16 v[108:111], v[64:67], v[176:179], v[108:111]
	v_mfma_f32_16x16x32_bf16 v[104:107], v[88:91], v[176:179], v[104:107]
	v_mfma_f32_16x16x32_bf16 v[84:87], v[64:67], v[190:193], v[84:87]
	v_mfma_f32_16x16x32_bf16 v[80:83], v[88:91], v[190:193], v[80:83]
	v_mfma_f32_16x16x32_bf16 v[160:163], v[68:71], v[164:167], v[160:163]
	v_mfma_f32_16x16x32_bf16 v[156:159], v[92:95], v[164:167], v[156:159]
	v_mfma_f32_16x16x32_bf16 v[132:135], v[68:71], v[172:175], v[132:135]
	v_mfma_f32_16x16x32_bf16 v[128:131], v[92:95], v[172:175], v[128:131]
	v_mfma_f32_16x16x32_bf16 v[108:111], v[68:71], v[180:183], v[108:111]
	v_mfma_f32_16x16x32_bf16 v[104:107], v[92:95], v[180:183], v[104:107]
	v_mfma_f32_16x16x32_bf16 v[84:87], v[68:71], v[194:197], v[84:87]
	v_mfma_f32_16x16x32_bf16 v[80:83], v[92:95], v[194:197], v[80:83]
	s_setprio 0
	s_setprio 1
	v_mfma_f32_16x16x32_bf16 v[148:151], v[112:115], v[152:155], v[148:151]
	v_mfma_f32_16x16x32_bf16 v[144:147], v[136:139], v[152:155], v[144:147]
	v_mfma_f32_16x16x32_bf16 v[124:127], v[112:115], v[168:171], v[124:127]
	v_mfma_f32_16x16x32_bf16 v[120:123], v[136:139], v[168:171], v[120:123]
	v_mfma_f32_16x16x32_bf16 v[100:103], v[112:115], v[176:179], v[100:103]
	v_mfma_f32_16x16x32_bf16 v[96:99], v[136:139], v[176:179], v[96:99]
	v_mfma_f32_16x16x32_bf16 v[76:79], v[112:115], v[190:193], v[76:79]
	v_mfma_f32_16x16x32_bf16 v[72:75], v[136:139], v[190:193], v[72:75]
	v_mfma_f32_16x16x32_bf16 v[148:151], v[116:119], v[164:167], v[148:151]
	v_mfma_f32_16x16x32_bf16 v[144:147], v[140:143], v[164:167], v[144:147]
	v_mfma_f32_16x16x32_bf16 v[124:127], v[116:119], v[172:175], v[124:127]
	v_mfma_f32_16x16x32_bf16 v[120:123], v[140:143], v[172:175], v[120:123]
	v_mfma_f32_16x16x32_bf16 v[100:103], v[116:119], v[180:183], v[100:103]
	v_mfma_f32_16x16x32_bf16 v[96:99], v[140:143], v[180:183], v[96:99]
	v_mfma_f32_16x16x32_bf16 v[76:79], v[116:119], v[194:197], v[76:79]
	v_mfma_f32_16x16x32_bf16 v[72:75], v[140:143], v[194:197], v[72:75]
	s_setprio 0
	s_barrier
; #define PG8_STAGE(bufoff, gbase, voff) do { _Pragma("unroll") for (int _i = 0; _i < 2; ++_i) \
;         { unsigned _vo = (voff)[_i]; asm volatile("" : "+v"(_vo));     \
;         __builtin_amdgcn_global_load_lds((const unsigned*)((const char*)(gbase) + _vo), (PG8_LAS unsigned*)(lds + (bufoff) + ldsw + _i * 8192), 16, 0, 0); } } while (0)
; #define PG8_LDA(dst, b, h) do { _Pragma("unroll") for (int m = 0; m < 4; ++m) _Pragma("unroll") for (int k = 0; k < 2; ++k) dst[m][k] = *(const PG8_LAS bf16x8*)(lds + PG8_SA(b, h) + aoff + m * 2048 + k * 1024); } while (0)
; #define PG8_BAR __builtin_amdgcn_s_barrier()
; template <class Epi, class Sched, bool ALIGN_EPI = false, bool SP2 = false, bool ABLK = false, bool F8 = false>
; __device__ __forceinline__ void gemm_phase(PG8_LAS unsigned char* lds, const Gemm g, const Sched& S, const Epi& E, const int wave_s) {
;     ...
;         for (int t = 0; t < nt; t += 2) {
;             const bool last = (t == nt - 2);
;             const char* a1 = cA + (size_t)(t + 1) * kstepA;
;             const char* a2 = last ? nA : cA + (size_t)(t + 2) * kstepA; const char* b2 = last ? nB : cB + (size_t)(t + 2) * kstep;
;             const char* a3 = a2 + kstepA; const char* b3 = b2 + kstep;
;             if (last && has_next) { S.a_ready(nxt); if constexpr (Epi::PREF) E.prefetch(nxt, wid, lane); }
;             if constexpr (SP2) {
;             PG8_LDB(B0, 0, 0); PG8_LDB(B1, 0, 1); PG8_SCHED; PG8_LDA(At, 0, 0); PG8_STAGE(PG8_SA(1, 1), a1 + hstepA, voffA);
;             PG8_WAIT_V(8); PG8_WAIT_L(0); PG8_BAR; PG8_MMA(0, 0, At, B0); PG8_MMA(0, 1, At, B1); PG8_BAR; PG8_SCHED;
;             PG8_LDA(At, 0, 1); PG8_STAGE(PG8_SB(0, 0), b2, voffB); PG8_STAGE(PG8_SB(0, 1), b2 + hstep, voffB); PG8_STAGE(PG8_SA(0, 0), a2, voffA);
;             PG8_WAIT_V(8); PG8_WAIT_L(0); PG8_BAR; PG8_MMA(1, 0, At, B0); PG8_MMA(1, 1, At, B1); PG8_BAR; PG8_SCHED;
;             PG8_LDB(B0, 1, 0); PG8_LDB(B1, 1, 1); PG8_SCHED; PG8_LDA(At, 1, 0); PG8_STAGE(PG8_SA(0, 1), a2 + hstepA, voffA);
;             PG8_WAIT_V(8); PG8_WAIT_L(0); PG8_BAR; PG8_MMA(0, 0, At, B0); PG8_MMA(0, 1, At, B1); PG8_BAR; PG8_SCHED;
;             PG8_LDA(At, 1, 1); PG8_STAGE(PG8_SB(1, 0), b3, voffB); PG8_STAGE(PG8_SB(1, 1), b3 + hstep, voffB); PG8_STAGE(PG8_SA(1, 0), a3, voffA);
;             PG8_WAIT_V(8); PG8_WAIT_L(0); PG8_BAR; PG8_MMA(1, 0, At, B0); PG8_MMA(1, 1, At, B1); PG8_BAR; PG8_SCHED;
	v_mov_b32_e32 v184, v230
	ds_read_b128 v[152:155], v238 offset:49152
	ds_read_b128 v[164:167], v238 offset:50176
	ds_read_b128 v[168:171], v238 offset:51200
	ds_read_b128 v[172:175], v238 offset:52224
	ds_read_b128 v[176:179], v238 offset:53248
	ds_read_b128 v[180:183], v238 offset:54272
	ds_read_b128 v[190:193], v238 offset:55296
	ds_read_b128 v[194:197], v238 offset:56320
	s_add_i32 s63, s63, s3
	v_lshl_add_u64 v[198:199], s[54:55], 0, v[184:185]
	v_lshl_add_u64 v[198:199], v[198:199], 0, s[10:11]
	s_mov_b32 m0, s63
	v_mov_b32_e32 v184, v232
	global_load_lds_dwordx4 v[198:199], off
	s_add_i32 m0, s63, 0x2000
	s_nop 0
	v_lshl_add_u64 v[198:199], s[54:55], 0, v[184:185]
	s_add_u32 s54, s54, 0x80080
	v_lshl_add_u64 v[198:199], v[198:199], 0, s[10:11]
	s_addc_u32 s55, s55, 0
	v_mov_b32_e32 v184, v230
	s_add_i32 s63, s66, s3
	global_load_lds_dwordx4 v[198:199], off
	s_mov_b32 m0, s63
	s_nop 0
	global_load_lds_dwordx4 v184, s[54:55]
	v_mov_b32_e32 v184, v232
	s_add_i32 m0, s63, 0x2000
	s_nop 0
	global_load_lds_dwordx4 v184, s[54:55]
	v_mov_b32_e32 v184, v229
	s_mov_b32 m0, s49
	v_lshl_add_u64 v[198:199], s[52:53], 0, v[184:185]
	v_lshl_add_u64 v[198:199], v[198:199], 0, s[10:11]
	v_mov_b32_e32 v184, v231
	global_load_lds_dwordx4 v[198:199], off
	s_mov_b32 m0, s56
	v_lshl_add_u64 v[198:199], s[52:53], 0, v[184:185]
	v_lshl_add_u64 v[198:199], v[198:199], 0, s[10:11]
	global_load_lds_dwordx4 v[198:199], off
	s_waitcnt vmcnt(8)
	s_waitcnt lgkmcnt(0)
	s_barrier
	s_setprio 1
	s_waitcnt lgkmcnt(0)
	v_mfma_f32_16x16x32_bf16 v[60:63], v[64:67], v[152:155], v[60:63]
	v_mfma_f32_16x16x32_bf16 v[56:59], v[88:91], v[152:155], v[56:59]
	v_mfma_f32_16x16x32_bf16 v[44:47], v[64:67], v[168:171], v[44:47]
	v_mfma_f32_16x16x32_bf16 v[40:43], v[88:91], v[168:171], v[40:43]
	v_mfma_f32_16x16x32_bf16 v[28:31], v[64:67], v[176:179], v[28:31]
	v_mfma_f32_16x16x32_bf16 v[24:27], v[88:91], v[176:179], v[24:27]
	v_mfma_f32_16x16x32_bf16 v[12:15], v[64:67], v[190:193], v[12:15]
	v_mfma_f32_16x16x32_bf16 v[8:11], v[88:91], v[190:193], v[8:11]
	v_mfma_f32_16x16x32_bf16 v[60:63], v[68:71], v[164:167], v[60:63]
	v_mfma_f32_16x16x32_bf16 v[56:59], v[92:95], v[164:167], v[56:59]
	v_mfma_f32_16x16x32_bf16 v[44:47], v[68:71], v[172:175], v[44:47]
	v_mfma_f32_16x16x32_bf16 v[40:43], v[92:95], v[172:175], v[40:43]
	v_mfma_f32_16x16x32_bf16 v[28:31], v[68:71], v[180:183], v[28:31]
	v_mfma_f32_16x16x32_bf16 v[24:27], v[92:95], v[180:183], v[24:27]
	v_mfma_f32_16x16x32_bf16 v[12:15], v[68:71], v[194:197], v[12:15]
	v_mfma_f32_16x16x32_bf16 v[8:11], v[92:95], v[194:197], v[8:11]
	s_setprio 0
	s_setprio 1
	v_mfma_f32_16x16x32_bf16 v[52:55], v[112:115], v[152:155], v[52:55]
	v_mfma_f32_16x16x32_bf16 v[48:51], v[136:139], v[152:155], v[48:51]
	v_mfma_f32_16x16x32_bf16 v[36:39], v[112:115], v[168:171], v[36:39]
	v_mfma_f32_16x16x32_bf16 v[32:35], v[136:139], v[168:171], v[32:35]
	v_mfma_f32_16x16x32_bf16 v[20:23], v[112:115], v[176:179], v[20:23]
	v_mfma_f32_16x16x32_bf16 v[16:19], v[136:139], v[176:179], v[16:19]
	v_mfma_f32_16x16x32_bf16 v[4:7], v[112:115], v[190:193], v[4:7]
	v_mfma_f32_16x16x32_bf16 v[0:3], v[136:139], v[190:193], v[0:3]
	v_mfma_f32_16x16x32_bf16 v[52:55], v[116:119], v[164:167], v[52:55]
	v_mfma_f32_16x16x32_bf16 v[48:51], v[140:143], v[164:167], v[48:51]
	v_mfma_f32_16x16x32_bf16 v[36:39], v[116:119], v[172:175], v[36:39]
	v_mfma_f32_16x16x32_bf16 v[32:35], v[140:143], v[172:175], v[32:35]
	v_mfma_f32_16x16x32_bf16 v[20:23], v[116:119], v[180:183], v[20:23]
	v_mfma_f32_16x16x32_bf16 v[16:19], v[140:143], v[180:183], v[16:19]
	v_mfma_f32_16x16x32_bf16 v[4:7], v[116:119], v[194:197], v[4:7]
	v_mfma_f32_16x16x32_bf16 v[0:3], v[140:143], v[194:197], v[0:3]
	s_setprio 0
	s_barrier
	s_add_i32 s62, s62, 2
	s_add_u32 s50, s50, 0x100
	s_addc_u32 s51, s51, 0
	s_add_u32 s60, s60, 0x100
	s_addc_u32 s61, s61, 0
	s_cmp_gt_u32 s62, 29
	s_cbranch_scc0 .LBB0_1010
	s_and_b64 vcc, exec, s[36:37]
	s_cbranch_vccz .LBB0_1013
	s_barrier

; __device__ __forceinline__ float rstd_of(float ss, float inv_n) { return __builtin_amdgcn_rsqf(ss * inv_n + 1e-6f); }
; __device__ __forceinline__ float bf_lo(unsigned w) { return __uint_as_float(w << 16); }
; __device__ __forceinline__ float bf_hi(unsigned w) { return __uint_as_float(w & 0xffff0000u); }
; #define GAS __attribute__((address_space(1)))
; __global__ void __launch_bounds__(NTHREADS, 2) mk_fwd(Args args) {
;     ...
;     if (PH(11)) { FRESH_IDS const bf16* E = (const bf16*)(ws + WS_E); const float* sse = stat + ST_SSE * MROWS; const int gw = bx * NWAVES + wave, NGW = G * NWAVES;
;         for (int m = gw; m < MROWS; m += NGW) { const float r = pg8::rstd_of(sse[m], 1.0f / 2048.0f); GAS f32x4* xr = (GAS f32x4*)(out + (size_t)m * DM) + lane; const GAS v2u* xbr = (const GAS v2u*)(XB + (size_t)m * DM) + lane; const GAS v2u* er = (const GAS v2u*)(E + (size_t)m * DM) + lane;
;             const GAS f32x4* gp = (const GAS f32x4*)in.ple_post + lane;
; #pragma unroll
;             for (int j = 0; j < 8; ++j) { const v2u xw = xbr[64 * j]; const v2u w = er[64 * j]; const f32x4 gg = gp[64 * j]; f32x4 v;
;                 v.x = pg8::bf_lo(xw.x) + pg8::bf_lo(w.x) * r * gg.x; v.y = pg8::bf_hi(xw.x) + pg8::bf_hi(w.x) * r * gg.y; v.z = pg8::bf_lo(xw.y) + pg8::bf_lo(w.y) * r * gg.z; v.w = pg8::bf_hi(xw.y) + pg8::bf_hi(w.y) * r * gg.w; xr[64 * j] = v; } } }
.Lp11_entry:
	v_mov_b32_e32 v3, v0
	v_lshrrev_b32_e32 v2, 1, v0
	s_add_u32 s16, s68, 0xc000000
	s_addc_u32 s17, s69, 0
	s_add_u32 s18, s68, 0x1c000000
	s_addc_u32 s19, s69, 0
	s_add_u32 s20, s68, 0xc0000
	s_addc_u32 s21, s69, 0
	s_add_u32 s22, s14, 0x1000
	s_addc_u32 s23, s15, 0
	s_add_u32 s12, s12, 0x1000
	s_addc_u32 s13, s13, 0
	global_load_dwordx4 v[32:35], v3, s[12:13] offset:-4096
	global_load_dwordx4 v[36:39], v3, s[12:13] offset:-3072
	global_load_dwordx4 v[40:43], v3, s[12:13] offset:-2048
	global_load_dwordx4 v[44:47], v3, s[12:13] offset:-1024
	global_load_dwordx4 v[48:51], v3, s[12:13] offset:0
	global_load_dwordx4 v[52:55], v3, s[12:13] offset:1024
	global_load_dwordx4 v[56:59], v3, s[12:13] offset:2048
	global_load_dwordx4 v[60:63], v3, s[12:13] offset:3072
	s_lshl_b32 s40, s24, 12
	s_add_u32 s30, s16, s40
	s_addc_u32 s31, s17, 0
	s_add_u32 s32, s18, s40
	s_addc_u32 s33, s19, 0
	s_lshl_b32 s41, s24, 2
	s_add_u32 s34, s20, s41
	s_addc_u32 s35, s21, 0
	global_load_dword v96, v1, s[34:35]
	global_load_dwordx2 v[64:65], v2, s[30:31]
	global_load_dwordx2 v[80:81], v2, s[32:33]
	global_load_dwordx2 v[66:67], v2, s[30:31] offset:512
	global_load_dwordx2 v[82:83], v2, s[32:33] offset:512
	global_load_dwordx2 v[68:69], v2, s[30:31] offset:1024
	global_load_dwordx2 v[84:85], v2, s[32:33] offset:1024
	global_load_dwordx2 v[70:71], v2, s[30:31] offset:1536
	global_load_dwordx2 v[86:87], v2, s[32:33] offset:1536
	global_load_dwordx2 v[72:73], v2, s[30:31] offset:2048
	global_load_dwordx2 v[88:89], v2, s[32:33] offset:2048
	global_load_dwordx2 v[74:75], v2, s[30:31] offset:2560
	global_load_dwordx2 v[90:91], v2, s[32:33] offset:2560
	global_load_dwordx2 v[76:77], v2, s[30:31] offset:3072
	global_load_dwordx2 v[92:93], v2, s[32:33] offset:3072
	global_load_dwordx2 v[78:79], v2, s[30:31] offset:3584
	global_load_dwordx2 v[94:95], v2, s[32:33] offset:3584
	s_lshl_b32 s42, s24, 13
	s_add_u32 s36, s22, s42
	s_addc_u32 s37, s23, 0
	s_add_i32 s24, s24, s26
	s_cmpk_gt_i32 s24, 0x7fff
	s_cbranch_scc1 .Lp11_last_f
	s_lshl_b32 s40, s24, 12
	s_add_u32 s30, s16, s40
	s_addc_u32 s31, s17, 0
	s_add_u32 s32, s18, s40
	s_addc_u32 s33, s19, 0
	s_lshl_b32 s41, s24, 2
	s_add_u32 s34, s20, s41
	s_addc_u32 s35, s21, 0
	global_load_dword v132, v1, s[34:35]
	global_load_dwordx2 v[100:101], v2, s[30:31]
	global_load_dwordx2 v[116:117], v2, s[32:33]
	global_load_dwordx2 v[102:103], v2, s[30:31] offset:512
	global_load_dwordx2 v[118:119], v2, s[32:33] offset:512
	global_load_dwordx2 v[104:105], v2, s[30:31] offset:1024
	global_load_dwordx2 v[120:121], v2, s[32:33] offset:1024
	global_load_dwordx2 v[106:107], v2, s[30:31] offset:1536
	global_load_dwordx2 v[122:123], v2, s[32:33] offset:1536
	global_load_dwordx2 v[108:109], v2, s[30:31] offset:2048
	global_load_dwordx2 v[124:125], v2, s[32:33] offset:2048
	global_load_dwordx2 v[110:111], v2, s[30:31] offset:2560
	global_load_dwordx2 v[126:127], v2, s[32:33] offset:2560
	global_load_dwordx2 v[112:113], v2, s[30:31] offset:3072
	global_load_dwordx2 v[128:129], v2, s[32:33] offset:3072
	global_load_dwordx2 v[114:115], v2, s[30:31] offset:3584
	global_load_dwordx2 v[130:131], v2, s[32:33] offset:3584
	s_waitcnt vmcnt(17)
	v_fmamk_f32 v0, v96, 0x3a000000, v16
	v_rsq_f32_e32 v0, v0
	v_lshlrev_b32_e32 v140, 16, v64
	v_and_b32_e32 v141, 0xffff0000, v64
	v_lshlrev_b32_e32 v142, 16, v65
	v_and_b32_e32 v143, 0xffff0000, v65
	v_lshlrev_b32_e32 v144, 16, v80
	v_and_b32_e32 v145, 0xffff0000, v80
	v_lshlrev_b32_e32 v146, 16, v81
	v_and_b32_e32 v147, 0xffff0000, v81
	v_pk_mul_f32 v[144:145], v[0:1], v[144:145] op_sel_hi:[0,1]
	v_pk_mul_f32 v[146:147], v[0:1], v[146:147] op_sel_hi:[0,1]
	v_pk_fma_f32 v[148:149], v[32:33], v[144:145], v[140:141]
	v_pk_fma_f32 v[150:151], v[34:35], v[146:147], v[142:143]
	global_store_dwordx4 v3, v[148:151], s[36:37] offset:-4096
	v_lshlrev_b32_e32 v156, 16, v66
	v_and_b32_e32 v157, 0xffff0000, v66
	v_lshlrev_b32_e32 v158, 16, v67
	v_and_b32_e32 v159, 0xffff0000, v67
	v_lshlrev_b32_e32 v160, 16, v82
	v_and_b32_e32 v161, 0xffff0000, v82
	v_lshlrev_b32_e32 v162, 16, v83
	v_and_b32_e32 v163, 0xffff0000, v83
	v_pk_mul_f32 v[160:161], v[0:1], v[160:161] op_sel_hi:[0,1]
	v_pk_mul_f32 v[162:163], v[0:1], v[162:163] op_sel_hi:[0,1]
	v_pk_fma_f32 v[152:153], v[36:37], v[160:161], v[156:157]
	v_pk_fma_f32 v[154:155], v[38:39], v[162:163], v[158:159]
	global_store_dwordx4 v3, v[152:155], s[36:37] offset:-3072
	v_lshlrev_b32_e32 v140, 16, v68
	v_and_b32_e32 v141, 0xffff0000, v68
	v_lshlrev_b32_e32 v142, 16, v69
	v_and_b32_e32 v143, 0xffff0000, v69
	v_lshlrev_b32_e32 v144, 16, v84
	v_and_b32_e32 v145, 0xffff0000, v84
	v_lshlrev_b32_e32 v146, 16, v85
	v_and_b32_e32 v147, 0xffff0000, v85
	v_pk_mul_f32 v[144:145], v[0:1], v[144:145] op_sel_hi:[0,1]
	v_pk_mul_f32 v[146:147], v[0:1], v[146:147] op_sel_hi:[0,1]
	v_pk_fma_f32 v[148:149], v[40:41], v[144:145], v[140:141]
	v_pk_fma_f32 v[150:151], v[42:43], v[146:147], v[142:143]
	global_store_dwordx4 v3, v[148:151], s[36:37] offset:-2048
	v_lshlrev_b32_e32 v156, 16, v70
	v_and_b32_e32 v157, 0xffff0000, v70
	v_lshlrev_b32_e32 v158, 16, v71
	v_and_b32_e32 v159, 0xffff0000, v71
	v_lshlrev_b32_e32 v160, 16, v86
	v_and_b32_e32 v161, 0xffff0000, v86
	v_lshlrev_b32_e32 v162, 16, v87
	v_and_b32_e32 v163, 0xffff0000, v87
	v_pk_mul_f32 v[160:161], v[0:1], v[160:161] op_sel_hi:[0,1]
	v_pk_mul_f32 v[162:163], v[0:1], v[162:163] op_sel_hi:[0,1]
	v_pk_fma_f32 v[152:153], v[44:45], v[160:161], v[156:157]
	v_pk_fma_f32 v[154:155], v[46:47], v[162:163], v[158:159]
	global_store_dwordx4 v3, v[152:155], s[36:37] offset:-1024
	v_lshlrev_b32_e32 v140, 16, v72
	v_and_b32_e32 v141, 0xffff0000, v72
; __device__ __forceinline__ float rstd_of(float ss, float inv_n) { return __builtin_amdgcn_rsqf(ss * inv_n + 1e-6f); }
; __device__ __forceinline__ float bf_lo(unsigned w) { return __uint_as_float(w << 16); }
; __device__ __forceinline__ float bf_hi(unsigned w) { return __uint_as_float(w & 0xffff0000u); }
; #define GAS __attribute__((address_space(1)))
; __global__ void __launch_bounds__(NTHREADS, 2) mk_fwd(Args args) {
;     ...
;     if (PH(11)) { FRESH_IDS const bf16* E = (const bf16*)(ws + WS_E); const float* sse = stat + ST_SSE * MROWS; const int gw = bx * NWAVES + wave, NGW = G * NWAVES;
;         for (int m = gw; m < MROWS; m += NGW) { const float r = pg8::rstd_of(sse[m], 1.0f / 2048.0f); GAS f32x4* xr = (GAS f32x4*)(out + (size_t)m * DM) + lane; const GAS v2u* xbr = (const GAS v2u*)(XB + (size_t)m * DM) + lane; const GAS v2u* er = (const GAS v2u*)(E + (size_t)m * DM) + lane;
;             const GAS f32x4* gp = (const GAS f32x4*)in.ple_post + lane;
; #pragma unroll
;             for (int j = 0; j < 8; ++j) { const v2u xw = xbr[64 * j]; const v2u w = er[64 * j]; const f32x4 gg = gp[64 * j]; f32x4 v;
;                 v.x = pg8::bf_lo(xw.x) + pg8::bf_lo(w.x) * r * gg.x; v.y = pg8::bf_hi(xw.x) + pg8::bf_hi(w.x) * r * gg.y; v.z = pg8::bf_lo(xw.y) + pg8::bf_lo(w.y) * r * gg.z; v.w = pg8::bf_hi(xw.y) + pg8::bf_hi(w.y) * r * gg.w; xr[64 * j] = v; } } }
	v_lshlrev_b32_e32 v142, 16, v73
	v_and_b32_e32 v143, 0xffff0000, v73
	v_lshlrev_b32_e32 v144, 16, v88
	v_and_b32_e32 v145, 0xffff0000, v88
	v_lshlrev_b32_e32 v146, 16, v89
	v_and_b32_e32 v147, 0xffff0000, v89
	v_pk_mul_f32 v[144:145], v[0:1], v[144:145] op_sel_hi:[0,1]
	v_pk_mul_f32 v[146:147], v[0:1], v[146:147] op_sel_hi:[0,1]
	v_pk_fma_f32 v[148:149], v[48:49], v[144:145], v[140:141]
	v_pk_fma_f32 v[150:151], v[50:51], v[146:147], v[142:143]
	global_store_dwordx4 v3, v[148:151], s[36:37] offset:0
	v_lshlrev_b32_e32 v156, 16, v74
	v_and_b32_e32 v157, 0xffff0000, v74
	v_lshlrev_b32_e32 v158, 16, v75
	v_and_b32_e32 v159, 0xffff0000, v75
	v_lshlrev_b32_e32 v160, 16, v90
	v_and_b32_e32 v161, 0xffff0000, v90
	v_lshlrev_b32_e32 v162, 16, v91
	v_and_b32_e32 v163, 0xffff0000, v91
	v_pk_mul_f32 v[160:161], v[0:1], v[160:161] op_sel_hi:[0,1]
	v_pk_mul_f32 v[162:163], v[0:1], v[162:163] op_sel_hi:[0,1]
	v_pk_fma_f32 v[152:153], v[52:53], v[160:161], v[156:157]
	v_pk_fma_f32 v[154:155], v[54:55], v[162:163], v[158:159]
	global_store_dwordx4 v3, v[152:155], s[36:37] offset:1024
	v_lshlrev_b32_e32 v140, 16, v76
	v_and_b32_e32 v141, 0xffff0000, v76
	v_lshlrev_b32_e32 v142, 16, v77
	v_and_b32_e32 v143, 0xffff0000, v77
	v_lshlrev_b32_e32 v144, 16, v92
	v_and_b32_e32 v145, 0xffff0000, v92
	v_lshlrev_b32_e32 v146, 16, v93
	v_and_b32_e32 v147, 0xffff0000, v93
	v_pk_mul_f32 v[144:145], v[0:1], v[144:145] op_sel_hi:[0,1]
	v_pk_mul_f32 v[146:147], v[0:1], v[146:147] op_sel_hi:[0,1]
	v_pk_fma_f32 v[148:149], v[56:57], v[144:145], v[140:141]
	v_pk_fma_f32 v[150:151], v[58:59], v[146:147], v[142:143]
	global_store_dwordx4 v3, v[148:151], s[36:37] offset:2048
	v_lshlrev_b32_e32 v156, 16, v78
	v_and_b32_e32 v157, 0xffff0000, v78
	v_lshlrev_b32_e32 v158, 16, v79
	v_and_b32_e32 v159, 0xffff0000, v79
	v_lshlrev_b32_e32 v160, 16, v94
	v_and_b32_e32 v161, 0xffff0000, v94
	v_lshlrev_b32_e32 v162, 16, v95
	v_and_b32_e32 v163, 0xffff0000, v95
	v_pk_mul_f32 v[160:161], v[0:1], v[160:161] op_sel_hi:[0,1]
	v_pk_mul_f32 v[162:163], v[0:1], v[162:163] op_sel_hi:[0,1]
	v_pk_fma_f32 v[152:153], v[60:61], v[160:161], v[156:157]
	v_pk_fma_f32 v[154:155], v[62:63], v[162:163], v[158:159]
	global_store_dwordx4 v3, v[152:155], s[36:37] offset:3072
	s_branch .Lp11_next_f
.Lp11_last_f:
	s_waitcnt vmcnt(0)
	v_fmamk_f32 v0, v96, 0x3a000000, v16
	v_rsq_f32_e32 v0, v0
	v_lshlrev_b32_e32 v140, 16, v64
	v_and_b32_e32 v141, 0xffff0000, v64
	v_lshlrev_b32_e32 v142, 16, v65
	v_and_b32_e32 v143, 0xffff0000, v65
	v_lshlrev_b32_e32 v144, 16, v80
	v_and_b32_e32 v145, 0xffff0000, v80
	v_lshlrev_b32_e32 v146, 16, v81
	v_and_b32_e32 v147, 0xffff0000, v81
	v_pk_mul_f32 v[144:145], v[0:1], v[144:145] op_sel_hi:[0,1]
	v_pk_mul_f32 v[146:147], v[0:1], v[146:147] op_sel_hi:[0,1]
	v_pk_fma_f32 v[148:149], v[32:33], v[144:145], v[140:141]
	v_pk_fma_f32 v[150:151], v[34:35], v[146:147], v[142:143]
	global_store_dwordx4 v3, v[148:151], s[36:37] offset:-4096
	v_lshlrev_b32_e32 v156, 16, v66
	v_and_b32_e32 v157, 0xffff0000, v66
	v_lshlrev_b32_e32 v158, 16, v67
	v_and_b32_e32 v159, 0xffff0000, v67
	v_lshlrev_b32_e32 v160, 16, v82
	v_and_b32_e32 v161, 0xffff0000, v82
	v_lshlrev_b32_e32 v162, 16, v83
	v_and_b32_e32 v163, 0xffff0000, v83
	v_pk_mul_f32 v[160:161], v[0:1], v[160:161] op_sel_hi:[0,1]
	v_pk_mul_f32 v[162:163], v[0:1], v[162:163] op_sel_hi:[0,1]
	v_pk_fma_f32 v[152:153], v[36:37], v[160:161], v[156:157]
	v_pk_fma_f32 v[154:155], v[38:39], v[162:163], v[158:159]
	global_store_dwordx4 v3, v[152:155], s[36:37] offset:-3072
	v_lshlrev_b32_e32 v140, 16, v68
	v_and_b32_e32 v141, 0xffff0000, v68
	v_lshlrev_b32_e32 v142, 16, v69
	v_and_b32_e32 v143, 0xffff0000, v69
	v_lshlrev_b32_e32 v144, 16, v84
	v_and_b32_e32 v145, 0xffff0000, v84
	v_lshlrev_b32_e32 v146, 16, v85
	v_and_b32_e32 v147, 0xffff0000, v85
	v_pk_mul_f32 v[144:145], v[0:1], v[144:145] op_sel_hi:[0,1]
	v_pk_mul_f32 v[146:147], v[0:1], v[146:147] op_sel_hi:[0,1]
	v_pk_fma_f32 v[148:149], v[40:41], v[144:145], v[140:141]
	v_pk_fma_f32 v[150:151], v[42:43], v[146:147], v[142:143]
	global_store_dwordx4 v3, v[148:151], s[36:37] offset:-2048
	v_lshlrev_b32_e32 v156, 16, v70
	v_and_b32_e32 v157, 0xffff0000, v70
	v_lshlrev_b32_e32 v158, 16, v71
	v_and_b32_e32 v159, 0xffff0000, v71
	v_lshlrev_b32_e32 v160, 16, v86
	v_and_b32_e32 v161, 0xffff0000, v86
	v_lshlrev_b32_e32 v162, 16, v87
	v_and_b32_e32 v163, 0xffff0000, v87
	v_pk_mul_f32 v[160:161], v[0:1], v[160:161] op_sel_hi:[0,1]
	v_pk_mul_f32 v[162:163], v[0:1], v[162:163] op_sel_hi:[0,1]
	v_pk_fma_f32 v[152:153], v[44:45], v[160:161], v[156:157]
	v_pk_fma_f32 v[154:155], v[46:47], v[162:163], v[158:159]
	global_store_dwordx4 v3, v[152:155], s[36:37] offset:-1024
	v_lshlrev_b32_e32 v140, 16, v72
	v_and_b32_e32 v141, 0xffff0000, v72
	v_lshlrev_b32_e32 v142, 16, v73
	v_and_b32_e32 v143, 0xffff0000, v73
	v_lshlrev_b32_e32 v144, 16, v88
	v_and_b32_e32 v145, 0xffff0000, v88
	v_lshlrev_b32_e32 v146, 16, v89
	v_and_b32_e32 v147, 0xffff0000, v89
	v_pk_mul_f32 v[144:145], v[0:1], v[144:145] op_sel_hi:[0,1]
	v_pk_mul_f32 v[146:147], v[0:1], v[146:147] op_sel_hi:[0,1]
	v_pk_fma_f32 v[148:149], v[48:49], v[144:145], v[140:141]
	v_pk_fma_f32 v[150:151], v[50:51], v[146:147], v[142:143]
	global_store_dwordx4 v3, v[148:151], s[36:37] offset:0
	v_lshlrev_b32_e32 v156, 16, v74
	v_and_b32_e32 v157, 0xffff0000, v74
	v_lshlrev_b32_e32 v158, 16, v75
	v_and_b32_e32 v159, 0xffff0000, v75
	v_lshlrev_b32_e32 v160, 16, v90
	v_and_b32_e32 v161, 0xffff0000, v90
	v_lshlrev_b32_e32 v162, 16, v91
	v_and_b32_e32 v163, 0xffff0000, v91
	v_pk_mul_f32 v[160:161], v[0:1], v[160:161] op_sel_hi:[0,1]
	v_pk_mul_f32 v[162:163], v[0:1], v[162:163] op_sel_hi:[0,1]
	v_pk_fma_f32 v[152:153], v[52:53], v[160:161], v[156:157]
	v_pk_fma_f32 v[154:155], v[54:55], v[162:163], v[158:159]
	global_store_dwordx4 v3, v[152:155], s[36:37] offset:1024
	v_lshlrev_b32_e32 v140, 16, v76
	v_and_b32_e32 v141, 0xffff0000, v76
	v_lshlrev_b32_e32 v142, 16, v77
	v_and_b32_e32 v143, 0xffff0000, v77
	v_lshlrev_b32_e32 v144, 16, v92
	v_and_b32_e32 v145, 0xffff0000, v92
	v_lshlrev_b32_e32 v146, 16, v93
	v_and_b32_e32 v147, 0xffff0000, v93
	v_pk_mul_f32 v[144:145], v[0:1], v[144:145] op_sel_hi:[0,1]
	v_pk_mul_f32 v[146:147], v[0:1], v[146:147] op_sel_hi:[0,1]
	v_pk_fma_f32 v[148:149], v[56:57], v[144:145], v[140:141]
	v_pk_fma_f32 v[150:151], v[58:59], v[146:147], v[142:143]
	global_store_dwordx4 v3, v[148:151], s[36:37] offset:2048
	v_lshlrev_b32_e32 v156, 16, v78
	v_and_b32_e32 v157, 0xffff0000, v78
	v_lshlrev_b32_e32 v158, 16, v79
	v_and_b32_e32 v159, 0xffff0000, v79
	v_lshlrev_b32_e32 v160, 16, v94
	v_and_b32_e32 v161, 0xffff0000, v94
	v_lshlrev_b32_e32 v162, 16, v95
	v_and_b32_e32 v163, 0xffff0000, v95
	v_pk_mul_f32 v[160:161], v[0:1], v[160:161] op_sel_hi:[0,1]
	v_pk_mul_f32 v[162:163], v[0:1], v[162:163] op_sel_hi:[0,1]
	v_pk_fma_f32 v[152:153], v[60:61], v[160:161], v[156:157]
	v_pk_fma_f32 v[154:155], v[62:63], v[162:163], v[158:159]
	global_store_dwordx4 v3, v[152:155], s[36:37] offset:3072
	s_endpgm
; __device__ __forceinline__ float rstd_of(float ss, float inv_n) { return __builtin_amdgcn_rsqf(ss * inv_n + 1e-6f); }
; __device__ __forceinline__ float bf_lo(unsigned w) { return __uint_as_float(w << 16); }
; __device__ __forceinline__ float bf_hi(unsigned w) { return __uint_as_float(w & 0xffff0000u); }
; #define GAS __attribute__((address_space(1)))
; __global__ void __launch_bounds__(NTHREADS, 2) mk_fwd(Args args) {
;     ...
;     if (PH(11)) { FRESH_IDS const bf16* E = (const bf16*)(ws + WS_E); const float* sse = stat + ST_SSE * MROWS; const int gw = bx * NWAVES + wave, NGW = G * NWAVES;
;         for (int m = gw; m < MROWS; m += NGW) { const float r = pg8::rstd_of(sse[m], 1.0f / 2048.0f); GAS f32x4* xr = (GAS f32x4*)(out + (size_t)m * DM) + lane; const GAS v2u* xbr = (const GAS v2u*)(XB + (size_t)m * DM) + lane; const GAS v2u* er = (const GAS v2u*)(E + (size_t)m * DM) + lane;
;             const GAS f32x4* gp = (const GAS f32x4*)in.ple_post + lane;
; #pragma unroll
;             for (int j = 0; j < 8; ++j) { const v2u xw = xbr[64 * j]; const v2u w = er[64 * j]; const f32x4 gg = gp[64 * j]; f32x4 v;
;                 v.x = pg8::bf_lo(xw.x) + pg8::bf_lo(w.x) * r * gg.x; v.y = pg8::bf_hi(xw.x) + pg8::bf_hi(w.x) * r * gg.y; v.z = pg8::bf_lo(xw.y) + pg8::bf_lo(w.y) * r * gg.z; v.w = pg8::bf_hi(xw.y) + pg8::bf_hi(w.y) * r * gg.w; xr[64 * j] = v; } } }
.Lp11_next_f:
.Lp11_loop:
	s_lshl_b32 s42, s24, 13
	s_add_u32 s36, s22, s42
	s_addc_u32 s37, s23, 0
	s_add_i32 s24, s24, s26
	s_cmpk_gt_i32 s24, 0x7fff
	s_cbranch_scc1 .Lp11_last_b
	s_lshl_b32 s40, s24, 12
	s_add_u32 s30, s16, s40
	s_addc_u32 s31, s17, 0
	s_add_u32 s32, s18, s40
	s_addc_u32 s33, s19, 0
	s_lshl_b32 s41, s24, 2
	s_add_u32 s34, s20, s41
	s_addc_u32 s35, s21, 0
	global_load_dword v96, v1, s[34:35]
	global_load_dwordx2 v[64:65], v2, s[30:31]
	global_load_dwordx2 v[80:81], v2, s[32:33]
	global_load_dwordx2 v[66:67], v2, s[30:31] offset:512
	global_load_dwordx2 v[82:83], v2, s[32:33] offset:512
	global_load_dwordx2 v[68:69], v2, s[30:31] offset:1024
	global_load_dwordx2 v[84:85], v2, s[32:33] offset:1024
	global_load_dwordx2 v[70:71], v2, s[30:31] offset:1536
	global_load_dwordx2 v[86:87], v2, s[32:33] offset:1536
	global_load_dwordx2 v[72:73], v2, s[30:31] offset:2048
	global_load_dwordx2 v[88:89], v2, s[32:33] offset:2048
	global_load_dwordx2 v[74:75], v2, s[30:31] offset:2560
	global_load_dwordx2 v[90:91], v2, s[32:33] offset:2560
	global_load_dwordx2 v[76:77], v2, s[30:31] offset:3072
	global_load_dwordx2 v[92:93], v2, s[32:33] offset:3072
	global_load_dwordx2 v[78:79], v2, s[30:31] offset:3584
	global_load_dwordx2 v[94:95], v2, s[32:33] offset:3584
	s_waitcnt vmcnt(25)
	v_fmamk_f32 v0, v132, 0x3a000000, v16
	v_rsq_f32_e32 v0, v0
	v_lshlrev_b32_e32 v140, 16, v100
	v_and_b32_e32 v141, 0xffff0000, v100
	v_lshlrev_b32_e32 v142, 16, v101
	v_and_b32_e32 v143, 0xffff0000, v101
	v_lshlrev_b32_e32 v144, 16, v116
	v_and_b32_e32 v145, 0xffff0000, v116
	v_lshlrev_b32_e32 v146, 16, v117
	v_and_b32_e32 v147, 0xffff0000, v117
	v_pk_mul_f32 v[144:145], v[0:1], v[144:145] op_sel_hi:[0,1]
	v_pk_mul_f32 v[146:147], v[0:1], v[146:147] op_sel_hi:[0,1]
	v_pk_fma_f32 v[148:149], v[32:33], v[144:145], v[140:141]
	v_pk_fma_f32 v[150:151], v[34:35], v[146:147], v[142:143]
	global_store_dwordx4 v3, v[148:151], s[36:37] offset:-4096
	v_lshlrev_b32_e32 v156, 16, v102
	v_and_b32_e32 v157, 0xffff0000, v102
	v_lshlrev_b32_e32 v158, 16, v103
	v_and_b32_e32 v159, 0xffff0000, v103
	v_lshlrev_b32_e32 v160, 16, v118
	v_and_b32_e32 v161, 0xffff0000, v118
	v_lshlrev_b32_e32 v162, 16, v119
	v_and_b32_e32 v163, 0xffff0000, v119
	v_pk_mul_f32 v[160:161], v[0:1], v[160:161] op_sel_hi:[0,1]
	v_pk_mul_f32 v[162:163], v[0:1], v[162:163] op_sel_hi:[0,1]
	v_pk_fma_f32 v[152:153], v[36:37], v[160:161], v[156:157]
	v_pk_fma_f32 v[154:155], v[38:39], v[162:163], v[158:159]
	global_store_dwordx4 v3, v[152:155], s[36:37] offset:-3072
	v_lshlrev_b32_e32 v140, 16, v104
	v_and_b32_e32 v141, 0xffff0000, v104
	v_lshlrev_b32_e32 v142, 16, v105
	v_and_b32_e32 v143, 0xffff0000, v105
	v_lshlrev_b32_e32 v144, 16, v120
	v_and_b32_e32 v145, 0xffff0000, v120
	v_lshlrev_b32_e32 v146, 16, v121
	v_and_b32_e32 v147, 0xffff0000, v121
	v_pk_mul_f32 v[144:145], v[0:1], v[144:145] op_sel_hi:[0,1]
	v_pk_mul_f32 v[146:147], v[0:1], v[146:147] op_sel_hi:[0,1]
	v_pk_fma_f32 v[148:149], v[40:41], v[144:145], v[140:141]
	v_pk_fma_f32 v[150:151], v[42:43], v[146:147], v[142:143]
	global_store_dwordx4 v3, v[148:151], s[36:37] offset:-2048
	v_lshlrev_b32_e32 v156, 16, v106
	v_and_b32_e32 v157, 0xffff0000, v106
	v_lshlrev_b32_e32 v158, 16, v107
	v_and_b32_e32 v159, 0xffff0000, v107
	v_lshlrev_b32_e32 v160, 16, v122
	v_and_b32_e32 v161, 0xffff0000, v122
	v_lshlrev_b32_e32 v162, 16, v123
	v_and_b32_e32 v163, 0xffff0000, v123
	v_pk_mul_f32 v[160:161], v[0:1], v[160:161] op_sel_hi:[0,1]
	v_pk_mul_f32 v[162:163], v[0:1], v[162:163] op_sel_hi:[0,1]
	v_pk_fma_f32 v[152:153], v[44:45], v[160:161], v[156:157]
	v_pk_fma_f32 v[154:155], v[46:47], v[162:163], v[158:159]
	global_store_dwordx4 v3, v[152:155], s[36:37] offset:-1024
	v_lshlrev_b32_e32 v140, 16, v108
	v_and_b32_e32 v141, 0xffff0000, v108
	v_lshlrev_b32_e32 v142, 16, v109
	v_and_b32_e32 v143, 0xffff0000, v109
	v_lshlrev_b32_e32 v144, 16, v124
	v_and_b32_e32 v145, 0xffff0000, v124
	v_lshlrev_b32_e32 v146, 16, v125
	v_and_b32_e32 v147, 0xffff0000, v125
	v_pk_mul_f32 v[144:145], v[0:1], v[144:145] op_sel_hi:[0,1]
	v_pk_mul_f32 v[146:147], v[0:1], v[146:147] op_sel_hi:[0,1]
	v_pk_fma_f32 v[148:149], v[48:49], v[144:145], v[140:141]
	v_pk_fma_f32 v[150:151], v[50:51], v[146:147], v[142:143]
	global_store_dwordx4 v3, v[148:151], s[36:37] offset:0
	v_lshlrev_b32_e32 v156, 16, v110
	v_and_b32_e32 v157, 0xffff0000, v110
	v_lshlrev_b32_e32 v158, 16, v111
	v_and_b32_e32 v159, 0xffff0000, v111
	v_lshlrev_b32_e32 v160, 16, v126
	v_and_b32_e32 v161, 0xffff0000, v126
	v_lshlrev_b32_e32 v162, 16, v127
	v_and_b32_e32 v163, 0xffff0000, v127
	v_pk_mul_f32 v[160:161], v[0:1], v[160:161] op_sel_hi:[0,1]
	v_pk_mul_f32 v[162:163], v[0:1], v[162:163] op_sel_hi:[0,1]
	v_pk_fma_f32 v[152:153], v[52:53], v[160:161], v[156:157]
	v_pk_fma_f32 v[154:155], v[54:55], v[162:163], v[158:159]
	global_store_dwordx4 v3, v[152:155], s[36:37] offset:1024
	v_lshlrev_b32_e32 v140, 16, v112
	v_and_b32_e32 v141, 0xffff0000, v112
	v_lshlrev_b32_e32 v142, 16, v113
	v_and_b32_e32 v143, 0xffff0000, v113
	v_lshlrev_b32_e32 v144, 16, v128
	v_and_b32_e32 v145, 0xffff0000, v128
	v_lshlrev_b32_e32 v146, 16, v129
	v_and_b32_e32 v147, 0xffff0000, v129
	v_pk_mul_f32 v[144:145], v[0:1], v[144:145] op_sel_hi:[0,1]
	v_pk_mul_f32 v[146:147], v[0:1], v[146:147] op_sel_hi:[0,1]
	v_pk_fma_f32 v[148:149], v[56:57], v[144:145], v[140:141]
	v_pk_fma_f32 v[150:151], v[58:59], v[146:147], v[142:143]
	global_store_dwordx4 v3, v[148:151], s[36:37] offset:2048
	v_lshlrev_b32_e32 v156, 16, v114
	v_and_b32_e32 v157, 0xffff0000, v114
	v_lshlrev_b32_e32 v158, 16, v115
	v_and_b32_e32 v159, 0xffff0000, v115
	v_lshlrev_b32_e32 v160, 16, v130
	v_and_b32_e32 v161, 0xffff0000, v130
	v_lshlrev_b32_e32 v162, 16, v131
	v_and_b32_e32 v163, 0xffff0000, v131
	v_pk_mul_f32 v[160:161], v[0:1], v[160:161] op_sel_hi:[0,1]
	v_pk_mul_f32 v[162:163], v[0:1], v[162:163] op_sel_hi:[0,1]
	v_pk_fma_f32 v[152:153], v[60:61], v[160:161], v[156:157]
	v_pk_fma_f32 v[154:155], v[62:63], v[162:163], v[158:159]
	global_store_dwordx4 v3, v[152:155], s[36:37] offset:3072
	s_branch .Lp11_next_b
; __device__ __forceinline__ float rstd_of(float ss, float inv_n) { return __builtin_amdgcn_rsqf(ss * inv_n + 1e-6f); }
; __device__ __forceinline__ float bf_lo(unsigned w) { return __uint_as_float(w << 16); }
; __device__ __forceinline__ float bf_hi(unsigned w) { return __uint_as_float(w & 0xffff0000u); }
; #define GAS __attribute__((address_space(1)))
; __global__ void __launch_bounds__(NTHREADS, 2) mk_fwd(Args args) {
;     ...
;     if (PH(11)) { FRESH_IDS const bf16* E = (const bf16*)(ws + WS_E); const float* sse = stat + ST_SSE * MROWS; const int gw = bx * NWAVES + wave, NGW = G * NWAVES;
;         for (int m = gw; m < MROWS; m += NGW) { const float r = pg8::rstd_of(sse[m], 1.0f / 2048.0f); GAS f32x4* xr = (GAS f32x4*)(out + (size_t)m * DM) + lane; const GAS v2u* xbr = (const GAS v2u*)(XB + (size_t)m * DM) + lane; const GAS v2u* er = (const GAS v2u*)(E + (size_t)m * DM) + lane;
;             const GAS f32x4* gp = (const GAS f32x4*)in.ple_post + lane;
; #pragma unroll
;             for (int j = 0; j < 8; ++j) { const v2u xw = xbr[64 * j]; const v2u w = er[64 * j]; const f32x4 gg = gp[64 * j]; f32x4 v;
;                 v.x = pg8::bf_lo(xw.x) + pg8::bf_lo(w.x) * r * gg.x; v.y = pg8::bf_hi(xw.x) + pg8::bf_hi(w.x) * r * gg.y; v.z = pg8::bf_lo(xw.y) + pg8::bf_lo(w.y) * r * gg.z; v.w = pg8::bf_hi(xw.y) + pg8::bf_hi(w.y) * r * gg.w; xr[64 * j] = v; } } }
.Lp11_last_b:
	s_waitcnt vmcnt(8)
	v_fmamk_f32 v0, v132, 0x3a000000, v16
	v_rsq_f32_e32 v0, v0
	v_lshlrev_b32_e32 v140, 16, v100
	v_and_b32_e32 v141, 0xffff0000, v100
	v_lshlrev_b32_e32 v142, 16, v101
	v_and_b32_e32 v143, 0xffff0000, v101
	v_lshlrev_b32_e32 v144, 16, v116
	v_and_b32_e32 v145, 0xffff0000, v116
	v_lshlrev_b32_e32 v146, 16, v117
	v_and_b32_e32 v147, 0xffff0000, v117
	v_pk_mul_f32 v[144:145], v[0:1], v[144:145] op_sel_hi:[0,1]
	v_pk_mul_f32 v[146:147], v[0:1], v[146:147] op_sel_hi:[0,1]
	v_pk_fma_f32 v[148:149], v[32:33], v[144:145], v[140:141]
	v_pk_fma_f32 v[150:151], v[34:35], v[146:147], v[142:143]
	global_store_dwordx4 v3, v[148:151], s[36:37] offset:-4096
	v_lshlrev_b32_e32 v156, 16, v102
	v_and_b32_e32 v157, 0xffff0000, v102
	v_lshlrev_b32_e32 v158, 16, v103
	v_and_b32_e32 v159, 0xffff0000, v103
	v_lshlrev_b32_e32 v160, 16, v118
	v_and_b32_e32 v161, 0xffff0000, v118
	v_lshlrev_b32_e32 v162, 16, v119
	v_and_b32_e32 v163, 0xffff0000, v119
	v_pk_mul_f32 v[160:161], v[0:1], v[160:161] op_sel_hi:[0,1]
	v_pk_mul_f32 v[162:163], v[0:1], v[162:163] op_sel_hi:[0,1]
	v_pk_fma_f32 v[152:153], v[36:37], v[160:161], v[156:157]
	v_pk_fma_f32 v[154:155], v[38:39], v[162:163], v[158:159]
	global_store_dwordx4 v3, v[152:155], s[36:37] offset:-3072
	v_lshlrev_b32_e32 v140, 16, v104
	v_and_b32_e32 v141, 0xffff0000, v104
	v_lshlrev_b32_e32 v142, 16, v105
	v_and_b32_e32 v143, 0xffff0000, v105
	v_lshlrev_b32_e32 v144, 16, v120
	v_and_b32_e32 v145, 0xffff0000, v120
	v_lshlrev_b32_e32 v146, 16, v121
	v_and_b32_e32 v147, 0xffff0000, v121
	v_pk_mul_f32 v[144:145], v[0:1], v[144:145] op_sel_hi:[0,1]
	v_pk_mul_f32 v[146:147], v[0:1], v[146:147] op_sel_hi:[0,1]
	v_pk_fma_f32 v[148:149], v[40:41], v[144:145], v[140:141]
	v_pk_fma_f32 v[150:151], v[42:43], v[146:147], v[142:143]
	global_store_dwordx4 v3, v[148:151], s[36:37] offset:-2048
	v_lshlrev_b32_e32 v156, 16, v106
	v_and_b32_e32 v157, 0xffff0000, v106
	v_lshlrev_b32_e32 v158, 16, v107
	v_and_b32_e32 v159, 0xffff0000, v107
	v_lshlrev_b32_e32 v160, 16, v122
	v_and_b32_e32 v161, 0xffff0000, v122
	v_lshlrev_b32_e32 v162, 16, v123
	v_and_b32_e32 v163, 0xffff0000, v123
	v_pk_mul_f32 v[160:161], v[0:1], v[160:161] op_sel_hi:[0,1]
	v_pk_mul_f32 v[162:163], v[0:1], v[162:163] op_sel_hi:[0,1]
	v_pk_fma_f32 v[152:153], v[44:45], v[160:161], v[156:157]
	v_pk_fma_f32 v[154:155], v[46:47], v[162:163], v[158:159]
	global_store_dwordx4 v3, v[152:155], s[36:37] offset:-1024
	v_lshlrev_b32_e32 v140, 16, v108
	v_and_b32_e32 v141, 0xffff0000, v108
	v_lshlrev_b32_e32 v142, 16, v109
	v_and_b32_e32 v143, 0xffff0000, v109
	v_lshlrev_b32_e32 v144, 16, v124
	v_and_b32_e32 v145, 0xffff0000, v124
	v_lshlrev_b32_e32 v146, 16, v125
	v_and_b32_e32 v147, 0xffff0000, v125
	v_pk_mul_f32 v[144:145], v[0:1], v[144:145] op_sel_hi:[0,1]
	v_pk_mul_f32 v[146:147], v[0:1], v[146:147] op_sel_hi:[0,1]
	v_pk_fma_f32 v[148:149], v[48:49], v[144:145], v[140:141]
	v_pk_fma_f32 v[150:151], v[50:51], v[146:147], v[142:143]
	global_store_dwordx4 v3, v[148:151], s[36:37] offset:0
	v_lshlrev_b32_e32 v156, 16, v110
	v_and_b32_e32 v157, 0xffff0000, v110
	v_lshlrev_b32_e32 v158, 16, v111
	v_and_b32_e32 v159, 0xffff0000, v111
	v_lshlrev_b32_e32 v160, 16, v126
	v_and_b32_e32 v161, 0xffff0000, v126
	v_lshlrev_b32_e32 v162, 16, v127
	v_and_b32_e32 v163, 0xffff0000, v127
	v_pk_mul_f32 v[160:161], v[0:1], v[160:161] op_sel_hi:[0,1]
	v_pk_mul_f32 v[162:163], v[0:1], v[162:163] op_sel_hi:[0,1]
	v_pk_fma_f32 v[152:153], v[52:53], v[160:161], v[156:157]
	v_pk_fma_f32 v[154:155], v[54:55], v[162:163], v[158:159]
	global_store_dwordx4 v3, v[152:155], s[36:37] offset:1024
	v_lshlrev_b32_e32 v140, 16, v112
	v_and_b32_e32 v141, 0xffff0000, v112
	v_lshlrev_b32_e32 v142, 16, v113
	v_and_b32_e32 v143, 0xffff0000, v113
	v_lshlrev_b32_e32 v144, 16, v128
	v_and_b32_e32 v145, 0xffff0000, v128
	v_lshlrev_b32_e32 v146, 16, v129
	v_and_b32_e32 v147, 0xffff0000, v129
	v_pk_mul_f32 v[144:145], v[0:1], v[144:145] op_sel_hi:[0,1]
	v_pk_mul_f32 v[146:147], v[0:1], v[146:147] op_sel_hi:[0,1]
	v_pk_fma_f32 v[148:149], v[56:57], v[144:145], v[140:141]
	v_pk_fma_f32 v[150:151], v[58:59], v[146:147], v[142:143]
	global_store_dwordx4 v3, v[148:151], s[36:37] offset:2048
	v_lshlrev_b32_e32 v156, 16, v114
	v_and_b32_e32 v157, 0xffff0000, v114
	v_lshlrev_b32_e32 v158, 16, v115
	v_and_b32_e32 v159, 0xffff0000, v115
	v_lshlrev_b32_e32 v160, 16, v130
	v_and_b32_e32 v161, 0xffff0000, v130
	v_lshlrev_b32_e32 v162, 16, v131
	v_and_b32_e32 v163, 0xffff0000, v131
	v_pk_mul_f32 v[160:161], v[0:1], v[160:161] op_sel_hi:[0,1]
	v_pk_mul_f32 v[162:163], v[0:1], v[162:163] op_sel_hi:[0,1]
	v_pk_fma_f32 v[152:153], v[60:61], v[160:161], v[156:157]
	v_pk_fma_f32 v[154:155], v[62:63], v[162:163], v[158:159]
	global_store_dwordx4 v3, v[152:155], s[36:37] offset:3072
	s_endpgm
; __device__ __forceinline__ float rstd_of(float ss, float inv_n) { return __builtin_amdgcn_rsqf(ss * inv_n + 1e-6f); }
; __device__ __forceinline__ float bf_lo(unsigned w) { return __uint_as_float(w << 16); }
; __device__ __forceinline__ float bf_hi(unsigned w) { return __uint_as_float(w & 0xffff0000u); }
; #define GAS __attribute__((address_space(1)))
; __global__ void __launch_bounds__(NTHREADS, 2) mk_fwd(Args args) {
;     ...
;     if (PH(11)) { FRESH_IDS const bf16* E = (const bf16*)(ws + WS_E); const float* sse = stat + ST_SSE * MROWS; const int gw = bx * NWAVES + wave, NGW = G * NWAVES;
;         for (int m = gw; m < MROWS; m += NGW) { const float r = pg8::rstd_of(sse[m], 1.0f / 2048.0f); GAS f32x4* xr = (GAS f32x4*)(out + (size_t)m * DM) + lane; const GAS v2u* xbr = (const GAS v2u*)(XB + (size_t)m * DM) + lane; const GAS v2u* er = (const GAS v2u*)(E + (size_t)m * DM) + lane;
;             const GAS f32x4* gp = (const GAS f32x4*)in.ple_post + lane;
; #pragma unroll
;             for (int j = 0; j < 8; ++j) { const v2u xw = xbr[64 * j]; const v2u w = er[64 * j]; const f32x4 gg = gp[64 * j]; f32x4 v;
;                 v.x = pg8::bf_lo(xw.x) + pg8::bf_lo(w.x) * r * gg.x; v.y = pg8::bf_hi(xw.x) + pg8::bf_hi(w.x) * r * gg.y; v.z = pg8::bf_lo(xw.y) + pg8::bf_lo(w.y) * r * gg.z; v.w = pg8::bf_hi(xw.y) + pg8::bf_hi(w.y) * r * gg.w; xr[64 * j] = v; } } }
.Lp11_next_b:
	s_lshl_b32 s42, s24, 13
	s_add_u32 s36, s22, s42
	s_addc_u32 s37, s23, 0
	s_add_i32 s24, s24, s26
	s_cmpk_gt_i32 s24, 0x7fff
	s_cbranch_scc1 .Lp11_last_a
	s_lshl_b32 s40, s24, 12
	s_add_u32 s30, s16, s40
	s_addc_u32 s31, s17, 0
	s_add_u32 s32, s18, s40
	s_addc_u32 s33, s19, 0
	s_lshl_b32 s41, s24, 2
	s_add_u32 s34, s20, s41
	s_addc_u32 s35, s21, 0
	global_load_dword v132, v1, s[34:35]
	global_load_dwordx2 v[100:101], v2, s[30:31]
	global_load_dwordx2 v[116:117], v2, s[32:33]
	global_load_dwordx2 v[102:103], v2, s[30:31] offset:512
	global_load_dwordx2 v[118:119], v2, s[32:33] offset:512
	global_load_dwordx2 v[104:105], v2, s[30:31] offset:1024
	global_load_dwordx2 v[120:121], v2, s[32:33] offset:1024
	global_load_dwordx2 v[106:107], v2, s[30:31] offset:1536
	global_load_dwordx2 v[122:123], v2, s[32:33] offset:1536
	global_load_dwordx2 v[108:109], v2, s[30:31] offset:2048
	global_load_dwordx2 v[124:125], v2, s[32:33] offset:2048
	global_load_dwordx2 v[110:111], v2, s[30:31] offset:2560
	global_load_dwordx2 v[126:127], v2, s[32:33] offset:2560
	global_load_dwordx2 v[112:113], v2, s[30:31] offset:3072
	global_load_dwordx2 v[128:129], v2, s[32:33] offset:3072
	global_load_dwordx2 v[114:115], v2, s[30:31] offset:3584
	global_load_dwordx2 v[130:131], v2, s[32:33] offset:3584
	s_waitcnt vmcnt(25)
	v_fmamk_f32 v0, v96, 0x3a000000, v16
	v_rsq_f32_e32 v0, v0
	v_lshlrev_b32_e32 v140, 16, v64
	v_and_b32_e32 v141, 0xffff0000, v64
	v_lshlrev_b32_e32 v142, 16, v65
	v_and_b32_e32 v143, 0xffff0000, v65
	v_lshlrev_b32_e32 v144, 16, v80
	v_and_b32_e32 v145, 0xffff0000, v80
	v_lshlrev_b32_e32 v146, 16, v81
	v_and_b32_e32 v147, 0xffff0000, v81
	v_pk_mul_f32 v[144:145], v[0:1], v[144:145] op_sel_hi:[0,1]
	v_pk_mul_f32 v[146:147], v[0:1], v[146:147] op_sel_hi:[0,1]
	v_pk_fma_f32 v[148:149], v[32:33], v[144:145], v[140:141]
	v_pk_fma_f32 v[150:151], v[34:35], v[146:147], v[142:143]
	global_store_dwordx4 v3, v[148:151], s[36:37] offset:-4096
	v_lshlrev_b32_e32 v156, 16, v66
	v_and_b32_e32 v157, 0xffff0000, v66
	v_lshlrev_b32_e32 v158, 16, v67
	v_and_b32_e32 v159, 0xffff0000, v67
	v_lshlrev_b32_e32 v160, 16, v82
	v_and_b32_e32 v161, 0xffff0000, v82
	v_lshlrev_b32_e32 v162, 16, v83
	v_and_b32_e32 v163, 0xffff0000, v83
	v_pk_mul_f32 v[160:161], v[0:1], v[160:161] op_sel_hi:[0,1]
	v_pk_mul_f32 v[162:163], v[0:1], v[162:163] op_sel_hi:[0,1]
	v_pk_fma_f32 v[152:153], v[36:37], v[160:161], v[156:157]
	v_pk_fma_f32 v[154:155], v[38:39], v[162:163], v[158:159]
	global_store_dwordx4 v3, v[152:155], s[36:37] offset:-3072
	v_lshlrev_b32_e32 v140, 16, v68
	v_and_b32_e32 v141, 0xffff0000, v68
	v_lshlrev_b32_e32 v142, 16, v69
	v_and_b32_e32 v143, 0xffff0000, v69
	v_lshlrev_b32_e32 v144, 16, v84
	v_and_b32_e32 v145, 0xffff0000, v84
	v_lshlrev_b32_e32 v146, 16, v85
	v_and_b32_e32 v147, 0xffff0000, v85
	v_pk_mul_f32 v[144:145], v[0:1], v[144:145] op_sel_hi:[0,1]
	v_pk_mul_f32 v[146:147], v[0:1], v[146:147] op_sel_hi:[0,1]
	v_pk_fma_f32 v[148:149], v[40:41], v[144:145], v[140:141]
	v_pk_fma_f32 v[150:151], v[42:43], v[146:147], v[142:143]
	global_store_dwordx4 v3, v[148:151], s[36:37] offset:-2048
	v_lshlrev_b32_e32 v156, 16, v70
	v_and_b32_e32 v157, 0xffff0000, v70
	v_lshlrev_b32_e32 v158, 16, v71
	v_and_b32_e32 v159, 0xffff0000, v71
	v_lshlrev_b32_e32 v160, 16, v86
	v_and_b32_e32 v161, 0xffff0000, v86
	v_lshlrev_b32_e32 v162, 16, v87
	v_and_b32_e32 v163, 0xffff0000, v87
	v_pk_mul_f32 v[160:161], v[0:1], v[160:161] op_sel_hi:[0,1]
	v_pk_mul_f32 v[162:163], v[0:1], v[162:163] op_sel_hi:[0,1]
	v_pk_fma_f32 v[152:153], v[44:45], v[160:161], v[156:157]
	v_pk_fma_f32 v[154:155], v[46:47], v[162:163], v[158:159]
	global_store_dwordx4 v3, v[152:155], s[36:37] offset:-1024
	v_lshlrev_b32_e32 v140, 16, v72
	v_and_b32_e32 v141, 0xffff0000, v72
	v_lshlrev_b32_e32 v142, 16, v73
	v_and_b32_e32 v143, 0xffff0000, v73
	v_lshlrev_b32_e32 v144, 16, v88
	v_and_b32_e32 v145, 0xffff0000, v88
	v_lshlrev_b32_e32 v146, 16, v89
	v_and_b32_e32 v147, 0xffff0000, v89
	v_pk_mul_f32 v[144:145], v[0:1], v[144:145] op_sel_hi:[0,1]
	v_pk_mul_f32 v[146:147], v[0:1], v[146:147] op_sel_hi:[0,1]
	v_pk_fma_f32 v[148:149], v[48:49], v[144:145], v[140:141]
	v_pk_fma_f32 v[150:151], v[50:51], v[146:147], v[142:143]
	global_store_dwordx4 v3, v[148:151], s[36:37] offset:0
	v_lshlrev_b32_e32 v156, 16, v74
	v_and_b32_e32 v157, 0xffff0000, v74
	v_lshlrev_b32_e32 v158, 16, v75
	v_and_b32_e32 v159, 0xffff0000, v75
	v_lshlrev_b32_e32 v160, 16, v90
	v_and_b32_e32 v161, 0xffff0000, v90
	v_lshlrev_b32_e32 v162, 16, v91
	v_and_b32_e32 v163, 0xffff0000, v91
	v_pk_mul_f32 v[160:161], v[0:1], v[160:161] op_sel_hi:[0,1]
	v_pk_mul_f32 v[162:163], v[0:1], v[162:163] op_sel_hi:[0,1]
	v_pk_fma_f32 v[152:153], v[52:53], v[160:161], v[156:157]
	v_pk_fma_f32 v[154:155], v[54:55], v[162:163], v[158:159]
	global_store_dwordx4 v3, v[152:155], s[36:37] offset:1024
	v_lshlrev_b32_e32 v140, 16, v76
	v_and_b32_e32 v141, 0xffff0000, v76
	v_lshlrev_b32_e32 v142, 16, v77
	v_and_b32_e32 v143, 0xffff0000, v77
	v_lshlrev_b32_e32 v144, 16, v92
	v_and_b32_e32 v145, 0xffff0000, v92
	v_lshlrev_b32_e32 v146, 16, v93
	v_and_b32_e32 v147, 0xffff0000, v93
	v_pk_mul_f32 v[144:145], v[0:1], v[144:145] op_sel_hi:[0,1]
	v_pk_mul_f32 v[146:147], v[0:1], v[146:147] op_sel_hi:[0,1]
	v_pk_fma_f32 v[148:149], v[56:57], v[144:145], v[140:141]
	v_pk_fma_f32 v[150:151], v[58:59], v[146:147], v[142:143]
	global_store_dwordx4 v3, v[148:151], s[36:37] offset:2048
	v_lshlrev_b32_e32 v156, 16, v78
	v_and_b32_e32 v157, 0xffff0000, v78
	v_lshlrev_b32_e32 v158, 16, v79
	v_and_b32_e32 v159, 0xffff0000, v79
	v_lshlrev_b32_e32 v160, 16, v94
	v_and_b32_e32 v161, 0xffff0000, v94
	v_lshlrev_b32_e32 v162, 16, v95
	v_and_b32_e32 v163, 0xffff0000, v95
	v_pk_mul_f32 v[160:161], v[0:1], v[160:161] op_sel_hi:[0,1]
	v_pk_mul_f32 v[162:163], v[0:1], v[162:163] op_sel_hi:[0,1]
	v_pk_fma_f32 v[152:153], v[60:61], v[160:161], v[156:157]
	v_pk_fma_f32 v[154:155], v[62:63], v[162:163], v[158:159]
	global_store_dwordx4 v3, v[152:155], s[36:37] offset:3072
	s_branch .Lp11_next_a
; __device__ __forceinline__ float rstd_of(float ss, float inv_n) { return __builtin_amdgcn_rsqf(ss * inv_n + 1e-6f); }
; __device__ __forceinline__ float bf_lo(unsigned w) { return __uint_as_float(w << 16); }
; __device__ __forceinline__ float bf_hi(unsigned w) { return __uint_as_float(w & 0xffff0000u); }
; #define GAS __attribute__((address_space(1)))
; __global__ void __launch_bounds__(NTHREADS, 2) mk_fwd(Args args) {
;     ...
;     if (PH(11)) { FRESH_IDS const bf16* E = (const bf16*)(ws + WS_E); const float* sse = stat + ST_SSE * MROWS; const int gw = bx * NWAVES + wave, NGW = G * NWAVES;
;         for (int m = gw; m < MROWS; m += NGW) { const float r = pg8::rstd_of(sse[m], 1.0f / 2048.0f); GAS f32x4* xr = (GAS f32x4*)(out + (size_t)m * DM) + lane; const GAS v2u* xbr = (const GAS v2u*)(XB + (size_t)m * DM) + lane; const GAS v2u* er = (const GAS v2u*)(E + (size_t)m * DM) + lane;
;             const GAS f32x4* gp = (const GAS f32x4*)in.ple_post + lane;
; #pragma unroll
;             for (int j = 0; j < 8; ++j) { const v2u xw = xbr[64 * j]; const v2u w = er[64 * j]; const f32x4 gg = gp[64 * j]; f32x4 v;
;                 v.x = pg8::bf_lo(xw.x) + pg8::bf_lo(w.x) * r * gg.x; v.y = pg8::bf_hi(xw.x) + pg8::bf_hi(w.x) * r * gg.y; v.z = pg8::bf_lo(xw.y) + pg8::bf_lo(w.y) * r * gg.z; v.w = pg8::bf_hi(xw.y) + pg8::bf_hi(w.y) * r * gg.w; xr[64 * j] = v; } } }
.Lp11_last_a:
	s_waitcnt vmcnt(8)
	v_fmamk_f32 v0, v96, 0x3a000000, v16
	v_rsq_f32_e32 v0, v0
	v_lshlrev_b32_e32 v140, 16, v64
	v_and_b32_e32 v141, 0xffff0000, v64
	v_lshlrev_b32_e32 v142, 16, v65
	v_and_b32_e32 v143, 0xffff0000, v65
	v_lshlrev_b32_e32 v144, 16, v80
	v_and_b32_e32 v145, 0xffff0000, v80
	v_lshlrev_b32_e32 v146, 16, v81
	v_and_b32_e32 v147, 0xffff0000, v81
	v_pk_mul_f32 v[144:145], v[0:1], v[144:145] op_sel_hi:[0,1]
	v_pk_mul_f32 v[146:147], v[0:1], v[146:147] op_sel_hi:[0,1]
	v_pk_fma_f32 v[148:149], v[32:33], v[144:145], v[140:141]
	v_pk_fma_f32 v[150:151], v[34:35], v[146:147], v[142:143]
	global_store_dwordx4 v3, v[148:151], s[36:37] offset:-4096
	v_lshlrev_b32_e32 v156, 16, v66
	v_and_b32_e32 v157, 0xffff0000, v66
	v_lshlrev_b32_e32 v158, 16, v67
	v_and_b32_e32 v159, 0xffff0000, v67
	v_lshlrev_b32_e32 v160, 16, v82
	v_and_b32_e32 v161, 0xffff0000, v82
	v_lshlrev_b32_e32 v162, 16, v83
	v_and_b32_e32 v163, 0xffff0000, v83
	v_pk_mul_f32 v[160:161], v[0:1], v[160:161] op_sel_hi:[0,1]
	v_pk_mul_f32 v[162:163], v[0:1], v[162:163] op_sel_hi:[0,1]
	v_pk_fma_f32 v[152:153], v[36:37], v[160:161], v[156:157]
	v_pk_fma_f32 v[154:155], v[38:39], v[162:163], v[158:159]
	global_store_dwordx4 v3, v[152:155], s[36:37] offset:-3072
	v_lshlrev_b32_e32 v140, 16, v68
	v_and_b32_e32 v141, 0xffff0000, v68
	v_lshlrev_b32_e32 v142, 16, v69
	v_and_b32_e32 v143, 0xffff0000, v69
	v_lshlrev_b32_e32 v144, 16, v84
	v_and_b32_e32 v145, 0xffff0000, v84
	v_lshlrev_b32_e32 v146, 16, v85
	v_and_b32_e32 v147, 0xffff0000, v85
	v_pk_mul_f32 v[144:145], v[0:1], v[144:145] op_sel_hi:[0,1]
	v_pk_mul_f32 v[146:147], v[0:1], v[146:147] op_sel_hi:[0,1]
	v_pk_fma_f32 v[148:149], v[40:41], v[144:145], v[140:141]
	v_pk_fma_f32 v[150:151], v[42:43], v[146:147], v[142:143]
	global_store_dwordx4 v3, v[148:151], s[36:37] offset:-2048
	v_lshlrev_b32_e32 v156, 16, v70
	v_and_b32_e32 v157, 0xffff0000, v70
	v_lshlrev_b32_e32 v158, 16, v71
	v_and_b32_e32 v159, 0xffff0000, v71
	v_lshlrev_b32_e32 v160, 16, v86
	v_and_b32_e32 v161, 0xffff0000, v86
	v_lshlrev_b32_e32 v162, 16, v87
	v_and_b32_e32 v163, 0xffff0000, v87
	v_pk_mul_f32 v[160:161], v[0:1], v[160:161] op_sel_hi:[0,1]
	v_pk_mul_f32 v[162:163], v[0:1], v[162:163] op_sel_hi:[0,1]
	v_pk_fma_f32 v[152:153], v[44:45], v[160:161], v[156:157]
	v_pk_fma_f32 v[154:155], v[46:47], v[162:163], v[158:159]
	global_store_dwordx4 v3, v[152:155], s[36:37] offset:-1024
	v_lshlrev_b32_e32 v140, 16, v72
	v_and_b32_e32 v141, 0xffff0000, v72
	v_lshlrev_b32_e32 v142, 16, v73
	v_and_b32_e32 v143, 0xffff0000, v73
	v_lshlrev_b32_e32 v144, 16, v88
	v_and_b32_e32 v145, 0xffff0000, v88
	v_lshlrev_b32_e32 v146, 16, v89
	v_and_b32_e32 v147, 0xffff0000, v89
	v_pk_mul_f32 v[144:145], v[0:1], v[144:145] op_sel_hi:[0,1]
	v_pk_mul_f32 v[146:147], v[0:1], v[146:147] op_sel_hi:[0,1]
	v_pk_fma_f32 v[148:149], v[48:49], v[144:145], v[140:141]
	v_pk_fma_f32 v[150:151], v[50:51], v[146:147], v[142:143]
	global_store_dwordx4 v3, v[148:151], s[36:37] offset:0
	v_lshlrev_b32_e32 v156, 16, v74
	v_and_b32_e32 v157, 0xffff0000, v74
	v_lshlrev_b32_e32 v158, 16, v75
	v_and_b32_e32 v159, 0xffff0000, v75
	v_lshlrev_b32_e32 v160, 16, v90
	v_and_b32_e32 v161, 0xffff0000, v90
	v_lshlrev_b32_e32 v162, 16, v91
	v_and_b32_e32 v163, 0xffff0000, v91
	v_pk_mul_f32 v[160:161], v[0:1], v[160:161] op_sel_hi:[0,1]
	v_pk_mul_f32 v[162:163], v[0:1], v[162:163] op_sel_hi:[0,1]
	v_pk_fma_f32 v[152:153], v[52:53], v[160:161], v[156:157]
	v_pk_fma_f32 v[154:155], v[54:55], v[162:163], v[158:159]
	global_store_dwordx4 v3, v[152:155], s[36:37] offset:1024
	v_lshlrev_b32_e32 v140, 16, v76
	v_and_b32_e32 v141, 0xffff0000, v76
	v_lshlrev_b32_e32 v142, 16, v77
	v_and_b32_e32 v143, 0xffff0000, v77
	v_lshlrev_b32_e32 v144, 16, v92
	v_and_b32_e32 v145, 0xffff0000, v92
	v_lshlrev_b32_e32 v146, 16, v93
	v_and_b32_e32 v147, 0xffff0000, v93
	v_pk_mul_f32 v[144:145], v[0:1], v[144:145] op_sel_hi:[0,1]
	v_pk_mul_f32 v[146:147], v[0:1], v[146:147] op_sel_hi:[0,1]
	v_pk_fma_f32 v[148:149], v[56:57], v[144:145], v[140:141]
	v_pk_fma_f32 v[150:151], v[58:59], v[146:147], v[142:143]
	global_store_dwordx4 v3, v[148:151], s[36:37] offset:2048
	v_lshlrev_b32_e32 v156, 16, v78
	v_and_b32_e32 v157, 0xffff0000, v78
	v_lshlrev_b32_e32 v158, 16, v79
	v_and_b32_e32 v159, 0xffff0000, v79
	v_lshlrev_b32_e32 v160, 16, v94
	v_and_b32_e32 v161, 0xffff0000, v94
	v_lshlrev_b32_e32 v162, 16, v95
	v_and_b32_e32 v163, 0xffff0000, v95
	v_pk_mul_f32 v[160:161], v[0:1], v[160:161] op_sel_hi:[0,1]
	v_pk_mul_f32 v[162:163], v[0:1], v[162:163] op_sel_hi:[0,1]
	v_pk_fma_f32 v[152:153], v[60:61], v[160:161], v[156:157]
	v_pk_fma_f32 v[154:155], v[62:63], v[162:163], v[158:159]
	global_store_dwordx4 v3, v[152:155], s[36:37] offset:3072
	s_endpgm
